# GEMM K-loop MFMA snake order over fragment pairs (one operand changes per MFMA) on top of barrier-4-early
# baseline (speedup 1.0000x reference)
; #define PG8_STAGE(bufoff, gbase, voff) do { if constexpr (!pg8_noload<Epi>::value) { _Pragma("unroll") for (int _i = 0; _i < 2; ++_i) \
;         __builtin_amdgcn_global_load_lds((const unsigned*)((const char*)(gbase) + (size_t)_i * pstep + (voff)[0]), (PG8_LAS unsigned*)(lds + (bufoff) + ldsw + _i * 8192), 16, 0, 0); } } while (0)
; #define PG8_LDA(dst, b, h) do { _Pragma("unroll") for (int m = 0; m < 4; ++m) _Pragma("unroll") for (int k = 0; k < 2; ++k) dst[m][k] = *(const PG8_LAS bf16x8*)(lds + PG8_SA(b, h) + aoff + m * 2048 + k * 1024); } while (0)
; #define PG8_LDB(dst, b, h) do { _Pragma("unroll") for (int n = 0; n < 2; ++n) _Pragma("unroll") for (int k = 0; k < 2; ++k) dst[n][k] = *(const PG8_LAS bf16x8*)(lds + PG8_SB(b, h) + boff + n * 2048 + k * 1024); } while (0)
; #define PG8_MMA(ai, bj, At, Bt) do { __builtin_amdgcn_s_setprio(1); _Pragma("unroll") for (int m = 0; m < 4; ++m) _Pragma("unroll") for (int n = 0; n < 2; ++n) _Pragma("unroll") for (int k = 0; k < 2; ++k) \
;         acc[ai][bj][m][n] = __builtin_amdgcn_mfma_f32_16x16x32_bf16(Bt[n][k], At[m][k], acc[ai][bj][m][n], 0, 0, 0); __builtin_amdgcn_s_setprio(0); } while (0)
; #define PG8_WAIT_V(n) asm volatile("s_waitcnt vmcnt(" #n ")" ::: "memory")
; #define PG8_WAIT_L(n) asm volatile("s_waitcnt lgkmcnt(" #n ")" ::: "memory")
; #define PG8_BAR __builtin_amdgcn_s_barrier()
; template <class Epi, class Sched, bool ALIGN_EPI = false, bool SP2 = false, bool ABLK = false>
; __device__ __forceinline__ void gemm_phase(PG8_LAS unsigned char* lds, const Gemm g, const Sched& S, const Epi& E) {
;     ...
;             const bool last = (t == nt - 2);
;             const char* a1 = cA + (size_t)(t + 1) * kstep;
;             const char* a2 = last ? nA : cA + (size_t)(t + 2) * kstep; const char* b2 = last ? nB : cB + (size_t)(t + 2) * kstepB;
;             const char* a3 = a2 + kstep; const char* b3 = b2 + kstepB;
;             if (last && has_next) S.a_ready(nxt);
;             if constexpr (SP2) {
;             PG8_LDB(B0, 0, 0); PG8_LDB(B1, 0, 1); PG8_SCHED; PG8_LDA(At, 0, 0); PG8_STAGE(PG8_SA(1, 1), a1 + hstep, voffA);
;             PG8_WAIT_V(8); PG8_WAIT_L(0); PG8_BAR; PG8_MMA(0, 0, At, B0); PG8_MMA(0, 1, At, B1); PG8_BAR; PG8_SCHED;
;             PG8_LDA(At, 0, 1); PG8_STAGE(PG8_SB(0, 0), b2, voffB); PG8_STAGE(PG8_SB(0, 1), b2 + hstep, voffB); PG8_STAGE(PG8_SA(0, 0), a2, voffA);
.LBB0_114:
	ds_read_b128 v[144:147], v168
	ds_read_b128 v[184:187], v168 offset:1024
	ds_read_b128 v[188:191], v168 offset:2048
	ds_read_b128 v[192:195], v168 offset:3072
	ds_read_b128 v[196:199], v169
	ds_read_b128 v[200:203], v169 offset:1024
	ds_read_b128 v[204:207], v169 offset:2048
	ds_read_b128 v[208:211], v169 offset:3072
	s_add_u32 s71, vcc_lo, 0xfff80800
	s_addc_u32 s73, vcc_hi, -1
	s_cmp_eq_u32 s70, 28
	s_cselect_b32 s75, s3, s73
	s_cselect_b32 s74, s7, s71
	s_cselect_b32 s77, s21, s17
	s_cselect_b32 s76, s72, s16
	v_lshl_add_u64 v[244:245], vcc, 0, v[136:137]
	s_add_i32 m0, s53, 0xc000
	ds_read_b128 v[212:215], v170
	ds_read_b128 v[216:219], v170 offset:1024
	ds_read_b128 v[220:223], v170 offset:2048
	ds_read_b128 v[224:227], v170 offset:3072
	ds_read_b128 v[228:231], v170 offset:4096
	ds_read_b128 v[232:235], v170 offset:5120
	ds_read_b128 v[236:239], v170 offset:6144
	ds_read_b128 v[240:243], v170 offset:7168
	global_load_lds_dwordx4 v[244:245], off
	v_lshl_add_u64 v[244:245], v[244:245], 0, s[0:1]
	s_add_i32 m0, s53, 0xe000
	s_nop 0
	global_load_lds_dwordx4 v[244:245], off
	s_waitcnt vmcnt(8)
	s_waitcnt lgkmcnt(0)
	s_barrier
	s_setprio 1
	s_waitcnt lgkmcnt(0)
	v_mfma_f32_16x16x32_bf16 v[126:129], v[144:147], v[212:215], v[126:129]
	v_mfma_f32_16x16x32_bf16 v[122:125], v[188:191], v[212:215], v[122:125]
	v_mfma_f32_16x16x32_bf16 v[106:109], v[188:191], v[220:223], v[106:109]
	v_mfma_f32_16x16x32_bf16 v[110:113], v[144:147], v[220:223], v[110:113]
	v_mfma_f32_16x16x32_bf16 v[94:97], v[144:147], v[228:231], v[94:97]
	v_mfma_f32_16x16x32_bf16 v[90:93], v[188:191], v[228:231], v[90:93]
	v_mfma_f32_16x16x32_bf16 v[74:77], v[188:191], v[236:239], v[74:77]
	v_mfma_f32_16x16x32_bf16 v[78:81], v[144:147], v[236:239], v[78:81]
	v_mfma_f32_16x16x32_bf16 v[126:129], v[184:187], v[216:219], v[126:129]
	v_mfma_f32_16x16x32_bf16 v[122:125], v[192:195], v[216:219], v[122:125]
	v_mfma_f32_16x16x32_bf16 v[106:109], v[192:195], v[224:227], v[106:109]
	v_mfma_f32_16x16x32_bf16 v[110:113], v[184:187], v[224:227], v[110:113]
	v_mfma_f32_16x16x32_bf16 v[94:97], v[184:187], v[232:235], v[94:97]
	v_mfma_f32_16x16x32_bf16 v[90:93], v[192:195], v[232:235], v[90:93]
	v_mfma_f32_16x16x32_bf16 v[74:77], v[192:195], v[240:243], v[74:77]
	v_mfma_f32_16x16x32_bf16 v[78:81], v[184:187], v[240:243], v[78:81]
	v_mfma_f32_16x16x32_bf16 v[118:121], v[196:199], v[212:215], v[118:121]
	v_mfma_f32_16x16x32_bf16 v[114:117], v[204:207], v[212:215], v[114:117]
	v_mfma_f32_16x16x32_bf16 v[98:101], v[204:207], v[220:223], v[98:101]
	v_mfma_f32_16x16x32_bf16 v[102:105], v[196:199], v[220:223], v[102:105]
	v_mfma_f32_16x16x32_bf16 v[86:89], v[196:199], v[228:231], v[86:89]
	v_mfma_f32_16x16x32_bf16 v[82:85], v[204:207], v[228:231], v[82:85]
	v_mfma_f32_16x16x32_bf16 v[66:69], v[204:207], v[236:239], v[66:69]
	v_mfma_f32_16x16x32_bf16 v[70:73], v[196:199], v[236:239], v[70:73]
	v_mfma_f32_16x16x32_bf16 v[118:121], v[200:203], v[216:219], v[118:121]
	v_mfma_f32_16x16x32_bf16 v[114:117], v[208:211], v[216:219], v[114:117]
	v_mfma_f32_16x16x32_bf16 v[98:101], v[208:211], v[224:227], v[98:101]
	v_mfma_f32_16x16x32_bf16 v[102:105], v[200:203], v[224:227], v[102:105]
	s_barrier
	s_setprio 2
	v_mfma_f32_16x16x32_bf16 v[86:89], v[200:203], v[232:235], v[86:89]
	v_mfma_f32_16x16x32_bf16 v[82:85], v[208:211], v[232:235], v[82:85]
	v_mfma_f32_16x16x32_bf16 v[66:69], v[208:211], v[240:243], v[66:69]
	v_mfma_f32_16x16x32_bf16 v[70:73], v[200:203], v[240:243], v[70:73]
	s_setprio 0
	s_add_i32 s71, s64, s52
	v_lshl_add_u64 v[244:245], s[76:77], 0, v[130:131]
	s_mov_b32 m0, s71
	ds_read_b128 v[212:215], v170 offset:16384
	ds_read_b128 v[216:219], v170 offset:17408
	ds_read_b128 v[220:223], v170 offset:18432
	ds_read_b128 v[224:227], v170 offset:19456
	ds_read_b128 v[228:231], v170 offset:20480
	ds_read_b128 v[232:235], v170 offset:21504
	ds_read_b128 v[236:239], v170 offset:22528
	ds_read_b128 v[240:243], v170 offset:23552
	global_load_lds_dwordx4 v[244:245], off
	v_lshl_add_u64 v[246:247], v[244:245], 0, s[0:1]
	s_add_i32 m0, s71, 0x2000
	s_add_i32 s71, s65, s52
	global_load_lds_dwordx4 v[246:247], off
	v_lshl_add_u64 v[246:247], v[244:245], 0, s[14:15]
	s_mov_b32 m0, s71
	s_nop 0
	global_load_lds_dwordx4 v[246:247], off
	v_lshl_add_u64 v[246:247], v[244:245], 0, s[18:19]
	s_add_i32 m0, s71, 0x2000
	s_nop 0
	global_load_lds_dwordx4 v[246:247], off
	v_lshl_add_u64 v[246:247], s[74:75], 0, v[130:131]
	s_mov_b32 m0, s53
	v_lshl_add_u64 v[248:249], v[246:247], 0, s[0:1]
	global_load_lds_dwordx4 v[246:247], off
	s_mov_b32 m0, s54
	s_nop 0
	global_load_lds_dwordx4 v[248:249], off
	s_waitcnt vmcnt(8)
	s_waitcnt lgkmcnt(0)
	s_barrier
; #define PG8_STAGE(bufoff, gbase, voff) do { if constexpr (!pg8_noload<Epi>::value) { _Pragma("unroll") for (int _i = 0; _i < 2; ++_i) \
;         __builtin_amdgcn_global_load_lds((const unsigned*)((const char*)(gbase) + (size_t)_i * pstep + (voff)[0]), (PG8_LAS unsigned*)(lds + (bufoff) + ldsw + _i * 8192), 16, 0, 0); } } while (0)
; #define PG8_LDA(dst, b, h) do { _Pragma("unroll") for (int m = 0; m < 4; ++m) _Pragma("unroll") for (int k = 0; k < 2; ++k) dst[m][k] = *(const PG8_LAS bf16x8*)(lds + PG8_SA(b, h) + aoff + m * 2048 + k * 1024); } while (0)
; #define PG8_LDB(dst, b, h) do { _Pragma("unroll") for (int n = 0; n < 2; ++n) _Pragma("unroll") for (int k = 0; k < 2; ++k) dst[n][k] = *(const PG8_LAS bf16x8*)(lds + PG8_SB(b, h) + boff + n * 2048 + k * 1024); } while (0)
; #define PG8_MMA(ai, bj, At, Bt) do { __builtin_amdgcn_s_setprio(1); _Pragma("unroll") for (int m = 0; m < 4; ++m) _Pragma("unroll") for (int n = 0; n < 2; ++n) _Pragma("unroll") for (int k = 0; k < 2; ++k) \
;         acc[ai][bj][m][n] = __builtin_amdgcn_mfma_f32_16x16x32_bf16(Bt[n][k], At[m][k], acc[ai][bj][m][n], 0, 0, 0); __builtin_amdgcn_s_setprio(0); } while (0)
; #define PG8_WAIT_V(n) asm volatile("s_waitcnt vmcnt(" #n ")" ::: "memory")
; #define PG8_WAIT_L(n) asm volatile("s_waitcnt lgkmcnt(" #n ")" ::: "memory")
; #define PG8_BAR __builtin_amdgcn_s_barrier()
; #define PG8_SCHED __builtin_amdgcn_sched_barrier(0)
; template <class Epi, class Sched, bool ALIGN_EPI = false, bool SP2 = false, bool ABLK = false>
; __device__ __forceinline__ void gemm_phase(PG8_LAS unsigned char* lds, const Gemm g, const Sched& S, const Epi& E) {
;     ...
;             PG8_WAIT_V(8); PG8_WAIT_L(0); PG8_BAR; PG8_MMA(1, 0, At, B0); PG8_MMA(1, 1, At, B1); PG8_BAR; PG8_SCHED;
;             PG8_LDB(B0, 1, 0); PG8_LDB(B1, 1, 1); PG8_SCHED; PG8_LDA(At, 1, 0); PG8_STAGE(PG8_SA(0, 1), a2 + hstep, voffA);
;             PG8_WAIT_V(8); PG8_WAIT_L(0); PG8_BAR; PG8_MMA(0, 0, At, B0); PG8_MMA(0, 1, At, B1); PG8_BAR; PG8_SCHED;
	s_setprio 1
	s_waitcnt lgkmcnt(0)
	v_mfma_f32_16x16x32_bf16 v[62:65], v[144:147], v[212:215], v[62:65]
	v_mfma_f32_16x16x32_bf16 v[58:61], v[188:191], v[212:215], v[58:61]
	v_mfma_f32_16x16x32_bf16 v[42:45], v[188:191], v[220:223], v[42:45]
	v_mfma_f32_16x16x32_bf16 v[46:49], v[144:147], v[220:223], v[46:49]
	v_mfma_f32_16x16x32_bf16 v[30:33], v[144:147], v[228:231], v[30:33]
	v_mfma_f32_16x16x32_bf16 v[26:29], v[188:191], v[228:231], v[26:29]
	v_mfma_f32_16x16x32_bf16 v[10:13], v[188:191], v[236:239], v[10:13]
	v_mfma_f32_16x16x32_bf16 v[14:17], v[144:147], v[236:239], v[14:17]
	v_mfma_f32_16x16x32_bf16 v[62:65], v[184:187], v[216:219], v[62:65]
	v_mfma_f32_16x16x32_bf16 v[58:61], v[192:195], v[216:219], v[58:61]
	v_mfma_f32_16x16x32_bf16 v[42:45], v[192:195], v[224:227], v[42:45]
	v_mfma_f32_16x16x32_bf16 v[46:49], v[184:187], v[224:227], v[46:49]
	v_mfma_f32_16x16x32_bf16 v[30:33], v[184:187], v[232:235], v[30:33]
	v_mfma_f32_16x16x32_bf16 v[26:29], v[192:195], v[232:235], v[26:29]
	v_mfma_f32_16x16x32_bf16 v[10:13], v[192:195], v[240:243], v[10:13]
	v_mfma_f32_16x16x32_bf16 v[14:17], v[184:187], v[240:243], v[14:17]
	v_mfma_f32_16x16x32_bf16 v[54:57], v[196:199], v[212:215], v[54:57]
	v_mfma_f32_16x16x32_bf16 v[50:53], v[204:207], v[212:215], v[50:53]
	v_mfma_f32_16x16x32_bf16 v[34:37], v[204:207], v[220:223], v[34:37]
	v_mfma_f32_16x16x32_bf16 v[38:41], v[196:199], v[220:223], v[38:41]
	v_mfma_f32_16x16x32_bf16 v[22:25], v[196:199], v[228:231], v[22:25]
	v_mfma_f32_16x16x32_bf16 v[18:21], v[204:207], v[228:231], v[18:21]
	v_mfma_f32_16x16x32_bf16 v[2:5], v[204:207], v[236:239], v[2:5]
	v_mfma_f32_16x16x32_bf16 v[6:9], v[196:199], v[236:239], v[6:9]
	v_mfma_f32_16x16x32_bf16 v[54:57], v[200:203], v[216:219], v[54:57]
	v_mfma_f32_16x16x32_bf16 v[50:53], v[208:211], v[216:219], v[50:53]
	v_mfma_f32_16x16x32_bf16 v[34:37], v[208:211], v[224:227], v[34:37]
	v_mfma_f32_16x16x32_bf16 v[38:41], v[200:203], v[224:227], v[38:41]
	s_barrier
	s_setprio 2
	v_mfma_f32_16x16x32_bf16 v[22:25], v[200:203], v[232:235], v[22:25]
	v_mfma_f32_16x16x32_bf16 v[18:21], v[208:211], v[232:235], v[18:21]
	v_mfma_f32_16x16x32_bf16 v[2:5], v[208:211], v[240:243], v[2:5]
	v_mfma_f32_16x16x32_bf16 v[6:9], v[200:203], v[240:243], v[6:9]
	s_setprio 0
	s_add_i32 s71, 0, 0x18000
	v_add_u32_e32 v133, s71, v149
	s_add_i32 s73, 0, 0x1c000
	ds_read_b128 v[144:147], v133
	ds_read_b128 v[184:187], v133 offset:1024
	ds_read_b128 v[188:191], v133 offset:2048
	ds_read_b128 v[192:195], v133 offset:3072
	v_add_u32_e32 v133, s73, v149
	ds_read_b128 v[196:199], v133
	ds_read_b128 v[200:203], v133 offset:1024
	ds_read_b128 v[204:207], v133 offset:2048
	ds_read_b128 v[208:211], v133 offset:3072
	s_mov_b32 m0, s55
	v_lshl_add_u64 v[248:249], v[246:247], 0, s[14:15]
	ds_read_b128 v[212:215], v170 offset:32768
	ds_read_b128 v[216:219], v170 offset:33792
	ds_read_b128 v[220:223], v170 offset:34816
	ds_read_b128 v[224:227], v170 offset:35840
	ds_read_b128 v[228:231], v170 offset:36864
	ds_read_b128 v[232:235], v170 offset:37888
	ds_read_b128 v[236:239], v170 offset:38912
	ds_read_b128 v[240:243], v170 offset:39936
	global_load_lds_dwordx4 v[248:249], off
	v_lshl_add_u64 v[248:249], v[246:247], 0, s[18:19]
	s_mov_b32 m0, s56
	s_nop 0
	global_load_lds_dwordx4 v[248:249], off
	s_waitcnt vmcnt(8)
	s_waitcnt lgkmcnt(0)
	s_barrier
	s_setprio 1
	s_waitcnt lgkmcnt(0)
	v_mfma_f32_16x16x32_bf16 v[126:129], v[144:147], v[212:215], v[126:129]
	v_mfma_f32_16x16x32_bf16 v[122:125], v[188:191], v[212:215], v[122:125]
	v_mfma_f32_16x16x32_bf16 v[106:109], v[188:191], v[220:223], v[106:109]
	v_mfma_f32_16x16x32_bf16 v[110:113], v[144:147], v[220:223], v[110:113]
	v_mfma_f32_16x16x32_bf16 v[94:97], v[144:147], v[228:231], v[94:97]
	v_mfma_f32_16x16x32_bf16 v[90:93], v[188:191], v[228:231], v[90:93]
	v_mfma_f32_16x16x32_bf16 v[74:77], v[188:191], v[236:239], v[74:77]
	v_mfma_f32_16x16x32_bf16 v[78:81], v[144:147], v[236:239], v[78:81]
	v_mfma_f32_16x16x32_bf16 v[126:129], v[184:187], v[216:219], v[126:129]
	v_mfma_f32_16x16x32_bf16 v[122:125], v[192:195], v[216:219], v[122:125]
	v_mfma_f32_16x16x32_bf16 v[106:109], v[192:195], v[224:227], v[106:109]
	v_mfma_f32_16x16x32_bf16 v[110:113], v[184:187], v[224:227], v[110:113]
	v_mfma_f32_16x16x32_bf16 v[94:97], v[184:187], v[232:235], v[94:97]
	v_mfma_f32_16x16x32_bf16 v[90:93], v[192:195], v[232:235], v[90:93]
	v_mfma_f32_16x16x32_bf16 v[74:77], v[192:195], v[240:243], v[74:77]
	v_mfma_f32_16x16x32_bf16 v[78:81], v[184:187], v[240:243], v[78:81]
	v_mfma_f32_16x16x32_bf16 v[118:121], v[196:199], v[212:215], v[118:121]
	v_mfma_f32_16x16x32_bf16 v[114:117], v[204:207], v[212:215], v[114:117]
	v_mfma_f32_16x16x32_bf16 v[98:101], v[204:207], v[220:223], v[98:101]
	v_mfma_f32_16x16x32_bf16 v[102:105], v[196:199], v[220:223], v[102:105]
	v_mfma_f32_16x16x32_bf16 v[86:89], v[196:199], v[228:231], v[86:89]
	v_mfma_f32_16x16x32_bf16 v[82:85], v[204:207], v[228:231], v[82:85]
	v_mfma_f32_16x16x32_bf16 v[66:69], v[204:207], v[236:239], v[66:69]
	v_mfma_f32_16x16x32_bf16 v[70:73], v[196:199], v[236:239], v[70:73]
	v_mfma_f32_16x16x32_bf16 v[118:121], v[200:203], v[216:219], v[118:121]
	v_mfma_f32_16x16x32_bf16 v[114:117], v[208:211], v[216:219], v[114:117]
	v_mfma_f32_16x16x32_bf16 v[98:101], v[208:211], v[224:227], v[98:101]
	v_mfma_f32_16x16x32_bf16 v[102:105], v[200:203], v[224:227], v[102:105]
	s_barrier
; #define PG8_STAGE(bufoff, gbase, voff) do { if constexpr (!pg8_noload<Epi>::value) { _Pragma("unroll") for (int _i = 0; _i < 2; ++_i) \
;         __builtin_amdgcn_global_load_lds((const unsigned*)((const char*)(gbase) + (size_t)_i * pstep + (voff)[0]), (PG8_LAS unsigned*)(lds + (bufoff) + ldsw + _i * 8192), 16, 0, 0); } } while (0)
; #define PG8_LDA(dst, b, h) do { _Pragma("unroll") for (int m = 0; m < 4; ++m) _Pragma("unroll") for (int k = 0; k < 2; ++k) dst[m][k] = *(const PG8_LAS bf16x8*)(lds + PG8_SA(b, h) + aoff + m * 2048 + k * 1024); } while (0)
; #define PG8_MMA(ai, bj, At, Bt) do { __builtin_amdgcn_s_setprio(1); _Pragma("unroll") for (int m = 0; m < 4; ++m) _Pragma("unroll") for (int n = 0; n < 2; ++n) _Pragma("unroll") for (int k = 0; k < 2; ++k) \
;         acc[ai][bj][m][n] = __builtin_amdgcn_mfma_f32_16x16x32_bf16(Bt[n][k], At[m][k], acc[ai][bj][m][n], 0, 0, 0); __builtin_amdgcn_s_setprio(0); } while (0)
; #define PG8_WAIT_V(n) asm volatile("s_waitcnt vmcnt(" #n ")" ::: "memory")
; #define PG8_WAIT_L(n) asm volatile("s_waitcnt lgkmcnt(" #n ")" ::: "memory")
; #define PG8_BAR __builtin_amdgcn_s_barrier()
; #define PG8_SCHED __builtin_amdgcn_sched_barrier(0)
; template <class Epi, class Sched, bool ALIGN_EPI = false, bool SP2 = false, bool ABLK = false>
; __device__ __forceinline__ void gemm_phase(PG8_LAS unsigned char* lds, const Gemm g, const Sched& S, const Epi& E) {
;     ...
;         for (int t = 0; t < nt; t += 2) {
;     ...
;             PG8_WAIT_V(8); PG8_WAIT_L(0); PG8_BAR; PG8_MMA(0, 0, At, B0); PG8_MMA(0, 1, At, B1); PG8_BAR; PG8_SCHED;
;             PG8_LDA(At, 1, 1); PG8_STAGE(PG8_SB(1, 0), b3, voffB); PG8_STAGE(PG8_SB(1, 1), b3 + hstep, voffB); PG8_STAGE(PG8_SA(1, 0), a3, voffA);
;             PG8_WAIT_V(8); PG8_WAIT_L(0); PG8_BAR; PG8_MMA(1, 0, At, B0); PG8_MMA(1, 1, At, B1); PG8_BAR; PG8_SCHED;
	s_setprio 2
	v_mfma_f32_16x16x32_bf16 v[86:89], v[200:203], v[232:235], v[86:89]
	v_mfma_f32_16x16x32_bf16 v[82:85], v[208:211], v[232:235], v[82:85]
	v_mfma_f32_16x16x32_bf16 v[66:69], v[208:211], v[240:243], v[66:69]
	v_mfma_f32_16x16x32_bf16 v[70:73], v[200:203], v[240:243], v[70:73]
	s_setprio 0
	s_add_i32 s71, s71, s52
	v_lshl_add_u64 v[248:249], v[244:245], 0, s[28:29]
	s_mov_b32 m0, s71
	ds_read_b128 v[212:215], v170 offset:49152
	ds_read_b128 v[216:219], v170 offset:50176
	ds_read_b128 v[220:223], v170 offset:51200
	ds_read_b128 v[224:227], v170 offset:52224
	ds_read_b128 v[228:231], v170 offset:53248
	ds_read_b128 v[232:235], v170 offset:54272
	ds_read_b128 v[236:239], v170 offset:55296
	ds_read_b128 v[240:243], v170 offset:56320
	global_load_lds_dwordx4 v[248:249], off
	v_lshl_add_u64 v[248:249], v[244:245], 0, s[30:31]
	s_add_i32 m0, s71, 0x2000
	s_add_i32 s71, s73, s52
	global_load_lds_dwordx4 v[248:249], off
	v_lshl_add_u64 v[248:249], v[244:245], 0, s[34:35]
	s_mov_b32 m0, s71
	v_lshl_add_u64 v[244:245], v[244:245], 0, s[36:37]
	global_load_lds_dwordx4 v[248:249], off
	s_add_i32 m0, s71, 0x2000
	s_nop 0
	global_load_lds_dwordx4 v[244:245], off
	v_lshl_add_u64 v[244:245], v[246:247], 0, s[28:29]
	s_mov_b32 m0, s59
	s_nop 0
	global_load_lds_dwordx4 v[244:245], off
	v_lshl_add_u64 v[244:245], v[246:247], 0, s[30:31]
	s_mov_b32 m0, s60
	s_nop 0
	global_load_lds_dwordx4 v[244:245], off
	s_waitcnt vmcnt(8)
	s_waitcnt lgkmcnt(0)
	s_barrier
	s_setprio 1
	s_waitcnt lgkmcnt(0)
	v_mfma_f32_16x16x32_bf16 v[62:65], v[144:147], v[212:215], v[62:65]
	v_mfma_f32_16x16x32_bf16 v[58:61], v[188:191], v[212:215], v[58:61]
	v_mfma_f32_16x16x32_bf16 v[42:45], v[188:191], v[220:223], v[42:45]
	v_mfma_f32_16x16x32_bf16 v[46:49], v[144:147], v[220:223], v[46:49]
	v_mfma_f32_16x16x32_bf16 v[30:33], v[144:147], v[228:231], v[30:33]
	v_mfma_f32_16x16x32_bf16 v[26:29], v[188:191], v[228:231], v[26:29]
	v_mfma_f32_16x16x32_bf16 v[10:13], v[188:191], v[236:239], v[10:13]
	v_mfma_f32_16x16x32_bf16 v[14:17], v[144:147], v[236:239], v[14:17]
	v_mfma_f32_16x16x32_bf16 v[62:65], v[184:187], v[216:219], v[62:65]
	v_mfma_f32_16x16x32_bf16 v[58:61], v[192:195], v[216:219], v[58:61]
	v_mfma_f32_16x16x32_bf16 v[42:45], v[192:195], v[224:227], v[42:45]
	v_mfma_f32_16x16x32_bf16 v[46:49], v[184:187], v[224:227], v[46:49]
	v_mfma_f32_16x16x32_bf16 v[30:33], v[184:187], v[232:235], v[30:33]
	v_mfma_f32_16x16x32_bf16 v[26:29], v[192:195], v[232:235], v[26:29]
	v_mfma_f32_16x16x32_bf16 v[10:13], v[192:195], v[240:243], v[10:13]
	v_mfma_f32_16x16x32_bf16 v[14:17], v[184:187], v[240:243], v[14:17]
	v_mfma_f32_16x16x32_bf16 v[54:57], v[196:199], v[212:215], v[54:57]
	v_mfma_f32_16x16x32_bf16 v[50:53], v[204:207], v[212:215], v[50:53]
	v_mfma_f32_16x16x32_bf16 v[34:37], v[204:207], v[220:223], v[34:37]
	v_mfma_f32_16x16x32_bf16 v[38:41], v[196:199], v[220:223], v[38:41]
	v_mfma_f32_16x16x32_bf16 v[22:25], v[196:199], v[228:231], v[22:25]
	v_mfma_f32_16x16x32_bf16 v[18:21], v[204:207], v[228:231], v[18:21]
	v_mfma_f32_16x16x32_bf16 v[2:5], v[204:207], v[236:239], v[2:5]
	v_mfma_f32_16x16x32_bf16 v[6:9], v[196:199], v[236:239], v[6:9]
	v_mfma_f32_16x16x32_bf16 v[54:57], v[200:203], v[216:219], v[54:57]
	v_mfma_f32_16x16x32_bf16 v[50:53], v[208:211], v[216:219], v[50:53]
	v_mfma_f32_16x16x32_bf16 v[34:37], v[208:211], v[224:227], v[34:37]
	v_mfma_f32_16x16x32_bf16 v[38:41], v[200:203], v[224:227], v[38:41]
	s_barrier
	s_setprio 2
	v_mfma_f32_16x16x32_bf16 v[22:25], v[200:203], v[232:235], v[22:25]
	v_mfma_f32_16x16x32_bf16 v[18:21], v[208:211], v[232:235], v[18:21]
	v_mfma_f32_16x16x32_bf16 v[2:5], v[208:211], v[240:243], v[2:5]
	v_mfma_f32_16x16x32_bf16 v[6:9], v[200:203], v[240:243], v[6:9]
	s_setprio 0
	s_add_i32 s70, s70, 2
	s_add_u32 vcc_lo, vcc_lo, 0x1000
	s_addc_u32 vcc_hi, vcc_hi, 0
	s_add_u32 s16, s16, 0x1000
	s_addc_u32 s17, s17, 0
	s_cmp_gt_u32 s70, 29
	s_cbranch_scc0 .LBB0_114
	s_and_b64 vcc, exec, s[38:39]
	s_cbranch_vccz .LBB0_117
	s_barrier

; #define PG8_STAGE(bufoff, gbase, voff) do { if constexpr (!pg8_noload<Epi>::value) { _Pragma("unroll") for (int _i = 0; _i < 2; ++_i) \
;         __builtin_amdgcn_global_load_lds((const unsigned*)((const char*)(gbase) + (size_t)_i * pstep + (voff)[0]), (PG8_LAS unsigned*)(lds + (bufoff) + ldsw + _i * 8192), 16, 0, 0); } } while (0)
; #define PG8_LDA(dst, b, h) do { _Pragma("unroll") for (int m = 0; m < 4; ++m) _Pragma("unroll") for (int k = 0; k < 2; ++k) dst[m][k] = *(const PG8_LAS bf16x8*)(lds + PG8_SA(b, h) + aoff + m * 2048 + k * 1024); } while (0)
; #define PG8_LDB(dst, b, h) do { _Pragma("unroll") for (int n = 0; n < 2; ++n) _Pragma("unroll") for (int k = 0; k < 2; ++k) dst[n][k] = *(const PG8_LAS bf16x8*)(lds + PG8_SB(b, h) + boff + n * 2048 + k * 1024); } while (0)
; #define PG8_MMA(ai, bj, At, Bt) do { __builtin_amdgcn_s_setprio(1); _Pragma("unroll") for (int m = 0; m < 4; ++m) _Pragma("unroll") for (int n = 0; n < 2; ++n) _Pragma("unroll") for (int k = 0; k < 2; ++k) \
;         acc[ai][bj][m][n] = __builtin_amdgcn_mfma_f32_16x16x32_bf16(Bt[n][k], At[m][k], acc[ai][bj][m][n], 0, 0, 0); __builtin_amdgcn_s_setprio(0); } while (0)
; #define PG8_WAIT_V(n) asm volatile("s_waitcnt vmcnt(" #n ")" ::: "memory")
; #define PG8_WAIT_L(n) asm volatile("s_waitcnt lgkmcnt(" #n ")" ::: "memory")
; #define PG8_BAR __builtin_amdgcn_s_barrier()
; template <class Epi, class Sched, bool ALIGN_EPI = false, bool SP2 = false, bool ABLK = false>
; __device__ __forceinline__ void gemm_phase(PG8_LAS unsigned char* lds, const Gemm g, const Sched& S, const Epi& E) {
;     ...
;             const bool last = (t == nt - 2);
;             const char* a1 = cA + (size_t)(t + 1) * kstep;
;             const char* a2 = last ? nA : cA + (size_t)(t + 2) * kstep; const char* b2 = last ? nB : cB + (size_t)(t + 2) * kstepB;
;             const char* a3 = a2 + kstep; const char* b3 = b2 + kstepB;
;             if (last && has_next) S.a_ready(nxt);
;             if constexpr (SP2) {
;             PG8_LDB(B0, 0, 0); PG8_LDB(B1, 0, 1); PG8_SCHED; PG8_LDA(At, 0, 0); PG8_STAGE(PG8_SA(1, 1), a1 + hstep, voffA);
;             PG8_WAIT_V(8); PG8_WAIT_L(0); PG8_BAR; PG8_MMA(0, 0, At, B0); PG8_MMA(0, 1, At, B1); PG8_BAR; PG8_SCHED;
;             PG8_LDA(At, 0, 1); PG8_STAGE(PG8_SB(0, 0), b2, voffB); PG8_STAGE(PG8_SB(0, 1), b2 + hstep, voffB); PG8_STAGE(PG8_SA(0, 0), a2, voffA);
.LBB0_487:
	ds_read_b128 v[114:117], v167
	ds_read_b128 v[126:129], v167 offset:1024
	ds_read_b128 v[130:133], v167 offset:2048
	ds_read_b128 v[142:145], v167 offset:3072
	ds_read_b128 v[146:149], v168
	ds_read_b128 v[150:153], v168 offset:1024
	ds_read_b128 v[174:177], v168 offset:2048
	ds_read_b128 v[178:181], v168 offset:3072
	s_add_i32 s65, s39, 2
	s_add_u32 s68, s92, 0xfff00800
	s_addc_u32 s69, s93, -1
	s_cmp_eq_u32 s3, s39
	s_cselect_b32 s69, s79, s69
	s_cselect_b32 s68, s78, s68
	s_cselect_b32 s71, s89, s37
	s_cselect_b32 s70, s88, s11
	v_lshl_add_u64 v[162:163], s[92:93], 0, v[158:159]
	s_add_i32 m0, s56, 0xc000
	ds_read_b128 v[184:187], v169
	ds_read_b128 v[188:191], v169 offset:1024
	ds_read_b128 v[192:195], v169 offset:2048
	ds_read_b128 v[196:199], v169 offset:3072
	ds_read_b128 v[200:203], v169 offset:4096
	ds_read_b128 v[204:207], v169 offset:5120
	ds_read_b128 v[208:211], v169 offset:6144
	ds_read_b128 v[212:215], v169 offset:7168
	global_load_lds_dwordx4 v[162:163], off
	v_lshl_add_u64 v[162:163], v[162:163], 0, s[12:13]
	s_add_i32 m0, s56, 0xe000
	s_nop 0
	global_load_lds_dwordx4 v[162:163], off
	s_waitcnt vmcnt(8)
	s_waitcnt lgkmcnt(0)
	s_barrier
	s_setprio 1
	s_waitcnt lgkmcnt(0)
	v_mfma_f32_16x16x32_bf16 v[138:141], v[114:117], v[184:187], v[138:141]
	v_mfma_f32_16x16x32_bf16 v[134:137], v[130:133], v[184:187], v[134:137]
	v_mfma_f32_16x16x32_bf16 v[106:109], v[130:133], v[192:195], v[106:109]
	v_mfma_f32_16x16x32_bf16 v[110:113], v[114:117], v[192:195], v[110:113]
	v_mfma_f32_16x16x32_bf16 v[94:97], v[114:117], v[200:203], v[94:97]
	v_mfma_f32_16x16x32_bf16 v[90:93], v[130:133], v[200:203], v[90:93]
	v_mfma_f32_16x16x32_bf16 v[74:77], v[130:133], v[208:211], v[74:77]
	v_mfma_f32_16x16x32_bf16 v[78:81], v[114:117], v[208:211], v[78:81]
	v_mfma_f32_16x16x32_bf16 v[138:141], v[126:129], v[188:191], v[138:141]
	v_mfma_f32_16x16x32_bf16 v[134:137], v[142:145], v[188:191], v[134:137]
	v_mfma_f32_16x16x32_bf16 v[106:109], v[142:145], v[196:199], v[106:109]
	v_mfma_f32_16x16x32_bf16 v[110:113], v[126:129], v[196:199], v[110:113]
	v_mfma_f32_16x16x32_bf16 v[94:97], v[126:129], v[204:207], v[94:97]
	v_mfma_f32_16x16x32_bf16 v[90:93], v[142:145], v[204:207], v[90:93]
	v_mfma_f32_16x16x32_bf16 v[74:77], v[142:145], v[212:215], v[74:77]
	v_mfma_f32_16x16x32_bf16 v[78:81], v[126:129], v[212:215], v[78:81]
	v_mfma_f32_16x16x32_bf16 v[122:125], v[146:149], v[184:187], v[122:125]
	v_mfma_f32_16x16x32_bf16 v[118:121], v[174:177], v[184:187], v[118:121]
	v_mfma_f32_16x16x32_bf16 v[98:101], v[174:177], v[192:195], v[98:101]
	v_mfma_f32_16x16x32_bf16 v[102:105], v[146:149], v[192:195], v[102:105]
	v_mfma_f32_16x16x32_bf16 v[86:89], v[146:149], v[200:203], v[86:89]
	v_mfma_f32_16x16x32_bf16 v[82:85], v[174:177], v[200:203], v[82:85]
	v_mfma_f32_16x16x32_bf16 v[66:69], v[174:177], v[208:211], v[66:69]
	v_mfma_f32_16x16x32_bf16 v[70:73], v[146:149], v[208:211], v[70:73]
	v_mfma_f32_16x16x32_bf16 v[122:125], v[150:153], v[188:191], v[122:125]
	v_mfma_f32_16x16x32_bf16 v[118:121], v[178:181], v[188:191], v[118:121]
	v_mfma_f32_16x16x32_bf16 v[98:101], v[178:181], v[196:199], v[98:101]
	v_mfma_f32_16x16x32_bf16 v[102:105], v[150:153], v[196:199], v[102:105]
	s_barrier
	s_setprio 2
	v_mfma_f32_16x16x32_bf16 v[86:89], v[150:153], v[204:207], v[86:89]
	v_mfma_f32_16x16x32_bf16 v[82:85], v[178:181], v[204:207], v[82:85]
	v_mfma_f32_16x16x32_bf16 v[66:69], v[178:181], v[212:215], v[66:69]
	v_mfma_f32_16x16x32_bf16 v[70:73], v[150:153], v[212:215], v[70:73]
	s_setprio 0
	s_add_i32 s39, s73, s55
	v_lshl_add_u64 v[162:163], s[70:71], 0, v[154:155]
	s_mov_b32 m0, s39
	ds_read_b128 v[184:187], v169 offset:16384
	ds_read_b128 v[188:191], v169 offset:17408
	ds_read_b128 v[192:195], v169 offset:18432
	ds_read_b128 v[196:199], v169 offset:19456
	ds_read_b128 v[200:203], v169 offset:20480
	ds_read_b128 v[204:207], v169 offset:21504
	ds_read_b128 v[208:211], v169 offset:22528
	ds_read_b128 v[212:215], v169 offset:23552
	global_load_lds_dwordx4 v[162:163], off
	v_lshl_add_u64 v[216:217], v[162:163], 0, s[12:13]
	s_add_i32 m0, s39, 0x2000
	s_add_i32 s39, s74, s55
	global_load_lds_dwordx4 v[216:217], off
	v_lshl_add_u64 v[216:217], v[162:163], 0, s[14:15]
	s_mov_b32 m0, s39
	s_nop 0
	global_load_lds_dwordx4 v[216:217], off
	v_lshl_add_u64 v[216:217], v[162:163], 0, s[16:17]
	s_add_i32 m0, s39, 0x2000
	s_nop 0
	global_load_lds_dwordx4 v[216:217], off
	v_lshl_add_u64 v[216:217], s[68:69], 0, v[154:155]
	s_mov_b32 m0, s56
	v_lshl_add_u64 v[218:219], v[216:217], 0, s[12:13]
	global_load_lds_dwordx4 v[216:217], off
	s_mov_b32 m0, s57
	s_nop 0
	global_load_lds_dwordx4 v[218:219], off
	s_waitcnt vmcnt(8)
	s_waitcnt lgkmcnt(0)
	s_barrier
; #define PG8_STAGE(bufoff, gbase, voff) do { if constexpr (!pg8_noload<Epi>::value) { _Pragma("unroll") for (int _i = 0; _i < 2; ++_i) \
;         __builtin_amdgcn_global_load_lds((const unsigned*)((const char*)(gbase) + (size_t)_i * pstep + (voff)[0]), (PG8_LAS unsigned*)(lds + (bufoff) + ldsw + _i * 8192), 16, 0, 0); } } while (0)
; #define PG8_LDA(dst, b, h) do { _Pragma("unroll") for (int m = 0; m < 4; ++m) _Pragma("unroll") for (int k = 0; k < 2; ++k) dst[m][k] = *(const PG8_LAS bf16x8*)(lds + PG8_SA(b, h) + aoff + m * 2048 + k * 1024); } while (0)
; #define PG8_LDB(dst, b, h) do { _Pragma("unroll") for (int n = 0; n < 2; ++n) _Pragma("unroll") for (int k = 0; k < 2; ++k) dst[n][k] = *(const PG8_LAS bf16x8*)(lds + PG8_SB(b, h) + boff + n * 2048 + k * 1024); } while (0)
; #define PG8_MMA(ai, bj, At, Bt) do { __builtin_amdgcn_s_setprio(1); _Pragma("unroll") for (int m = 0; m < 4; ++m) _Pragma("unroll") for (int n = 0; n < 2; ++n) _Pragma("unroll") for (int k = 0; k < 2; ++k) \
;         acc[ai][bj][m][n] = __builtin_amdgcn_mfma_f32_16x16x32_bf16(Bt[n][k], At[m][k], acc[ai][bj][m][n], 0, 0, 0); __builtin_amdgcn_s_setprio(0); } while (0)
; #define PG8_WAIT_V(n) asm volatile("s_waitcnt vmcnt(" #n ")" ::: "memory")
; #define PG8_WAIT_L(n) asm volatile("s_waitcnt lgkmcnt(" #n ")" ::: "memory")
; #define PG8_BAR __builtin_amdgcn_s_barrier()
; #define PG8_SCHED __builtin_amdgcn_sched_barrier(0)
; template <class Epi, class Sched, bool ALIGN_EPI = false, bool SP2 = false, bool ABLK = false>
; __device__ __forceinline__ void gemm_phase(PG8_LAS unsigned char* lds, const Gemm g, const Sched& S, const Epi& E) {
;     ...
;             PG8_WAIT_V(8); PG8_WAIT_L(0); PG8_BAR; PG8_MMA(1, 0, At, B0); PG8_MMA(1, 1, At, B1); PG8_BAR; PG8_SCHED;
;             PG8_LDB(B0, 1, 0); PG8_LDB(B1, 1, 1); PG8_SCHED; PG8_LDA(At, 1, 0); PG8_STAGE(PG8_SA(0, 1), a2 + hstep, voffA);
;             PG8_WAIT_V(8); PG8_WAIT_L(0); PG8_BAR; PG8_MMA(0, 0, At, B0); PG8_MMA(0, 1, At, B1); PG8_BAR; PG8_SCHED;
	s_setprio 1
	s_waitcnt lgkmcnt(0)
	v_mfma_f32_16x16x32_bf16 v[62:65], v[114:117], v[184:187], v[62:65]
	v_mfma_f32_16x16x32_bf16 v[58:61], v[130:133], v[184:187], v[58:61]
	v_mfma_f32_16x16x32_bf16 v[42:45], v[130:133], v[192:195], v[42:45]
	v_mfma_f32_16x16x32_bf16 v[46:49], v[114:117], v[192:195], v[46:49]
	v_mfma_f32_16x16x32_bf16 v[30:33], v[114:117], v[200:203], v[30:33]
	v_mfma_f32_16x16x32_bf16 v[26:29], v[130:133], v[200:203], v[26:29]
	v_mfma_f32_16x16x32_bf16 v[10:13], v[130:133], v[208:211], v[10:13]
	v_mfma_f32_16x16x32_bf16 v[14:17], v[114:117], v[208:211], v[14:17]
	v_mfma_f32_16x16x32_bf16 v[62:65], v[126:129], v[188:191], v[62:65]
	v_mfma_f32_16x16x32_bf16 v[58:61], v[142:145], v[188:191], v[58:61]
	v_mfma_f32_16x16x32_bf16 v[42:45], v[142:145], v[196:199], v[42:45]
	v_mfma_f32_16x16x32_bf16 v[46:49], v[126:129], v[196:199], v[46:49]
	v_mfma_f32_16x16x32_bf16 v[30:33], v[126:129], v[204:207], v[30:33]
	v_mfma_f32_16x16x32_bf16 v[26:29], v[142:145], v[204:207], v[26:29]
	v_mfma_f32_16x16x32_bf16 v[10:13], v[142:145], v[212:215], v[10:13]
	v_mfma_f32_16x16x32_bf16 v[14:17], v[126:129], v[212:215], v[14:17]
	v_mfma_f32_16x16x32_bf16 v[54:57], v[146:149], v[184:187], v[54:57]
	v_mfma_f32_16x16x32_bf16 v[50:53], v[174:177], v[184:187], v[50:53]
	v_mfma_f32_16x16x32_bf16 v[34:37], v[174:177], v[192:195], v[34:37]
	v_mfma_f32_16x16x32_bf16 v[38:41], v[146:149], v[192:195], v[38:41]
	v_mfma_f32_16x16x32_bf16 v[22:25], v[146:149], v[200:203], v[22:25]
	v_mfma_f32_16x16x32_bf16 v[18:21], v[174:177], v[200:203], v[18:21]
	v_mfma_f32_16x16x32_bf16 v[2:5], v[174:177], v[208:211], v[2:5]
	v_mfma_f32_16x16x32_bf16 v[6:9], v[146:149], v[208:211], v[6:9]
	v_mfma_f32_16x16x32_bf16 v[54:57], v[150:153], v[188:191], v[54:57]
	v_mfma_f32_16x16x32_bf16 v[50:53], v[178:181], v[188:191], v[50:53]
	v_mfma_f32_16x16x32_bf16 v[34:37], v[178:181], v[196:199], v[34:37]
	v_mfma_f32_16x16x32_bf16 v[38:41], v[150:153], v[196:199], v[38:41]
	s_barrier
	s_setprio 2
	v_mfma_f32_16x16x32_bf16 v[22:25], v[150:153], v[204:207], v[22:25]
	v_mfma_f32_16x16x32_bf16 v[18:21], v[178:181], v[204:207], v[18:21]
	v_mfma_f32_16x16x32_bf16 v[2:5], v[178:181], v[212:215], v[2:5]
	v_mfma_f32_16x16x32_bf16 v[6:9], v[150:153], v[212:215], v[6:9]
	s_setprio 0
	s_add_i32 s39, 0, 0x18000
	s_add_i32 s68, 0, 0x1c000
	v_add_u32_e32 v142, s39, v1
	v_add_u32_e32 v173, s68, v1
	ds_read_b128 v[114:117], v142
	ds_read_b128 v[126:129], v142 offset:1024
	ds_read_b128 v[130:133], v142 offset:2048
	ds_read_b128 v[142:145], v142 offset:3072
	ds_read_b128 v[146:149], v173
	ds_read_b128 v[150:153], v173 offset:1024
	ds_read_b128 v[174:177], v173 offset:2048
	ds_read_b128 v[178:181], v173 offset:3072
	s_mov_b32 m0, s58
	v_lshl_add_u64 v[218:219], v[216:217], 0, s[14:15]
	ds_read_b128 v[184:187], v169 offset:32768
	ds_read_b128 v[188:191], v169 offset:33792
	ds_read_b128 v[192:195], v169 offset:34816
	ds_read_b128 v[196:199], v169 offset:35840
	ds_read_b128 v[200:203], v169 offset:36864
	ds_read_b128 v[204:207], v169 offset:37888
	ds_read_b128 v[208:211], v169 offset:38912
	ds_read_b128 v[212:215], v169 offset:39936
	global_load_lds_dwordx4 v[218:219], off
	v_lshl_add_u64 v[218:219], v[216:217], 0, s[16:17]
	s_mov_b32 m0, s59
	s_nop 0
	global_load_lds_dwordx4 v[218:219], off
	s_waitcnt vmcnt(8)
	s_waitcnt lgkmcnt(0)
	s_barrier
	s_setprio 1
	s_waitcnt lgkmcnt(0)
	v_mfma_f32_16x16x32_bf16 v[138:141], v[114:117], v[184:187], v[138:141]
	v_mfma_f32_16x16x32_bf16 v[134:137], v[130:133], v[184:187], v[134:137]
	v_mfma_f32_16x16x32_bf16 v[106:109], v[130:133], v[192:195], v[106:109]
	v_mfma_f32_16x16x32_bf16 v[110:113], v[114:117], v[192:195], v[110:113]
	v_mfma_f32_16x16x32_bf16 v[94:97], v[114:117], v[200:203], v[94:97]
	v_mfma_f32_16x16x32_bf16 v[90:93], v[130:133], v[200:203], v[90:93]
	v_mfma_f32_16x16x32_bf16 v[74:77], v[130:133], v[208:211], v[74:77]
	v_mfma_f32_16x16x32_bf16 v[78:81], v[114:117], v[208:211], v[78:81]
	v_mfma_f32_16x16x32_bf16 v[138:141], v[126:129], v[188:191], v[138:141]
	v_mfma_f32_16x16x32_bf16 v[134:137], v[142:145], v[188:191], v[134:137]
	v_mfma_f32_16x16x32_bf16 v[106:109], v[142:145], v[196:199], v[106:109]
	v_mfma_f32_16x16x32_bf16 v[110:113], v[126:129], v[196:199], v[110:113]
	v_mfma_f32_16x16x32_bf16 v[94:97], v[126:129], v[204:207], v[94:97]
	v_mfma_f32_16x16x32_bf16 v[90:93], v[142:145], v[204:207], v[90:93]
	v_mfma_f32_16x16x32_bf16 v[74:77], v[142:145], v[212:215], v[74:77]
	v_mfma_f32_16x16x32_bf16 v[78:81], v[126:129], v[212:215], v[78:81]
	v_mfma_f32_16x16x32_bf16 v[122:125], v[146:149], v[184:187], v[122:125]
	v_mfma_f32_16x16x32_bf16 v[118:121], v[174:177], v[184:187], v[118:121]
	v_mfma_f32_16x16x32_bf16 v[98:101], v[174:177], v[192:195], v[98:101]
	v_mfma_f32_16x16x32_bf16 v[102:105], v[146:149], v[192:195], v[102:105]
	v_mfma_f32_16x16x32_bf16 v[86:89], v[146:149], v[200:203], v[86:89]
	v_mfma_f32_16x16x32_bf16 v[82:85], v[174:177], v[200:203], v[82:85]
	v_mfma_f32_16x16x32_bf16 v[66:69], v[174:177], v[208:211], v[66:69]
	v_mfma_f32_16x16x32_bf16 v[70:73], v[146:149], v[208:211], v[70:73]
	v_mfma_f32_16x16x32_bf16 v[122:125], v[150:153], v[188:191], v[122:125]
	v_mfma_f32_16x16x32_bf16 v[118:121], v[178:181], v[188:191], v[118:121]
	v_mfma_f32_16x16x32_bf16 v[98:101], v[178:181], v[196:199], v[98:101]
	v_mfma_f32_16x16x32_bf16 v[102:105], v[150:153], v[196:199], v[102:105]
	s_barrier
; #define PG8_STAGE(bufoff, gbase, voff) do { if constexpr (!pg8_noload<Epi>::value) { _Pragma("unroll") for (int _i = 0; _i < 2; ++_i) \
;         __builtin_amdgcn_global_load_lds((const unsigned*)((const char*)(gbase) + (size_t)_i * pstep + (voff)[0]), (PG8_LAS unsigned*)(lds + (bufoff) + ldsw + _i * 8192), 16, 0, 0); } } while (0)
; #define PG8_LDA(dst, b, h) do { _Pragma("unroll") for (int m = 0; m < 4; ++m) _Pragma("unroll") for (int k = 0; k < 2; ++k) dst[m][k] = *(const PG8_LAS bf16x8*)(lds + PG8_SA(b, h) + aoff + m * 2048 + k * 1024); } while (0)
; #define PG8_MMA(ai, bj, At, Bt) do { __builtin_amdgcn_s_setprio(1); _Pragma("unroll") for (int m = 0; m < 4; ++m) _Pragma("unroll") for (int n = 0; n < 2; ++n) _Pragma("unroll") for (int k = 0; k < 2; ++k) \
;         acc[ai][bj][m][n] = __builtin_amdgcn_mfma_f32_16x16x32_bf16(Bt[n][k], At[m][k], acc[ai][bj][m][n], 0, 0, 0); __builtin_amdgcn_s_setprio(0); } while (0)
; #define PG8_WAIT_V(n) asm volatile("s_waitcnt vmcnt(" #n ")" ::: "memory")
; #define PG8_WAIT_L(n) asm volatile("s_waitcnt lgkmcnt(" #n ")" ::: "memory")
; #define PG8_BAR __builtin_amdgcn_s_barrier()
; #define PG8_SCHED __builtin_amdgcn_sched_barrier(0)
;     __device__ __forceinline__ void operator()(const f32x4 (&acc)[2][2][4][2], const Unit& u, int wr, int wc, int fr, int fq) const {
;         const int c0 = u.pn * BM + wc * 32 + 8 * fq;
;         if (u.pm * BM < seq) {
;             bf16_t* xbb = XB + ((size_t)(u.pm * 16 + wr * 4) * 64 + u.pn * 8 + 2 * wc) * 512 + fr * 32 + (((fq * 16) ^ ((fr >> 3) << 5)) >> 1);
; template <class Epi, class Sched, bool ALIGN_EPI = false, bool SP2 = false, bool ABLK = false>
; __device__ __forceinline__ void gemm_phase(PG8_LAS unsigned char* lds, const Gemm g, const Sched& S, const Epi& E) {
;     ...
;         for (int t = 0; t < nt; t += 2) {
;     ...
;             PG8_WAIT_V(8); PG8_WAIT_L(0); PG8_BAR; PG8_MMA(0, 0, At, B0); PG8_MMA(0, 1, At, B1); PG8_BAR; PG8_SCHED;
;             PG8_LDA(At, 1, 1); PG8_STAGE(PG8_SB(1, 0), b3, voffB); PG8_STAGE(PG8_SB(1, 1), b3 + hstep, voffB); PG8_STAGE(PG8_SA(1, 0), a3, voffA);
;             PG8_WAIT_V(8); PG8_WAIT_L(0); PG8_BAR; PG8_MMA(1, 0, At, B0); PG8_MMA(1, 1, At, B1); PG8_BAR; PG8_SCHED;
	s_setprio 2
	v_mfma_f32_16x16x32_bf16 v[86:89], v[150:153], v[204:207], v[86:89]
	v_mfma_f32_16x16x32_bf16 v[82:85], v[178:181], v[204:207], v[82:85]
	v_mfma_f32_16x16x32_bf16 v[66:69], v[178:181], v[212:215], v[66:69]
	v_mfma_f32_16x16x32_bf16 v[70:73], v[150:153], v[212:215], v[70:73]
	s_setprio 0
	s_add_i32 s39, s39, s55
	v_lshl_add_u64 v[218:219], v[162:163], 0, s[24:25]
	s_mov_b32 m0, s39
	ds_read_b128 v[184:187], v169 offset:49152
	ds_read_b128 v[188:191], v169 offset:50176
	ds_read_b128 v[192:195], v169 offset:51200
	ds_read_b128 v[196:199], v169 offset:52224
	ds_read_b128 v[200:203], v169 offset:53248
	ds_read_b128 v[204:207], v169 offset:54272
	ds_read_b128 v[208:211], v169 offset:55296
	ds_read_b128 v[212:215], v169 offset:56320
	global_load_lds_dwordx4 v[218:219], off
	v_lshl_add_u64 v[218:219], v[162:163], 0, s[26:27]
	s_add_i32 m0, s39, 0x2000
	s_add_i32 s39, s68, s55
	global_load_lds_dwordx4 v[218:219], off
	v_lshl_add_u64 v[218:219], v[162:163], 0, s[28:29]
	s_mov_b32 m0, s39
	v_lshl_add_u64 v[162:163], v[162:163], 0, s[30:31]
	global_load_lds_dwordx4 v[218:219], off
	s_add_i32 m0, s39, 0x2000
	s_nop 0
	global_load_lds_dwordx4 v[162:163], off
	v_lshl_add_u64 v[162:163], v[216:217], 0, s[24:25]
	s_mov_b32 m0, s62
	s_nop 0
	global_load_lds_dwordx4 v[162:163], off
	v_lshl_add_u64 v[162:163], v[216:217], 0, s[26:27]
	s_mov_b32 m0, s63
	s_nop 0
	global_load_lds_dwordx4 v[162:163], off
	s_waitcnt vmcnt(8)
	s_waitcnt lgkmcnt(0)
	s_barrier
	s_setprio 1
	s_waitcnt lgkmcnt(0)
	v_mfma_f32_16x16x32_bf16 v[62:65], v[114:117], v[184:187], v[62:65]
	v_mfma_f32_16x16x32_bf16 v[58:61], v[130:133], v[184:187], v[58:61]
	v_mfma_f32_16x16x32_bf16 v[42:45], v[130:133], v[192:195], v[42:45]
	v_mfma_f32_16x16x32_bf16 v[46:49], v[114:117], v[192:195], v[46:49]
	v_mfma_f32_16x16x32_bf16 v[30:33], v[114:117], v[200:203], v[30:33]
	v_mfma_f32_16x16x32_bf16 v[26:29], v[130:133], v[200:203], v[26:29]
	v_mfma_f32_16x16x32_bf16 v[10:13], v[130:133], v[208:211], v[10:13]
	v_mfma_f32_16x16x32_bf16 v[14:17], v[114:117], v[208:211], v[14:17]
	v_mfma_f32_16x16x32_bf16 v[62:65], v[126:129], v[188:191], v[62:65]
	v_mfma_f32_16x16x32_bf16 v[58:61], v[142:145], v[188:191], v[58:61]
	v_mfma_f32_16x16x32_bf16 v[42:45], v[142:145], v[196:199], v[42:45]
	v_mfma_f32_16x16x32_bf16 v[46:49], v[126:129], v[196:199], v[46:49]
	v_mfma_f32_16x16x32_bf16 v[30:33], v[126:129], v[204:207], v[30:33]
	v_mfma_f32_16x16x32_bf16 v[26:29], v[142:145], v[204:207], v[26:29]
	v_mfma_f32_16x16x32_bf16 v[10:13], v[142:145], v[212:215], v[10:13]
	v_mfma_f32_16x16x32_bf16 v[14:17], v[126:129], v[212:215], v[14:17]
	v_mfma_f32_16x16x32_bf16 v[54:57], v[146:149], v[184:187], v[54:57]
	v_mfma_f32_16x16x32_bf16 v[50:53], v[174:177], v[184:187], v[50:53]
	v_mfma_f32_16x16x32_bf16 v[34:37], v[174:177], v[192:195], v[34:37]
	v_mfma_f32_16x16x32_bf16 v[38:41], v[146:149], v[192:195], v[38:41]
	v_mfma_f32_16x16x32_bf16 v[22:25], v[146:149], v[200:203], v[22:25]
	v_mfma_f32_16x16x32_bf16 v[18:21], v[174:177], v[200:203], v[18:21]
	v_mfma_f32_16x16x32_bf16 v[2:5], v[174:177], v[208:211], v[2:5]
	v_mfma_f32_16x16x32_bf16 v[6:9], v[146:149], v[208:211], v[6:9]
	v_mfma_f32_16x16x32_bf16 v[54:57], v[150:153], v[188:191], v[54:57]
	v_mfma_f32_16x16x32_bf16 v[50:53], v[178:181], v[188:191], v[50:53]
	v_mfma_f32_16x16x32_bf16 v[34:37], v[178:181], v[196:199], v[34:37]
	v_mfma_f32_16x16x32_bf16 v[38:41], v[150:153], v[196:199], v[38:41]
	s_barrier
	s_setprio 2
	v_mfma_f32_16x16x32_bf16 v[22:25], v[150:153], v[204:207], v[22:25]
	v_mfma_f32_16x16x32_bf16 v[18:21], v[178:181], v[204:207], v[18:21]
	v_mfma_f32_16x16x32_bf16 v[2:5], v[178:181], v[212:215], v[2:5]
	v_mfma_f32_16x16x32_bf16 v[6:9], v[150:153], v[212:215], v[6:9]
	s_setprio 0
	s_add_u32 s92, s92, 0x1000
	s_addc_u32 s93, s93, 0
	s_add_u32 s11, s11, 0x1000
	s_addc_u32 s37, s37, 0
	s_cmp_ge_i32 s65, s80
	s_mov_b32 s39, s65
	s_cbranch_scc0 .LBB0_487
	s_and_b64 vcc, exec, s[34:35]
	s_cbranch_vccnz .LBB0_492
	s_lshl_b32 s11, s2, 8
	s_cmp_gt_i32 s2, 63
	s_mov_b64 s[68:69], -1
	s_cbranch_scc1 .LBB0_493

; #define PG8_STAGE(bufoff, gbase, voff) do { if constexpr (!pg8_noload<Epi>::value) { _Pragma("unroll") for (int _i = 0; _i < 2; ++_i) \
;         __builtin_amdgcn_global_load_lds((const unsigned*)((const char*)(gbase) + (size_t)_i * pstep + (voff)[0]), (PG8_LAS unsigned*)(lds + (bufoff) + ldsw + _i * 8192), 16, 0, 0); } } while (0)
; #define PG8_LDA(dst, b, h) do { _Pragma("unroll") for (int m = 0; m < 4; ++m) _Pragma("unroll") for (int k = 0; k < 2; ++k) dst[m][k] = *(const PG8_LAS bf16x8*)(lds + PG8_SA(b, h) + aoff + m * 2048 + k * 1024); } while (0)
; #define PG8_LDB(dst, b, h) do { _Pragma("unroll") for (int n = 0; n < 2; ++n) _Pragma("unroll") for (int k = 0; k < 2; ++k) dst[n][k] = *(const PG8_LAS bf16x8*)(lds + PG8_SB(b, h) + boff + n * 2048 + k * 1024); } while (0)
; #define PG8_MMA(ai, bj, At, Bt) do { __builtin_amdgcn_s_setprio(1); _Pragma("unroll") for (int m = 0; m < 4; ++m) _Pragma("unroll") for (int n = 0; n < 2; ++n) _Pragma("unroll") for (int k = 0; k < 2; ++k) \
;         acc[ai][bj][m][n] = __builtin_amdgcn_mfma_f32_16x16x32_bf16(Bt[n][k], At[m][k], acc[ai][bj][m][n], 0, 0, 0); __builtin_amdgcn_s_setprio(0); } while (0)
; #define PG8_WAIT_V(n) asm volatile("s_waitcnt vmcnt(" #n ")" ::: "memory")
; #define PG8_WAIT_L(n) asm volatile("s_waitcnt lgkmcnt(" #n ")" ::: "memory")
; #define PG8_BAR __builtin_amdgcn_s_barrier()
; template <class Epi, class Sched, bool ALIGN_EPI = false, bool SP2 = false, bool ABLK = false>
; __device__ __forceinline__ void gemm_phase(PG8_LAS unsigned char* lds, const Gemm g, const Sched& S, const Epi& E) {
;     ...
;             const bool last = (t == nt - 2);
;             const char* a1 = cA + (size_t)(t + 1) * kstep;
;             const char* a2 = last ? nA : cA + (size_t)(t + 2) * kstep; const char* b2 = last ? nB : cB + (size_t)(t + 2) * kstepB;
;             const char* a3 = a2 + kstep; const char* b3 = b2 + kstepB;
;             if (last && has_next) S.a_ready(nxt);
;             if constexpr (SP2) {
;             PG8_LDB(B0, 0, 0); PG8_LDB(B1, 0, 1); PG8_SCHED; PG8_LDA(At, 0, 0); PG8_STAGE(PG8_SA(1, 1), a1 + hstep, voffA);
;             PG8_WAIT_V(8); PG8_WAIT_L(0); PG8_BAR; PG8_MMA(0, 0, At, B0); PG8_MMA(0, 1, At, B1); PG8_BAR; PG8_SCHED;
;             PG8_LDA(At, 0, 1); PG8_STAGE(PG8_SB(0, 0), b2, voffB); PG8_STAGE(PG8_SB(0, 1), b2 + hstep, voffB); PG8_STAGE(PG8_SA(0, 0), a2, voffA);
.LBB0_619:
	s_or_b32 s28, s57, 1
	s_lshl_b64 s[58:59], s[28:29], 11
	s_add_u32 s58, s2, s58
	s_addc_u32 s59, s3, s59
	s_add_i32 s28, s57, 2
	v_add_u32_e32 v160, s78, v168
	v_add_u32_e32 v180, s79, v168
	s_lshl_b64 s[60:61], s[28:29], 11
	ds_read_b128 v[130:133], v160
	ds_read_b128 v[134:137], v160 offset:1024
	ds_read_b128 v[156:159], v160 offset:2048
	ds_read_b128 v[160:163], v160 offset:3072
	ds_read_b128 v[164:167], v180
	ds_read_b128 v[176:179], v180 offset:1024
	ds_read_b128 v[184:187], v180 offset:2048
	ds_read_b128 v[188:191], v180 offset:3072
	s_add_u32 s66, s2, s60
	s_addc_u32 s67, s3, s61
	s_and_b64 s[62:63], s[68:69], exec
	s_cselect_b32 s73, s67, s7
	s_cselect_b32 s72, s66, s15
	s_add_u32 s62, s16, s60
	s_addc_u32 s63, s17, s61
	s_and_b64 s[60:61], s[68:69], exec
	s_cselect_b32 s61, s63, s9
	s_cselect_b32 s60, s62, s56
	v_lshl_add_u64 v[180:181], s[58:59], 0, v[138:139]
	v_lshl_add_u64 v[224:225], v[180:181], 0, s[24:25]
	s_add_i32 m0, s70, 0xc000
	ds_read_b128 v[192:195], v173
	ds_read_b128 v[196:199], v173 offset:1024
	ds_read_b128 v[200:203], v173 offset:2048
	ds_read_b128 v[204:207], v173 offset:3072
	ds_read_b128 v[208:211], v173 offset:4096
	ds_read_b128 v[212:215], v173 offset:5120
	ds_read_b128 v[216:219], v173 offset:6144
	ds_read_b128 v[220:223], v173 offset:7168
	global_load_lds_dwordx4 v[224:225], off
	v_lshl_add_u64 v[180:181], v[180:181], 0, s[26:27]
	s_add_i32 m0, s70, 0xe000
	s_nop 0
	global_load_lds_dwordx4 v[180:181], off
	s_waitcnt vmcnt(8)
	s_waitcnt lgkmcnt(0)
	s_barrier
	s_setprio 1
	s_waitcnt lgkmcnt(0)
	v_mfma_f32_16x16x32_bf16 v[126:129], v[130:133], v[192:195], v[126:129]
	v_mfma_f32_16x16x32_bf16 v[122:125], v[156:159], v[192:195], v[122:125]
	v_mfma_f32_16x16x32_bf16 v[106:109], v[156:159], v[200:203], v[106:109]
	v_mfma_f32_16x16x32_bf16 v[110:113], v[130:133], v[200:203], v[110:113]
	v_mfma_f32_16x16x32_bf16 v[94:97], v[130:133], v[208:211], v[94:97]
	v_mfma_f32_16x16x32_bf16 v[90:93], v[156:159], v[208:211], v[90:93]
	v_mfma_f32_16x16x32_bf16 v[74:77], v[156:159], v[216:219], v[74:77]
	v_mfma_f32_16x16x32_bf16 v[78:81], v[130:133], v[216:219], v[78:81]
	v_mfma_f32_16x16x32_bf16 v[126:129], v[134:137], v[196:199], v[126:129]
	v_mfma_f32_16x16x32_bf16 v[122:125], v[160:163], v[196:199], v[122:125]
	v_mfma_f32_16x16x32_bf16 v[106:109], v[160:163], v[204:207], v[106:109]
	v_mfma_f32_16x16x32_bf16 v[110:113], v[134:137], v[204:207], v[110:113]
	v_mfma_f32_16x16x32_bf16 v[94:97], v[134:137], v[212:215], v[94:97]
	v_mfma_f32_16x16x32_bf16 v[90:93], v[160:163], v[212:215], v[90:93]
	v_mfma_f32_16x16x32_bf16 v[74:77], v[160:163], v[220:223], v[74:77]
	v_mfma_f32_16x16x32_bf16 v[78:81], v[134:137], v[220:223], v[78:81]
	v_mfma_f32_16x16x32_bf16 v[118:121], v[164:167], v[192:195], v[118:121]
	v_mfma_f32_16x16x32_bf16 v[114:117], v[184:187], v[192:195], v[114:117]
	v_mfma_f32_16x16x32_bf16 v[98:101], v[184:187], v[200:203], v[98:101]
	v_mfma_f32_16x16x32_bf16 v[102:105], v[164:167], v[200:203], v[102:105]
	v_mfma_f32_16x16x32_bf16 v[86:89], v[164:167], v[208:211], v[86:89]
	v_mfma_f32_16x16x32_bf16 v[82:85], v[184:187], v[208:211], v[82:85]
	v_mfma_f32_16x16x32_bf16 v[66:69], v[184:187], v[216:219], v[66:69]
	v_mfma_f32_16x16x32_bf16 v[70:73], v[164:167], v[216:219], v[70:73]
	v_mfma_f32_16x16x32_bf16 v[118:121], v[176:179], v[196:199], v[118:121]
	v_mfma_f32_16x16x32_bf16 v[114:117], v[188:191], v[196:199], v[114:117]
	v_mfma_f32_16x16x32_bf16 v[98:101], v[188:191], v[204:207], v[98:101]
	v_mfma_f32_16x16x32_bf16 v[102:105], v[176:179], v[204:207], v[102:105]
	s_barrier
	s_setprio 2
	v_mfma_f32_16x16x32_bf16 v[86:89], v[176:179], v[212:215], v[86:89]
	v_mfma_f32_16x16x32_bf16 v[82:85], v[188:191], v[212:215], v[82:85]
	v_mfma_f32_16x16x32_bf16 v[66:69], v[188:191], v[220:223], v[66:69]
	v_mfma_f32_16x16x32_bf16 v[70:73], v[176:179], v[220:223], v[70:73]
	s_setprio 0
	s_add_i32 s58, s78, s91
	v_lshl_add_u64 v[180:181], s[60:61], 0, v[138:139]
	s_mov_b32 m0, s58
	ds_read_b128 v[192:195], v173 offset:16384
	ds_read_b128 v[196:199], v173 offset:17408
	ds_read_b128 v[200:203], v173 offset:18432
	ds_read_b128 v[204:207], v173 offset:19456
	ds_read_b128 v[208:211], v173 offset:20480
	ds_read_b128 v[212:215], v173 offset:21504
	ds_read_b128 v[216:219], v173 offset:22528
	ds_read_b128 v[220:223], v173 offset:23552
	global_load_lds_dwordx4 v[180:181], off
	v_lshl_add_u64 v[224:225], v[180:181], 0, s[22:23]
	s_add_i32 m0, s58, 0x2000
	s_add_i32 s58, s79, s91
	global_load_lds_dwordx4 v[224:225], off
	v_lshl_add_u64 v[224:225], v[180:181], 0, s[24:25]
	s_mov_b32 m0, s58
	s_nop 0
	global_load_lds_dwordx4 v[224:225], off
	v_lshl_add_u64 v[224:225], v[180:181], 0, s[26:27]
	s_add_i32 m0, s58, 0x2000
	s_nop 0
	global_load_lds_dwordx4 v[224:225], off
	v_lshl_add_u64 v[224:225], s[72:73], 0, v[138:139]
	s_mov_b32 m0, s70
	v_lshl_add_u64 v[226:227], v[224:225], 0, s[22:23]
	global_load_lds_dwordx4 v[224:225], off
	s_mov_b32 m0, s71
	s_nop 0
	global_load_lds_dwordx4 v[226:227], off
	s_waitcnt vmcnt(8)
	s_waitcnt lgkmcnt(0)
	s_barrier
; #define PG8_STAGE(bufoff, gbase, voff) do { if constexpr (!pg8_noload<Epi>::value) { _Pragma("unroll") for (int _i = 0; _i < 2; ++_i) \
;         __builtin_amdgcn_global_load_lds((const unsigned*)((const char*)(gbase) + (size_t)_i * pstep + (voff)[0]), (PG8_LAS unsigned*)(lds + (bufoff) + ldsw + _i * 8192), 16, 0, 0); } } while (0)
; #define PG8_LDA(dst, b, h) do { _Pragma("unroll") for (int m = 0; m < 4; ++m) _Pragma("unroll") for (int k = 0; k < 2; ++k) dst[m][k] = *(const PG8_LAS bf16x8*)(lds + PG8_SA(b, h) + aoff + m * 2048 + k * 1024); } while (0)
; #define PG8_LDB(dst, b, h) do { _Pragma("unroll") for (int n = 0; n < 2; ++n) _Pragma("unroll") for (int k = 0; k < 2; ++k) dst[n][k] = *(const PG8_LAS bf16x8*)(lds + PG8_SB(b, h) + boff + n * 2048 + k * 1024); } while (0)
; #define PG8_MMA(ai, bj, At, Bt) do { __builtin_amdgcn_s_setprio(1); _Pragma("unroll") for (int m = 0; m < 4; ++m) _Pragma("unroll") for (int n = 0; n < 2; ++n) _Pragma("unroll") for (int k = 0; k < 2; ++k) \
;         acc[ai][bj][m][n] = __builtin_amdgcn_mfma_f32_16x16x32_bf16(Bt[n][k], At[m][k], acc[ai][bj][m][n], 0, 0, 0); __builtin_amdgcn_s_setprio(0); } while (0)
; #define PG8_WAIT_V(n) asm volatile("s_waitcnt vmcnt(" #n ")" ::: "memory")
; #define PG8_WAIT_L(n) asm volatile("s_waitcnt lgkmcnt(" #n ")" ::: "memory")
; #define PG8_BAR __builtin_amdgcn_s_barrier()
; #define PG8_SCHED __builtin_amdgcn_sched_barrier(0)
; template <class Epi, class Sched, bool ALIGN_EPI = false, bool SP2 = false, bool ABLK = false>
; __device__ __forceinline__ void gemm_phase(PG8_LAS unsigned char* lds, const Gemm g, const Sched& S, const Epi& E) {
;     ...
;             PG8_WAIT_V(8); PG8_WAIT_L(0); PG8_BAR; PG8_MMA(1, 0, At, B0); PG8_MMA(1, 1, At, B1); PG8_BAR; PG8_SCHED;
;             PG8_LDB(B0, 1, 0); PG8_LDB(B1, 1, 1); PG8_SCHED; PG8_LDA(At, 1, 0); PG8_STAGE(PG8_SA(0, 1), a2 + hstep, voffA);
;             PG8_WAIT_V(8); PG8_WAIT_L(0); PG8_BAR; PG8_MMA(0, 0, At, B0); PG8_MMA(0, 1, At, B1); PG8_BAR; PG8_SCHED;
	s_setprio 1
	s_waitcnt lgkmcnt(0)
	v_mfma_f32_16x16x32_bf16 v[62:65], v[130:133], v[192:195], v[62:65]
	v_mfma_f32_16x16x32_bf16 v[58:61], v[156:159], v[192:195], v[58:61]
	v_mfma_f32_16x16x32_bf16 v[42:45], v[156:159], v[200:203], v[42:45]
	v_mfma_f32_16x16x32_bf16 v[46:49], v[130:133], v[200:203], v[46:49]
	v_mfma_f32_16x16x32_bf16 v[30:33], v[130:133], v[208:211], v[30:33]
	v_mfma_f32_16x16x32_bf16 v[26:29], v[156:159], v[208:211], v[26:29]
	v_mfma_f32_16x16x32_bf16 v[10:13], v[156:159], v[216:219], v[10:13]
	v_mfma_f32_16x16x32_bf16 v[14:17], v[130:133], v[216:219], v[14:17]
	v_mfma_f32_16x16x32_bf16 v[62:65], v[134:137], v[196:199], v[62:65]
	v_mfma_f32_16x16x32_bf16 v[58:61], v[160:163], v[196:199], v[58:61]
	v_mfma_f32_16x16x32_bf16 v[42:45], v[160:163], v[204:207], v[42:45]
	v_mfma_f32_16x16x32_bf16 v[46:49], v[134:137], v[204:207], v[46:49]
	v_mfma_f32_16x16x32_bf16 v[30:33], v[134:137], v[212:215], v[30:33]
	v_mfma_f32_16x16x32_bf16 v[26:29], v[160:163], v[212:215], v[26:29]
	v_mfma_f32_16x16x32_bf16 v[10:13], v[160:163], v[220:223], v[10:13]
	v_mfma_f32_16x16x32_bf16 v[14:17], v[134:137], v[220:223], v[14:17]
	v_mfma_f32_16x16x32_bf16 v[54:57], v[164:167], v[192:195], v[54:57]
	v_mfma_f32_16x16x32_bf16 v[50:53], v[184:187], v[192:195], v[50:53]
	v_mfma_f32_16x16x32_bf16 v[34:37], v[184:187], v[200:203], v[34:37]
	v_mfma_f32_16x16x32_bf16 v[38:41], v[164:167], v[200:203], v[38:41]
	v_mfma_f32_16x16x32_bf16 v[22:25], v[164:167], v[208:211], v[22:25]
	v_mfma_f32_16x16x32_bf16 v[18:21], v[184:187], v[208:211], v[18:21]
	v_mfma_f32_16x16x32_bf16 v[2:5], v[184:187], v[216:219], v[2:5]
	v_mfma_f32_16x16x32_bf16 v[6:9], v[164:167], v[216:219], v[6:9]
	v_mfma_f32_16x16x32_bf16 v[54:57], v[176:179], v[196:199], v[54:57]
	v_mfma_f32_16x16x32_bf16 v[50:53], v[188:191], v[196:199], v[50:53]
	v_mfma_f32_16x16x32_bf16 v[34:37], v[188:191], v[204:207], v[34:37]
	v_mfma_f32_16x16x32_bf16 v[38:41], v[176:179], v[204:207], v[38:41]
	s_barrier
	s_setprio 2
	v_mfma_f32_16x16x32_bf16 v[22:25], v[176:179], v[212:215], v[22:25]
	v_mfma_f32_16x16x32_bf16 v[18:21], v[188:191], v[212:215], v[18:21]
	v_mfma_f32_16x16x32_bf16 v[2:5], v[188:191], v[220:223], v[2:5]
	v_mfma_f32_16x16x32_bf16 v[6:9], v[176:179], v[220:223], v[6:9]
	s_setprio 0
	s_add_i32 s58, 0, 0x18000
	s_add_i32 s59, 0, 0x1c000
	v_add_u32_e32 v160, s58, v168
	v_add_u32_e32 v188, s59, v168
	ds_read_b128 v[130:133], v160
	ds_read_b128 v[134:137], v160 offset:1024
	ds_read_b128 v[156:159], v160 offset:2048
	ds_read_b128 v[160:163], v160 offset:3072
	ds_read_b128 v[164:167], v188
	ds_read_b128 v[176:179], v188 offset:1024
	ds_read_b128 v[184:187], v188 offset:2048
	ds_read_b128 v[188:191], v188 offset:3072
	s_mov_b32 m0, s34
	v_lshl_add_u64 v[226:227], v[224:225], 0, s[24:25]
	ds_read_b128 v[192:195], v173 offset:32768
	ds_read_b128 v[196:199], v173 offset:33792
	ds_read_b128 v[200:203], v173 offset:34816
	ds_read_b128 v[204:207], v173 offset:35840
	ds_read_b128 v[208:211], v173 offset:36864
	ds_read_b128 v[212:215], v173 offset:37888
	ds_read_b128 v[216:219], v173 offset:38912
	ds_read_b128 v[220:223], v173 offset:39936
	global_load_lds_dwordx4 v[226:227], off
	v_lshl_add_u64 v[226:227], v[224:225], 0, s[26:27]
	s_mov_b32 m0, s35
	s_nop 0
	global_load_lds_dwordx4 v[226:227], off
	s_waitcnt vmcnt(8)
	s_waitcnt lgkmcnt(0)
	s_barrier
	s_setprio 1
	s_waitcnt lgkmcnt(0)
	v_mfma_f32_16x16x32_bf16 v[126:129], v[130:133], v[192:195], v[126:129]
	v_mfma_f32_16x16x32_bf16 v[122:125], v[156:159], v[192:195], v[122:125]
	v_mfma_f32_16x16x32_bf16 v[106:109], v[156:159], v[200:203], v[106:109]
	v_mfma_f32_16x16x32_bf16 v[110:113], v[130:133], v[200:203], v[110:113]
	v_mfma_f32_16x16x32_bf16 v[94:97], v[130:133], v[208:211], v[94:97]
	v_mfma_f32_16x16x32_bf16 v[90:93], v[156:159], v[208:211], v[90:93]
	v_mfma_f32_16x16x32_bf16 v[74:77], v[156:159], v[216:219], v[74:77]
	v_mfma_f32_16x16x32_bf16 v[78:81], v[130:133], v[216:219], v[78:81]
	v_mfma_f32_16x16x32_bf16 v[126:129], v[134:137], v[196:199], v[126:129]
	v_mfma_f32_16x16x32_bf16 v[122:125], v[160:163], v[196:199], v[122:125]
	v_mfma_f32_16x16x32_bf16 v[106:109], v[160:163], v[204:207], v[106:109]
	v_mfma_f32_16x16x32_bf16 v[110:113], v[134:137], v[204:207], v[110:113]
	v_mfma_f32_16x16x32_bf16 v[94:97], v[134:137], v[212:215], v[94:97]
	v_mfma_f32_16x16x32_bf16 v[90:93], v[160:163], v[212:215], v[90:93]
	v_mfma_f32_16x16x32_bf16 v[74:77], v[160:163], v[220:223], v[74:77]
	v_mfma_f32_16x16x32_bf16 v[78:81], v[134:137], v[220:223], v[78:81]
	v_mfma_f32_16x16x32_bf16 v[118:121], v[164:167], v[192:195], v[118:121]
	v_mfma_f32_16x16x32_bf16 v[114:117], v[184:187], v[192:195], v[114:117]
	v_mfma_f32_16x16x32_bf16 v[98:101], v[184:187], v[200:203], v[98:101]
	v_mfma_f32_16x16x32_bf16 v[102:105], v[164:167], v[200:203], v[102:105]
	v_mfma_f32_16x16x32_bf16 v[86:89], v[164:167], v[208:211], v[86:89]
	v_mfma_f32_16x16x32_bf16 v[82:85], v[184:187], v[208:211], v[82:85]
	v_mfma_f32_16x16x32_bf16 v[66:69], v[184:187], v[216:219], v[66:69]
	v_mfma_f32_16x16x32_bf16 v[70:73], v[164:167], v[216:219], v[70:73]
	v_mfma_f32_16x16x32_bf16 v[118:121], v[176:179], v[196:199], v[118:121]
	v_mfma_f32_16x16x32_bf16 v[114:117], v[188:191], v[196:199], v[114:117]
	v_mfma_f32_16x16x32_bf16 v[98:101], v[188:191], v[204:207], v[98:101]
	v_mfma_f32_16x16x32_bf16 v[102:105], v[176:179], v[204:207], v[102:105]
	s_barrier
; #define PG8_STAGE(bufoff, gbase, voff) do { if constexpr (!pg8_noload<Epi>::value) { _Pragma("unroll") for (int _i = 0; _i < 2; ++_i) \
;         __builtin_amdgcn_global_load_lds((const unsigned*)((const char*)(gbase) + (size_t)_i * pstep + (voff)[0]), (PG8_LAS unsigned*)(lds + (bufoff) + ldsw + _i * 8192), 16, 0, 0); } } while (0)
; #define PG8_LDA(dst, b, h) do { _Pragma("unroll") for (int m = 0; m < 4; ++m) _Pragma("unroll") for (int k = 0; k < 2; ++k) dst[m][k] = *(const PG8_LAS bf16x8*)(lds + PG8_SA(b, h) + aoff + m * 2048 + k * 1024); } while (0)
; #define PG8_MMA(ai, bj, At, Bt) do { __builtin_amdgcn_s_setprio(1); _Pragma("unroll") for (int m = 0; m < 4; ++m) _Pragma("unroll") for (int n = 0; n < 2; ++n) _Pragma("unroll") for (int k = 0; k < 2; ++k) \
;         acc[ai][bj][m][n] = __builtin_amdgcn_mfma_f32_16x16x32_bf16(Bt[n][k], At[m][k], acc[ai][bj][m][n], 0, 0, 0); __builtin_amdgcn_s_setprio(0); } while (0)
; #define PG8_WAIT_V(n) asm volatile("s_waitcnt vmcnt(" #n ")" ::: "memory")
; #define PG8_WAIT_L(n) asm volatile("s_waitcnt lgkmcnt(" #n ")" ::: "memory")
; #define PG8_BAR __builtin_amdgcn_s_barrier()
; #define PG8_SCHED __builtin_amdgcn_sched_barrier(0)
; template <class Epi, class Sched, bool ALIGN_EPI = false, bool SP2 = false, bool ABLK = false>
; __device__ __forceinline__ void gemm_phase(PG8_LAS unsigned char* lds, const Gemm g, const Sched& S, const Epi& E) {
;     ...
;         for (int t = 0; t < nt; t += 2) {
;     ...
;             PG8_WAIT_V(8); PG8_WAIT_L(0); PG8_BAR; PG8_MMA(0, 0, At, B0); PG8_MMA(0, 1, At, B1); PG8_BAR; PG8_SCHED;
;             PG8_LDA(At, 1, 1); PG8_STAGE(PG8_SB(1, 0), b3, voffB); PG8_STAGE(PG8_SB(1, 1), b3 + hstep, voffB); PG8_STAGE(PG8_SA(1, 0), a3, voffA);
;             PG8_WAIT_V(8); PG8_WAIT_L(0); PG8_BAR; PG8_MMA(1, 0, At, B0); PG8_MMA(1, 1, At, B1); PG8_BAR; PG8_SCHED;
	s_setprio 2
	v_mfma_f32_16x16x32_bf16 v[86:89], v[176:179], v[212:215], v[86:89]
	v_mfma_f32_16x16x32_bf16 v[82:85], v[188:191], v[212:215], v[82:85]
	v_mfma_f32_16x16x32_bf16 v[66:69], v[188:191], v[220:223], v[66:69]
	v_mfma_f32_16x16x32_bf16 v[70:73], v[176:179], v[220:223], v[70:73]
	s_setprio 0
	s_add_i32 s58, s58, s91
	v_lshl_add_u64 v[226:227], v[180:181], 0, s[92:93]
	s_mov_b32 m0, s58
	ds_read_b128 v[192:195], v173 offset:49152
	ds_read_b128 v[196:199], v173 offset:50176
	ds_read_b128 v[200:203], v173 offset:51200
	ds_read_b128 v[204:207], v173 offset:52224
	ds_read_b128 v[208:211], v173 offset:53248
	ds_read_b128 v[212:215], v173 offset:54272
	ds_read_b128 v[216:219], v173 offset:55296
	ds_read_b128 v[220:223], v173 offset:56320
	global_load_lds_dwordx4 v[226:227], off
	v_lshl_add_u64 v[226:227], v[180:181], 0, s[94:95]
	s_add_i32 m0, s58, 0x2000
	s_add_i32 s58, s59, s91
	global_load_lds_dwordx4 v[226:227], off
	v_lshl_add_u64 v[226:227], v[180:181], 0, s[96:97]
	s_mov_b32 m0, s58
	v_lshl_add_u64 v[180:181], v[180:181], 0, s[88:89]
	global_load_lds_dwordx4 v[226:227], off
	s_add_i32 m0, s58, 0x2000
	s_nop 0
	global_load_lds_dwordx4 v[180:181], off
	v_lshl_add_u64 v[180:181], v[224:225], 0, s[92:93]
	s_mov_b32 m0, s10
	s_nop 0
	global_load_lds_dwordx4 v[180:181], off
	v_lshl_add_u64 v[180:181], v[224:225], 0, s[94:95]
	s_mov_b32 m0, s11
	s_nop 0
	global_load_lds_dwordx4 v[180:181], off
	s_waitcnt vmcnt(8)
	s_waitcnt lgkmcnt(0)
	s_barrier
	s_setprio 1
	s_waitcnt lgkmcnt(0)
	v_mfma_f32_16x16x32_bf16 v[62:65], v[130:133], v[192:195], v[62:65]
	v_mfma_f32_16x16x32_bf16 v[58:61], v[156:159], v[192:195], v[58:61]
	v_mfma_f32_16x16x32_bf16 v[42:45], v[156:159], v[200:203], v[42:45]
	v_mfma_f32_16x16x32_bf16 v[46:49], v[130:133], v[200:203], v[46:49]
	v_mfma_f32_16x16x32_bf16 v[30:33], v[130:133], v[208:211], v[30:33]
	v_mfma_f32_16x16x32_bf16 v[26:29], v[156:159], v[208:211], v[26:29]
	v_mfma_f32_16x16x32_bf16 v[10:13], v[156:159], v[216:219], v[10:13]
	v_mfma_f32_16x16x32_bf16 v[14:17], v[130:133], v[216:219], v[14:17]
	v_mfma_f32_16x16x32_bf16 v[62:65], v[134:137], v[196:199], v[62:65]
	v_mfma_f32_16x16x32_bf16 v[58:61], v[160:163], v[196:199], v[58:61]
	v_mfma_f32_16x16x32_bf16 v[42:45], v[160:163], v[204:207], v[42:45]
	v_mfma_f32_16x16x32_bf16 v[46:49], v[134:137], v[204:207], v[46:49]
	v_mfma_f32_16x16x32_bf16 v[30:33], v[134:137], v[212:215], v[30:33]
	v_mfma_f32_16x16x32_bf16 v[26:29], v[160:163], v[212:215], v[26:29]
	v_mfma_f32_16x16x32_bf16 v[10:13], v[160:163], v[220:223], v[10:13]
	v_mfma_f32_16x16x32_bf16 v[14:17], v[134:137], v[220:223], v[14:17]
	v_mfma_f32_16x16x32_bf16 v[54:57], v[164:167], v[192:195], v[54:57]
	v_mfma_f32_16x16x32_bf16 v[50:53], v[184:187], v[192:195], v[50:53]
	v_mfma_f32_16x16x32_bf16 v[34:37], v[184:187], v[200:203], v[34:37]
	v_mfma_f32_16x16x32_bf16 v[38:41], v[164:167], v[200:203], v[38:41]
	v_mfma_f32_16x16x32_bf16 v[22:25], v[164:167], v[208:211], v[22:25]
	v_mfma_f32_16x16x32_bf16 v[18:21], v[184:187], v[208:211], v[18:21]
	v_mfma_f32_16x16x32_bf16 v[2:5], v[184:187], v[216:219], v[2:5]
	v_mfma_f32_16x16x32_bf16 v[6:9], v[164:167], v[216:219], v[6:9]
	v_mfma_f32_16x16x32_bf16 v[54:57], v[176:179], v[196:199], v[54:57]
	v_mfma_f32_16x16x32_bf16 v[50:53], v[188:191], v[196:199], v[50:53]
	v_mfma_f32_16x16x32_bf16 v[34:37], v[188:191], v[204:207], v[34:37]
	v_mfma_f32_16x16x32_bf16 v[38:41], v[176:179], v[204:207], v[38:41]
	s_barrier
	s_setprio 2
	v_mfma_f32_16x16x32_bf16 v[22:25], v[176:179], v[212:215], v[22:25]
	v_mfma_f32_16x16x32_bf16 v[18:21], v[188:191], v[212:215], v[18:21]
	v_mfma_f32_16x16x32_bf16 v[2:5], v[188:191], v[220:223], v[2:5]
	v_mfma_f32_16x16x32_bf16 v[6:9], v[176:179], v[220:223], v[6:9]
	s_setprio 0
	s_cmp_gt_u32 s57, 29
	s_mov_b32 s57, s28
	s_cbranch_scc1 .LBB0_631

; #define PG8_STAGE(bufoff, gbase, voff) do { if constexpr (!pg8_noload<Epi>::value) { _Pragma("unroll") for (int _i = 0; _i < 2; ++_i) \
;         __builtin_amdgcn_global_load_lds((const unsigned*)((const char*)(gbase) + (size_t)_i * pstep + (voff)[0]), (PG8_LAS unsigned*)(lds + (bufoff) + ldsw + _i * 8192), 16, 0, 0); } } while (0)
; #define PG8_LDA(dst, b, h) do { _Pragma("unroll") for (int m = 0; m < 4; ++m) _Pragma("unroll") for (int k = 0; k < 2; ++k) dst[m][k] = *(const PG8_LAS bf16x8*)(lds + PG8_SA(b, h) + aoff + m * 2048 + k * 1024); } while (0)
; #define PG8_LDB(dst, b, h) do { _Pragma("unroll") for (int n = 0; n < 2; ++n) _Pragma("unroll") for (int k = 0; k < 2; ++k) dst[n][k] = *(const PG8_LAS bf16x8*)(lds + PG8_SB(b, h) + boff + n * 2048 + k * 1024); } while (0)
; #define PG8_MMA(ai, bj, At, Bt) do { __builtin_amdgcn_s_setprio(1); _Pragma("unroll") for (int m = 0; m < 4; ++m) _Pragma("unroll") for (int n = 0; n < 2; ++n) _Pragma("unroll") for (int k = 0; k < 2; ++k) \
;         acc[ai][bj][m][n] = __builtin_amdgcn_mfma_f32_16x16x32_bf16(Bt[n][k], At[m][k], acc[ai][bj][m][n], 0, 0, 0); __builtin_amdgcn_s_setprio(0); } while (0)
; #define PG8_WAIT_V(n) asm volatile("s_waitcnt vmcnt(" #n ")" ::: "memory")
; #define PG8_WAIT_L(n) asm volatile("s_waitcnt lgkmcnt(" #n ")" ::: "memory")
; #define PG8_BAR __builtin_amdgcn_s_barrier()
; template <class Epi, class Sched, bool ALIGN_EPI = false, bool SP2 = false, bool ABLK = false>
; __device__ __forceinline__ void gemm_phase(PG8_LAS unsigned char* lds, const Gemm g, const Sched& S, const Epi& E) {
;     ...
;             const bool last = (t == nt - 2);
;             const char* a1 = cA + (size_t)(t + 1) * kstep;
;             const char* a2 = last ? nA : cA + (size_t)(t + 2) * kstep; const char* b2 = last ? nB : cB + (size_t)(t + 2) * kstepB;
;             const char* a3 = a2 + kstep; const char* b3 = b2 + kstepB;
;             if (last && has_next) S.a_ready(nxt);
;             if constexpr (SP2) {
;             PG8_LDB(B0, 0, 0); PG8_LDB(B1, 0, 1); PG8_SCHED; PG8_LDA(At, 0, 0); PG8_STAGE(PG8_SA(1, 1), a1 + hstep, voffA);
;             PG8_WAIT_V(8); PG8_WAIT_L(0); PG8_BAR; PG8_MMA(0, 0, At, B0); PG8_MMA(0, 1, At, B1); PG8_BAR; PG8_SCHED;
;             PG8_LDA(At, 0, 1); PG8_STAGE(PG8_SB(0, 0), b2, voffB); PG8_STAGE(PG8_SB(0, 1), b2 + hstep, voffB); PG8_STAGE(PG8_SA(0, 0), a2, voffA);
.LBB0_1533:
	ds_read_b128 v[114:117], v167
	ds_read_b128 v[126:129], v167 offset:1024
	ds_read_b128 v[130:133], v167 offset:2048
	ds_read_b128 v[142:145], v167 offset:3072
	ds_read_b128 v[146:149], v168
	ds_read_b128 v[150:153], v168 offset:1024
	ds_read_b128 v[174:177], v168 offset:2048
	ds_read_b128 v[178:181], v168 offset:3072
	s_add_i32 s41, s39, 2
	s_add_u32 s70, s68, 0xfff00800
	s_addc_u32 s71, s69, -1
	s_cmp_eq_u32 s3, s39
	s_cselect_b32 s71, s43, s71
	s_cselect_b32 s70, s42, s70
	s_cselect_b32 s81, s65, s37
	s_cselect_b32 s80, s64, s11
	v_lshl_add_u64 v[162:163], s[68:69], 0, v[158:159]
	s_add_i32 m0, s56, 0xc000
	ds_read_b128 v[184:187], v169
	ds_read_b128 v[188:191], v169 offset:1024
	ds_read_b128 v[192:195], v169 offset:2048
	ds_read_b128 v[196:199], v169 offset:3072
	ds_read_b128 v[200:203], v169 offset:4096
	ds_read_b128 v[204:207], v169 offset:5120
	ds_read_b128 v[208:211], v169 offset:6144
	ds_read_b128 v[212:215], v169 offset:7168
	global_load_lds_dwordx4 v[162:163], off
	v_lshl_add_u64 v[162:163], v[162:163], 0, s[12:13]
	s_add_i32 m0, s56, 0xe000
	s_nop 0
	global_load_lds_dwordx4 v[162:163], off
	s_waitcnt vmcnt(8)
	s_waitcnt lgkmcnt(0)
	s_barrier
	s_setprio 1
	s_waitcnt lgkmcnt(0)
	v_mfma_f32_16x16x32_bf16 v[138:141], v[114:117], v[184:187], v[138:141]
	v_mfma_f32_16x16x32_bf16 v[134:137], v[130:133], v[184:187], v[134:137]
	v_mfma_f32_16x16x32_bf16 v[106:109], v[130:133], v[192:195], v[106:109]
	v_mfma_f32_16x16x32_bf16 v[110:113], v[114:117], v[192:195], v[110:113]
	v_mfma_f32_16x16x32_bf16 v[94:97], v[114:117], v[200:203], v[94:97]
	v_mfma_f32_16x16x32_bf16 v[90:93], v[130:133], v[200:203], v[90:93]
	v_mfma_f32_16x16x32_bf16 v[74:77], v[130:133], v[208:211], v[74:77]
	v_mfma_f32_16x16x32_bf16 v[78:81], v[114:117], v[208:211], v[78:81]
	v_mfma_f32_16x16x32_bf16 v[138:141], v[126:129], v[188:191], v[138:141]
	v_mfma_f32_16x16x32_bf16 v[134:137], v[142:145], v[188:191], v[134:137]
	v_mfma_f32_16x16x32_bf16 v[106:109], v[142:145], v[196:199], v[106:109]
	v_mfma_f32_16x16x32_bf16 v[110:113], v[126:129], v[196:199], v[110:113]
	v_mfma_f32_16x16x32_bf16 v[94:97], v[126:129], v[204:207], v[94:97]
	v_mfma_f32_16x16x32_bf16 v[90:93], v[142:145], v[204:207], v[90:93]
	v_mfma_f32_16x16x32_bf16 v[74:77], v[142:145], v[212:215], v[74:77]
	v_mfma_f32_16x16x32_bf16 v[78:81], v[126:129], v[212:215], v[78:81]
	v_mfma_f32_16x16x32_bf16 v[122:125], v[146:149], v[184:187], v[122:125]
	v_mfma_f32_16x16x32_bf16 v[118:121], v[174:177], v[184:187], v[118:121]
	v_mfma_f32_16x16x32_bf16 v[98:101], v[174:177], v[192:195], v[98:101]
	v_mfma_f32_16x16x32_bf16 v[102:105], v[146:149], v[192:195], v[102:105]
	v_mfma_f32_16x16x32_bf16 v[86:89], v[146:149], v[200:203], v[86:89]
	v_mfma_f32_16x16x32_bf16 v[82:85], v[174:177], v[200:203], v[82:85]
	v_mfma_f32_16x16x32_bf16 v[66:69], v[174:177], v[208:211], v[66:69]
	v_mfma_f32_16x16x32_bf16 v[70:73], v[146:149], v[208:211], v[70:73]
	v_mfma_f32_16x16x32_bf16 v[122:125], v[150:153], v[188:191], v[122:125]
	v_mfma_f32_16x16x32_bf16 v[118:121], v[178:181], v[188:191], v[118:121]
	v_mfma_f32_16x16x32_bf16 v[98:101], v[178:181], v[196:199], v[98:101]
	v_mfma_f32_16x16x32_bf16 v[102:105], v[150:153], v[196:199], v[102:105]
	s_barrier
	s_setprio 2
	v_mfma_f32_16x16x32_bf16 v[86:89], v[150:153], v[204:207], v[86:89]
	v_mfma_f32_16x16x32_bf16 v[82:85], v[178:181], v[204:207], v[82:85]
	v_mfma_f32_16x16x32_bf16 v[66:69], v[178:181], v[212:215], v[66:69]
	v_mfma_f32_16x16x32_bf16 v[70:73], v[150:153], v[212:215], v[70:73]
	s_setprio 0
	s_add_i32 s39, s74, s55
	v_lshl_add_u64 v[162:163], s[80:81], 0, v[154:155]
	s_mov_b32 m0, s39
	ds_read_b128 v[184:187], v169 offset:16384
	ds_read_b128 v[188:191], v169 offset:17408
	ds_read_b128 v[192:195], v169 offset:18432
	ds_read_b128 v[196:199], v169 offset:19456
	ds_read_b128 v[200:203], v169 offset:20480
	ds_read_b128 v[204:207], v169 offset:21504
	ds_read_b128 v[208:211], v169 offset:22528
	ds_read_b128 v[212:215], v169 offset:23552
	global_load_lds_dwordx4 v[162:163], off
	v_lshl_add_u64 v[216:217], v[162:163], 0, s[12:13]
	s_add_i32 m0, s39, 0x2000
	s_add_i32 s39, s75, s55
	global_load_lds_dwordx4 v[216:217], off
	v_lshl_add_u64 v[216:217], v[162:163], 0, s[14:15]
	s_mov_b32 m0, s39
	s_nop 0
	global_load_lds_dwordx4 v[216:217], off
	v_lshl_add_u64 v[216:217], v[162:163], 0, s[16:17]
	s_add_i32 m0, s39, 0x2000
	s_nop 0
	global_load_lds_dwordx4 v[216:217], off
	v_lshl_add_u64 v[216:217], s[70:71], 0, v[154:155]
	s_mov_b32 m0, s56
	v_lshl_add_u64 v[218:219], v[216:217], 0, s[12:13]
	global_load_lds_dwordx4 v[216:217], off
	s_mov_b32 m0, s57
	s_nop 0
	global_load_lds_dwordx4 v[218:219], off
	s_waitcnt vmcnt(8)
	s_waitcnt lgkmcnt(0)
	s_barrier
; #define PG8_STAGE(bufoff, gbase, voff) do { if constexpr (!pg8_noload<Epi>::value) { _Pragma("unroll") for (int _i = 0; _i < 2; ++_i) \
;         __builtin_amdgcn_global_load_lds((const unsigned*)((const char*)(gbase) + (size_t)_i * pstep + (voff)[0]), (PG8_LAS unsigned*)(lds + (bufoff) + ldsw + _i * 8192), 16, 0, 0); } } while (0)
; #define PG8_LDA(dst, b, h) do { _Pragma("unroll") for (int m = 0; m < 4; ++m) _Pragma("unroll") for (int k = 0; k < 2; ++k) dst[m][k] = *(const PG8_LAS bf16x8*)(lds + PG8_SA(b, h) + aoff + m * 2048 + k * 1024); } while (0)
; #define PG8_LDB(dst, b, h) do { _Pragma("unroll") for (int n = 0; n < 2; ++n) _Pragma("unroll") for (int k = 0; k < 2; ++k) dst[n][k] = *(const PG8_LAS bf16x8*)(lds + PG8_SB(b, h) + boff + n * 2048 + k * 1024); } while (0)
; #define PG8_MMA(ai, bj, At, Bt) do { __builtin_amdgcn_s_setprio(1); _Pragma("unroll") for (int m = 0; m < 4; ++m) _Pragma("unroll") for (int n = 0; n < 2; ++n) _Pragma("unroll") for (int k = 0; k < 2; ++k) \
;         acc[ai][bj][m][n] = __builtin_amdgcn_mfma_f32_16x16x32_bf16(Bt[n][k], At[m][k], acc[ai][bj][m][n], 0, 0, 0); __builtin_amdgcn_s_setprio(0); } while (0)
; #define PG8_WAIT_V(n) asm volatile("s_waitcnt vmcnt(" #n ")" ::: "memory")
; #define PG8_WAIT_L(n) asm volatile("s_waitcnt lgkmcnt(" #n ")" ::: "memory")
; #define PG8_BAR __builtin_amdgcn_s_barrier()
; #define PG8_SCHED __builtin_amdgcn_sched_barrier(0)
; template <class Epi, class Sched, bool ALIGN_EPI = false, bool SP2 = false, bool ABLK = false>
; __device__ __forceinline__ void gemm_phase(PG8_LAS unsigned char* lds, const Gemm g, const Sched& S, const Epi& E) {
;     ...
;             PG8_WAIT_V(8); PG8_WAIT_L(0); PG8_BAR; PG8_MMA(1, 0, At, B0); PG8_MMA(1, 1, At, B1); PG8_BAR; PG8_SCHED;
;             PG8_LDB(B0, 1, 0); PG8_LDB(B1, 1, 1); PG8_SCHED; PG8_LDA(At, 1, 0); PG8_STAGE(PG8_SA(0, 1), a2 + hstep, voffA);
;             PG8_WAIT_V(8); PG8_WAIT_L(0); PG8_BAR; PG8_MMA(0, 0, At, B0); PG8_MMA(0, 1, At, B1); PG8_BAR; PG8_SCHED;
	s_setprio 1
	s_waitcnt lgkmcnt(0)
	v_mfma_f32_16x16x32_bf16 v[62:65], v[114:117], v[184:187], v[62:65]
	v_mfma_f32_16x16x32_bf16 v[58:61], v[130:133], v[184:187], v[58:61]
	v_mfma_f32_16x16x32_bf16 v[42:45], v[130:133], v[192:195], v[42:45]
	v_mfma_f32_16x16x32_bf16 v[46:49], v[114:117], v[192:195], v[46:49]
	v_mfma_f32_16x16x32_bf16 v[30:33], v[114:117], v[200:203], v[30:33]
	v_mfma_f32_16x16x32_bf16 v[26:29], v[130:133], v[200:203], v[26:29]
	v_mfma_f32_16x16x32_bf16 v[10:13], v[130:133], v[208:211], v[10:13]
	v_mfma_f32_16x16x32_bf16 v[14:17], v[114:117], v[208:211], v[14:17]
	v_mfma_f32_16x16x32_bf16 v[62:65], v[126:129], v[188:191], v[62:65]
	v_mfma_f32_16x16x32_bf16 v[58:61], v[142:145], v[188:191], v[58:61]
	v_mfma_f32_16x16x32_bf16 v[42:45], v[142:145], v[196:199], v[42:45]
	v_mfma_f32_16x16x32_bf16 v[46:49], v[126:129], v[196:199], v[46:49]
	v_mfma_f32_16x16x32_bf16 v[30:33], v[126:129], v[204:207], v[30:33]
	v_mfma_f32_16x16x32_bf16 v[26:29], v[142:145], v[204:207], v[26:29]
	v_mfma_f32_16x16x32_bf16 v[10:13], v[142:145], v[212:215], v[10:13]
	v_mfma_f32_16x16x32_bf16 v[14:17], v[126:129], v[212:215], v[14:17]
	v_mfma_f32_16x16x32_bf16 v[54:57], v[146:149], v[184:187], v[54:57]
	v_mfma_f32_16x16x32_bf16 v[50:53], v[174:177], v[184:187], v[50:53]
	v_mfma_f32_16x16x32_bf16 v[34:37], v[174:177], v[192:195], v[34:37]
	v_mfma_f32_16x16x32_bf16 v[38:41], v[146:149], v[192:195], v[38:41]
	v_mfma_f32_16x16x32_bf16 v[22:25], v[146:149], v[200:203], v[22:25]
	v_mfma_f32_16x16x32_bf16 v[18:21], v[174:177], v[200:203], v[18:21]
	v_mfma_f32_16x16x32_bf16 v[2:5], v[174:177], v[208:211], v[2:5]
	v_mfma_f32_16x16x32_bf16 v[6:9], v[146:149], v[208:211], v[6:9]
	v_mfma_f32_16x16x32_bf16 v[54:57], v[150:153], v[188:191], v[54:57]
	v_mfma_f32_16x16x32_bf16 v[50:53], v[178:181], v[188:191], v[50:53]
	v_mfma_f32_16x16x32_bf16 v[34:37], v[178:181], v[196:199], v[34:37]
	v_mfma_f32_16x16x32_bf16 v[38:41], v[150:153], v[196:199], v[38:41]
	s_barrier
	s_setprio 2
	v_mfma_f32_16x16x32_bf16 v[22:25], v[150:153], v[204:207], v[22:25]
	v_mfma_f32_16x16x32_bf16 v[18:21], v[178:181], v[204:207], v[18:21]
	v_mfma_f32_16x16x32_bf16 v[2:5], v[178:181], v[212:215], v[2:5]
	v_mfma_f32_16x16x32_bf16 v[6:9], v[150:153], v[212:215], v[6:9]
	s_setprio 0
	s_add_i32 s39, 0, 0x18000
	s_add_i32 s70, 0, 0x1c000
	v_add_u32_e32 v142, s39, v1
	v_add_u32_e32 v173, s70, v1
	ds_read_b128 v[114:117], v142
	ds_read_b128 v[126:129], v142 offset:1024
	ds_read_b128 v[130:133], v142 offset:2048
	ds_read_b128 v[142:145], v142 offset:3072
	ds_read_b128 v[146:149], v173
	ds_read_b128 v[150:153], v173 offset:1024
	ds_read_b128 v[174:177], v173 offset:2048
	ds_read_b128 v[178:181], v173 offset:3072
	s_mov_b32 m0, s58
	v_lshl_add_u64 v[218:219], v[216:217], 0, s[14:15]
	ds_read_b128 v[184:187], v169 offset:32768
	ds_read_b128 v[188:191], v169 offset:33792
	ds_read_b128 v[192:195], v169 offset:34816
	ds_read_b128 v[196:199], v169 offset:35840
	ds_read_b128 v[200:203], v169 offset:36864
	ds_read_b128 v[204:207], v169 offset:37888
	ds_read_b128 v[208:211], v169 offset:38912
	ds_read_b128 v[212:215], v169 offset:39936
	global_load_lds_dwordx4 v[218:219], off
	v_lshl_add_u64 v[218:219], v[216:217], 0, s[16:17]
	s_mov_b32 m0, s59
	s_nop 0
	global_load_lds_dwordx4 v[218:219], off
	s_waitcnt vmcnt(8)
	s_waitcnt lgkmcnt(0)
	s_barrier
	s_setprio 1
	s_waitcnt lgkmcnt(0)
	v_mfma_f32_16x16x32_bf16 v[138:141], v[114:117], v[184:187], v[138:141]
	v_mfma_f32_16x16x32_bf16 v[134:137], v[130:133], v[184:187], v[134:137]
	v_mfma_f32_16x16x32_bf16 v[106:109], v[130:133], v[192:195], v[106:109]
	v_mfma_f32_16x16x32_bf16 v[110:113], v[114:117], v[192:195], v[110:113]
	v_mfma_f32_16x16x32_bf16 v[94:97], v[114:117], v[200:203], v[94:97]
	v_mfma_f32_16x16x32_bf16 v[90:93], v[130:133], v[200:203], v[90:93]
	v_mfma_f32_16x16x32_bf16 v[74:77], v[130:133], v[208:211], v[74:77]
	v_mfma_f32_16x16x32_bf16 v[78:81], v[114:117], v[208:211], v[78:81]
	v_mfma_f32_16x16x32_bf16 v[138:141], v[126:129], v[188:191], v[138:141]
	v_mfma_f32_16x16x32_bf16 v[134:137], v[142:145], v[188:191], v[134:137]
	v_mfma_f32_16x16x32_bf16 v[106:109], v[142:145], v[196:199], v[106:109]
	v_mfma_f32_16x16x32_bf16 v[110:113], v[126:129], v[196:199], v[110:113]
	v_mfma_f32_16x16x32_bf16 v[94:97], v[126:129], v[204:207], v[94:97]
	v_mfma_f32_16x16x32_bf16 v[90:93], v[142:145], v[204:207], v[90:93]
	v_mfma_f32_16x16x32_bf16 v[74:77], v[142:145], v[212:215], v[74:77]
	v_mfma_f32_16x16x32_bf16 v[78:81], v[126:129], v[212:215], v[78:81]
	v_mfma_f32_16x16x32_bf16 v[122:125], v[146:149], v[184:187], v[122:125]
	v_mfma_f32_16x16x32_bf16 v[118:121], v[174:177], v[184:187], v[118:121]
	v_mfma_f32_16x16x32_bf16 v[98:101], v[174:177], v[192:195], v[98:101]
	v_mfma_f32_16x16x32_bf16 v[102:105], v[146:149], v[192:195], v[102:105]
	v_mfma_f32_16x16x32_bf16 v[86:89], v[146:149], v[200:203], v[86:89]
	v_mfma_f32_16x16x32_bf16 v[82:85], v[174:177], v[200:203], v[82:85]
	v_mfma_f32_16x16x32_bf16 v[66:69], v[174:177], v[208:211], v[66:69]
	v_mfma_f32_16x16x32_bf16 v[70:73], v[146:149], v[208:211], v[70:73]
	v_mfma_f32_16x16x32_bf16 v[122:125], v[150:153], v[188:191], v[122:125]
	v_mfma_f32_16x16x32_bf16 v[118:121], v[178:181], v[188:191], v[118:121]
	v_mfma_f32_16x16x32_bf16 v[98:101], v[178:181], v[196:199], v[98:101]
	v_mfma_f32_16x16x32_bf16 v[102:105], v[150:153], v[196:199], v[102:105]
	s_barrier
; #define PG8_STAGE(bufoff, gbase, voff) do { if constexpr (!pg8_noload<Epi>::value) { _Pragma("unroll") for (int _i = 0; _i < 2; ++_i) \
;         __builtin_amdgcn_global_load_lds((const unsigned*)((const char*)(gbase) + (size_t)_i * pstep + (voff)[0]), (PG8_LAS unsigned*)(lds + (bufoff) + ldsw + _i * 8192), 16, 0, 0); } } while (0)
; #define PG8_LDA(dst, b, h) do { _Pragma("unroll") for (int m = 0; m < 4; ++m) _Pragma("unroll") for (int k = 0; k < 2; ++k) dst[m][k] = *(const PG8_LAS bf16x8*)(lds + PG8_SA(b, h) + aoff + m * 2048 + k * 1024); } while (0)
; #define PG8_MMA(ai, bj, At, Bt) do { __builtin_amdgcn_s_setprio(1); _Pragma("unroll") for (int m = 0; m < 4; ++m) _Pragma("unroll") for (int n = 0; n < 2; ++n) _Pragma("unroll") for (int k = 0; k < 2; ++k) \
;         acc[ai][bj][m][n] = __builtin_amdgcn_mfma_f32_16x16x32_bf16(Bt[n][k], At[m][k], acc[ai][bj][m][n], 0, 0, 0); __builtin_amdgcn_s_setprio(0); } while (0)
; #define PG8_WAIT_V(n) asm volatile("s_waitcnt vmcnt(" #n ")" ::: "memory")
; #define PG8_WAIT_L(n) asm volatile("s_waitcnt lgkmcnt(" #n ")" ::: "memory")
; #define PG8_BAR __builtin_amdgcn_s_barrier()
; #define PG8_SCHED __builtin_amdgcn_sched_barrier(0)
;     __device__ __forceinline__ void operator()(const f32x4 (&acc)[2][2][4][2], const Unit& u, int wr, int wc, int fr, int fq) const {
;         const int c0 = u.pn * BM + wc * 32 + 8 * fq;
;         if (u.pm * BM < seq) {
;             bf16_t* xbb = XB + ((size_t)(u.pm * 16 + wr * 4) * 64 + u.pn * 8 + 2 * wc) * 512 + fr * 32 + (((fq * 16) ^ ((fr >> 3) << 5)) >> 1);
; template <class Epi, class Sched, bool ALIGN_EPI = false, bool SP2 = false, bool ABLK = false>
; __device__ __forceinline__ void gemm_phase(PG8_LAS unsigned char* lds, const Gemm g, const Sched& S, const Epi& E) {
;     ...
;         for (int t = 0; t < nt; t += 2) {
;     ...
;             PG8_WAIT_V(8); PG8_WAIT_L(0); PG8_BAR; PG8_MMA(0, 0, At, B0); PG8_MMA(0, 1, At, B1); PG8_BAR; PG8_SCHED;
;             PG8_LDA(At, 1, 1); PG8_STAGE(PG8_SB(1, 0), b3, voffB); PG8_STAGE(PG8_SB(1, 1), b3 + hstep, voffB); PG8_STAGE(PG8_SA(1, 0), a3, voffA);
;             PG8_WAIT_V(8); PG8_WAIT_L(0); PG8_BAR; PG8_MMA(1, 0, At, B0); PG8_MMA(1, 1, At, B1); PG8_BAR; PG8_SCHED;
	s_setprio 2
	v_mfma_f32_16x16x32_bf16 v[86:89], v[150:153], v[204:207], v[86:89]
	v_mfma_f32_16x16x32_bf16 v[82:85], v[178:181], v[204:207], v[82:85]
	v_mfma_f32_16x16x32_bf16 v[66:69], v[178:181], v[212:215], v[66:69]
	v_mfma_f32_16x16x32_bf16 v[70:73], v[150:153], v[212:215], v[70:73]
	s_setprio 0
	s_add_i32 s39, s39, s55
	v_lshl_add_u64 v[218:219], v[162:163], 0, s[24:25]
	s_mov_b32 m0, s39
	ds_read_b128 v[184:187], v169 offset:49152
	ds_read_b128 v[188:191], v169 offset:50176
	ds_read_b128 v[192:195], v169 offset:51200
	ds_read_b128 v[196:199], v169 offset:52224
	ds_read_b128 v[200:203], v169 offset:53248
	ds_read_b128 v[204:207], v169 offset:54272
	ds_read_b128 v[208:211], v169 offset:55296
	ds_read_b128 v[212:215], v169 offset:56320
	global_load_lds_dwordx4 v[218:219], off
	v_lshl_add_u64 v[218:219], v[162:163], 0, s[26:27]
	s_add_i32 m0, s39, 0x2000
	s_add_i32 s39, s70, s55
	global_load_lds_dwordx4 v[218:219], off
	v_lshl_add_u64 v[218:219], v[162:163], 0, s[28:29]
	s_mov_b32 m0, s39
	v_lshl_add_u64 v[162:163], v[162:163], 0, s[30:31]
	global_load_lds_dwordx4 v[218:219], off
	s_add_i32 m0, s39, 0x2000
	s_nop 0
	global_load_lds_dwordx4 v[162:163], off
	v_lshl_add_u64 v[162:163], v[216:217], 0, s[24:25]
	s_mov_b32 m0, s62
	s_nop 0
	global_load_lds_dwordx4 v[162:163], off
	v_lshl_add_u64 v[162:163], v[216:217], 0, s[26:27]
	s_mov_b32 m0, s63
	s_nop 0
	global_load_lds_dwordx4 v[162:163], off
	s_waitcnt vmcnt(8)
	s_waitcnt lgkmcnt(0)
	s_barrier
	s_setprio 1
	s_waitcnt lgkmcnt(0)
	v_mfma_f32_16x16x32_bf16 v[62:65], v[114:117], v[184:187], v[62:65]
	v_mfma_f32_16x16x32_bf16 v[58:61], v[130:133], v[184:187], v[58:61]
	v_mfma_f32_16x16x32_bf16 v[42:45], v[130:133], v[192:195], v[42:45]
	v_mfma_f32_16x16x32_bf16 v[46:49], v[114:117], v[192:195], v[46:49]
	v_mfma_f32_16x16x32_bf16 v[30:33], v[114:117], v[200:203], v[30:33]
	v_mfma_f32_16x16x32_bf16 v[26:29], v[130:133], v[200:203], v[26:29]
	v_mfma_f32_16x16x32_bf16 v[10:13], v[130:133], v[208:211], v[10:13]
	v_mfma_f32_16x16x32_bf16 v[14:17], v[114:117], v[208:211], v[14:17]
	v_mfma_f32_16x16x32_bf16 v[62:65], v[126:129], v[188:191], v[62:65]
	v_mfma_f32_16x16x32_bf16 v[58:61], v[142:145], v[188:191], v[58:61]
	v_mfma_f32_16x16x32_bf16 v[42:45], v[142:145], v[196:199], v[42:45]
	v_mfma_f32_16x16x32_bf16 v[46:49], v[126:129], v[196:199], v[46:49]
	v_mfma_f32_16x16x32_bf16 v[30:33], v[126:129], v[204:207], v[30:33]
	v_mfma_f32_16x16x32_bf16 v[26:29], v[142:145], v[204:207], v[26:29]
	v_mfma_f32_16x16x32_bf16 v[10:13], v[142:145], v[212:215], v[10:13]
	v_mfma_f32_16x16x32_bf16 v[14:17], v[126:129], v[212:215], v[14:17]
	v_mfma_f32_16x16x32_bf16 v[54:57], v[146:149], v[184:187], v[54:57]
	v_mfma_f32_16x16x32_bf16 v[50:53], v[174:177], v[184:187], v[50:53]
	v_mfma_f32_16x16x32_bf16 v[34:37], v[174:177], v[192:195], v[34:37]
	v_mfma_f32_16x16x32_bf16 v[38:41], v[146:149], v[192:195], v[38:41]
	v_mfma_f32_16x16x32_bf16 v[22:25], v[146:149], v[200:203], v[22:25]
	v_mfma_f32_16x16x32_bf16 v[18:21], v[174:177], v[200:203], v[18:21]
	v_mfma_f32_16x16x32_bf16 v[2:5], v[174:177], v[208:211], v[2:5]
	v_mfma_f32_16x16x32_bf16 v[6:9], v[146:149], v[208:211], v[6:9]
	v_mfma_f32_16x16x32_bf16 v[54:57], v[150:153], v[188:191], v[54:57]
	v_mfma_f32_16x16x32_bf16 v[50:53], v[178:181], v[188:191], v[50:53]
	v_mfma_f32_16x16x32_bf16 v[34:37], v[178:181], v[196:199], v[34:37]
	v_mfma_f32_16x16x32_bf16 v[38:41], v[150:153], v[196:199], v[38:41]
	s_barrier
	s_setprio 2
	v_mfma_f32_16x16x32_bf16 v[22:25], v[150:153], v[204:207], v[22:25]
	v_mfma_f32_16x16x32_bf16 v[18:21], v[178:181], v[204:207], v[18:21]
	v_mfma_f32_16x16x32_bf16 v[2:5], v[178:181], v[212:215], v[2:5]
	v_mfma_f32_16x16x32_bf16 v[6:9], v[150:153], v[212:215], v[6:9]
	s_setprio 0
	s_add_u32 s68, s68, 0x1000
	s_addc_u32 s69, s69, 0
	s_add_u32 s11, s11, 0x1000
	s_addc_u32 s37, s37, 0
	s_cmp_ge_i32 s41, s79
	s_mov_b32 s39, s41
	s_cbranch_scc0 .LBB0_1533
	s_and_b64 vcc, exec, s[34:35]
	s_cbranch_vccnz .LBB0_1538
	s_lshl_b32 s11, s2, 8
	s_cmp_gt_i32 s2, 63
	s_mov_b64 s[68:69], -1
	s_cbranch_scc1 .LBB0_1539

; #define PG8_STAGE(bufoff, gbase, voff) do { if constexpr (!pg8_noload<Epi>::value) { _Pragma("unroll") for (int _i = 0; _i < 2; ++_i) \
;         __builtin_amdgcn_global_load_lds((const unsigned*)((const char*)(gbase) + (size_t)_i * pstep + (voff)[0]), (PG8_LAS unsigned*)(lds + (bufoff) + ldsw + _i * 8192), 16, 0, 0); } } while (0)
; #define PG8_LDA(dst, b, h) do { _Pragma("unroll") for (int m = 0; m < 4; ++m) _Pragma("unroll") for (int k = 0; k < 2; ++k) dst[m][k] = *(const PG8_LAS bf16x8*)(lds + PG8_SA(b, h) + aoff + m * 2048 + k * 1024); } while (0)
; #define PG8_LDB(dst, b, h) do { _Pragma("unroll") for (int n = 0; n < 2; ++n) _Pragma("unroll") for (int k = 0; k < 2; ++k) dst[n][k] = *(const PG8_LAS bf16x8*)(lds + PG8_SB(b, h) + boff + n * 2048 + k * 1024); } while (0)
; #define PG8_MMA(ai, bj, At, Bt) do { __builtin_amdgcn_s_setprio(1); _Pragma("unroll") for (int m = 0; m < 4; ++m) _Pragma("unroll") for (int n = 0; n < 2; ++n) _Pragma("unroll") for (int k = 0; k < 2; ++k) \
;         acc[ai][bj][m][n] = __builtin_amdgcn_mfma_f32_16x16x32_bf16(Bt[n][k], At[m][k], acc[ai][bj][m][n], 0, 0, 0); __builtin_amdgcn_s_setprio(0); } while (0)
; #define PG8_WAIT_V(n) asm volatile("s_waitcnt vmcnt(" #n ")" ::: "memory")
; #define PG8_WAIT_L(n) asm volatile("s_waitcnt lgkmcnt(" #n ")" ::: "memory")
; #define PG8_BAR __builtin_amdgcn_s_barrier()
; template <class Epi, class Sched, bool ALIGN_EPI = false, bool SP2 = false, bool ABLK = false>
; __device__ __forceinline__ void gemm_phase(PG8_LAS unsigned char* lds, const Gemm g, const Sched& S, const Epi& E) {
;     ...
;             const bool last = (t == nt - 2);
;             const char* a1 = cA + (size_t)(t + 1) * kstep;
;             const char* a2 = last ? nA : cA + (size_t)(t + 2) * kstep; const char* b2 = last ? nB : cB + (size_t)(t + 2) * kstepB;
;             const char* a3 = a2 + kstep; const char* b3 = b2 + kstepB;
;             if (last && has_next) S.a_ready(nxt);
;             if constexpr (SP2) {
;             PG8_LDB(B0, 0, 0); PG8_LDB(B1, 0, 1); PG8_SCHED; PG8_LDA(At, 0, 0); PG8_STAGE(PG8_SA(1, 1), a1 + hstep, voffA);
;             PG8_WAIT_V(8); PG8_WAIT_L(0); PG8_BAR; PG8_MMA(0, 0, At, B0); PG8_MMA(0, 1, At, B1); PG8_BAR; PG8_SCHED;
;             PG8_LDA(At, 0, 1); PG8_STAGE(PG8_SB(0, 0), b2, voffB); PG8_STAGE(PG8_SB(0, 1), b2 + hstep, voffB); PG8_STAGE(PG8_SA(0, 0), a2, voffA);
.LBB0_1657:
	s_or_b32 s26, s94, 1
	s_lshl_b64 s[82:83], s[26:27], 11
	s_add_u32 s88, s74, s82
	v_add_u32_e32 v140, s12, v173
	s_addc_u32 s89, s75, s83
	s_add_i32 s26, s94, 2
	ds_read_b128 v[130:133], v140
	ds_read_b128 v[134:137], v140 offset:1024
	ds_read_b128 v[154:157], v140 offset:2048
	ds_read_b128 v[158:161], v140 offset:3072
	v_add_u32_e32 v140, s13, v173
	s_lshl_b64 s[90:91], s[26:27], 11
	ds_read_b128 v[162:165], v140
	ds_read_b128 v[166:169], v140 offset:1024
	ds_read_b128 v[184:187], v140 offset:2048
	ds_read_b128 v[188:191], v140 offset:3072
	s_add_u32 s92, s74, s90
	s_addc_u32 s93, s75, s91
	s_and_b64 s[82:83], s[80:81], exec
	s_cselect_b32 s83, s93, s3
	s_cselect_b32 s82, s92, s25
	s_add_u32 s90, s76, s90
	s_addc_u32 s91, s77, s91
	s_and_b64 s[80:81], s[80:81], exec
	s_cselect_b32 s81, s91, s65
	s_cselect_b32 s80, s90, s67
	v_lshl_add_u64 v[170:171], s[88:89], 0, v[138:139]
	v_lshl_add_u64 v[224:225], v[170:171], 0, s[20:21]
	s_add_i32 m0, s56, 0xc000
	ds_read_b128 v[192:195], v178
	ds_read_b128 v[196:199], v178 offset:1024
	ds_read_b128 v[200:203], v178 offset:2048
	ds_read_b128 v[204:207], v178 offset:3072
	ds_read_b128 v[208:211], v178 offset:4096
	ds_read_b128 v[212:215], v178 offset:5120
	ds_read_b128 v[216:219], v178 offset:6144
	ds_read_b128 v[220:223], v178 offset:7168
	global_load_lds_dwordx4 v[224:225], off
	v_lshl_add_u64 v[170:171], v[170:171], 0, s[22:23]
	s_add_i32 m0, s56, 0xe000
	s_nop 0
	global_load_lds_dwordx4 v[170:171], off
	s_waitcnt vmcnt(8)
	s_waitcnt lgkmcnt(0)
	s_barrier
	s_setprio 1
	s_waitcnt lgkmcnt(0)
	v_mfma_f32_16x16x32_bf16 v[126:129], v[130:133], v[192:195], v[126:129]
	v_mfma_f32_16x16x32_bf16 v[122:125], v[154:157], v[192:195], v[122:125]
	v_mfma_f32_16x16x32_bf16 v[106:109], v[154:157], v[200:203], v[106:109]
	v_mfma_f32_16x16x32_bf16 v[110:113], v[130:133], v[200:203], v[110:113]
	v_mfma_f32_16x16x32_bf16 v[94:97], v[130:133], v[208:211], v[94:97]
	v_mfma_f32_16x16x32_bf16 v[90:93], v[154:157], v[208:211], v[90:93]
	v_mfma_f32_16x16x32_bf16 v[74:77], v[154:157], v[216:219], v[74:77]
	v_mfma_f32_16x16x32_bf16 v[78:81], v[130:133], v[216:219], v[78:81]
	v_mfma_f32_16x16x32_bf16 v[126:129], v[134:137], v[196:199], v[126:129]
	v_mfma_f32_16x16x32_bf16 v[122:125], v[158:161], v[196:199], v[122:125]
	v_mfma_f32_16x16x32_bf16 v[106:109], v[158:161], v[204:207], v[106:109]
	v_mfma_f32_16x16x32_bf16 v[110:113], v[134:137], v[204:207], v[110:113]
	v_mfma_f32_16x16x32_bf16 v[94:97], v[134:137], v[212:215], v[94:97]
	v_mfma_f32_16x16x32_bf16 v[90:93], v[158:161], v[212:215], v[90:93]
	v_mfma_f32_16x16x32_bf16 v[74:77], v[158:161], v[220:223], v[74:77]
	v_mfma_f32_16x16x32_bf16 v[78:81], v[134:137], v[220:223], v[78:81]
	v_mfma_f32_16x16x32_bf16 v[118:121], v[162:165], v[192:195], v[118:121]
	v_mfma_f32_16x16x32_bf16 v[114:117], v[184:187], v[192:195], v[114:117]
	v_mfma_f32_16x16x32_bf16 v[98:101], v[184:187], v[200:203], v[98:101]
	v_mfma_f32_16x16x32_bf16 v[102:105], v[162:165], v[200:203], v[102:105]
	v_mfma_f32_16x16x32_bf16 v[86:89], v[162:165], v[208:211], v[86:89]
	v_mfma_f32_16x16x32_bf16 v[82:85], v[184:187], v[208:211], v[82:85]
	v_mfma_f32_16x16x32_bf16 v[66:69], v[184:187], v[216:219], v[66:69]
	v_mfma_f32_16x16x32_bf16 v[70:73], v[162:165], v[216:219], v[70:73]
	v_mfma_f32_16x16x32_bf16 v[118:121], v[166:169], v[196:199], v[118:121]
	v_mfma_f32_16x16x32_bf16 v[114:117], v[188:191], v[196:199], v[114:117]
	v_mfma_f32_16x16x32_bf16 v[98:101], v[188:191], v[204:207], v[98:101]
	v_mfma_f32_16x16x32_bf16 v[102:105], v[166:169], v[204:207], v[102:105]
	s_barrier
	s_setprio 2
	v_mfma_f32_16x16x32_bf16 v[86:89], v[166:169], v[212:215], v[86:89]
	v_mfma_f32_16x16x32_bf16 v[82:85], v[188:191], v[212:215], v[82:85]
	v_mfma_f32_16x16x32_bf16 v[66:69], v[188:191], v[220:223], v[66:69]
	v_mfma_f32_16x16x32_bf16 v[70:73], v[166:169], v[220:223], v[70:73]
	s_setprio 0
	v_lshl_add_u64 v[170:171], s[80:81], 0, v[138:139]
	s_add_i32 s80, s12, s55
	s_mov_b32 m0, s80
	ds_read_b128 v[192:195], v178 offset:16384
	ds_read_b128 v[196:199], v178 offset:17408
	ds_read_b128 v[200:203], v178 offset:18432
	ds_read_b128 v[204:207], v178 offset:19456
	ds_read_b128 v[208:211], v178 offset:20480
	ds_read_b128 v[212:215], v178 offset:21504
	ds_read_b128 v[216:219], v178 offset:22528
	ds_read_b128 v[220:223], v178 offset:23552
	global_load_lds_dwordx4 v[170:171], off
	v_lshl_add_u64 v[224:225], v[170:171], 0, s[18:19]
	s_add_i32 m0, s80, 0x2000
	s_add_i32 s80, s13, s55
	global_load_lds_dwordx4 v[224:225], off
	v_lshl_add_u64 v[224:225], v[170:171], 0, s[20:21]
	s_mov_b32 m0, s80
	s_nop 0
	global_load_lds_dwordx4 v[224:225], off
	v_lshl_add_u64 v[224:225], v[170:171], 0, s[22:23]
	s_add_i32 m0, s80, 0x2000
	s_nop 0
	global_load_lds_dwordx4 v[224:225], off
	v_lshl_add_u64 v[224:225], s[82:83], 0, v[138:139]
	s_mov_b32 m0, s56
	v_lshl_add_u64 v[226:227], v[224:225], 0, s[18:19]
	global_load_lds_dwordx4 v[224:225], off
	s_mov_b32 m0, s57
	s_nop 0
	global_load_lds_dwordx4 v[226:227], off
	s_waitcnt vmcnt(8)
	s_waitcnt lgkmcnt(0)
	s_barrier
; #define PG8_STAGE(bufoff, gbase, voff) do { if constexpr (!pg8_noload<Epi>::value) { _Pragma("unroll") for (int _i = 0; _i < 2; ++_i) \
;         __builtin_amdgcn_global_load_lds((const unsigned*)((const char*)(gbase) + (size_t)_i * pstep + (voff)[0]), (PG8_LAS unsigned*)(lds + (bufoff) + ldsw + _i * 8192), 16, 0, 0); } } while (0)
; #define PG8_LDA(dst, b, h) do { _Pragma("unroll") for (int m = 0; m < 4; ++m) _Pragma("unroll") for (int k = 0; k < 2; ++k) dst[m][k] = *(const PG8_LAS bf16x8*)(lds + PG8_SA(b, h) + aoff + m * 2048 + k * 1024); } while (0)
; #define PG8_LDB(dst, b, h) do { _Pragma("unroll") for (int n = 0; n < 2; ++n) _Pragma("unroll") for (int k = 0; k < 2; ++k) dst[n][k] = *(const PG8_LAS bf16x8*)(lds + PG8_SB(b, h) + boff + n * 2048 + k * 1024); } while (0)
; #define PG8_MMA(ai, bj, At, Bt) do { __builtin_amdgcn_s_setprio(1); _Pragma("unroll") for (int m = 0; m < 4; ++m) _Pragma("unroll") for (int n = 0; n < 2; ++n) _Pragma("unroll") for (int k = 0; k < 2; ++k) \
;         acc[ai][bj][m][n] = __builtin_amdgcn_mfma_f32_16x16x32_bf16(Bt[n][k], At[m][k], acc[ai][bj][m][n], 0, 0, 0); __builtin_amdgcn_s_setprio(0); } while (0)
; #define PG8_WAIT_V(n) asm volatile("s_waitcnt vmcnt(" #n ")" ::: "memory")
; #define PG8_WAIT_L(n) asm volatile("s_waitcnt lgkmcnt(" #n ")" ::: "memory")
; #define PG8_BAR __builtin_amdgcn_s_barrier()
; #define PG8_SCHED __builtin_amdgcn_sched_barrier(0)
; template <class Epi, class Sched, bool ALIGN_EPI = false, bool SP2 = false, bool ABLK = false>
; __device__ __forceinline__ void gemm_phase(PG8_LAS unsigned char* lds, const Gemm g, const Sched& S, const Epi& E) {
;     ...
;             PG8_WAIT_V(8); PG8_WAIT_L(0); PG8_BAR; PG8_MMA(1, 0, At, B0); PG8_MMA(1, 1, At, B1); PG8_BAR; PG8_SCHED;
;             PG8_LDB(B0, 1, 0); PG8_LDB(B1, 1, 1); PG8_SCHED; PG8_LDA(At, 1, 0); PG8_STAGE(PG8_SA(0, 1), a2 + hstep, voffA);
;             PG8_WAIT_V(8); PG8_WAIT_L(0); PG8_BAR; PG8_MMA(0, 0, At, B0); PG8_MMA(0, 1, At, B1); PG8_BAR; PG8_SCHED;
	s_setprio 1
	s_waitcnt lgkmcnt(0)
	v_mfma_f32_16x16x32_bf16 v[62:65], v[130:133], v[192:195], v[62:65]
	v_mfma_f32_16x16x32_bf16 v[58:61], v[154:157], v[192:195], v[58:61]
	v_mfma_f32_16x16x32_bf16 v[42:45], v[154:157], v[200:203], v[42:45]
	v_mfma_f32_16x16x32_bf16 v[46:49], v[130:133], v[200:203], v[46:49]
	v_mfma_f32_16x16x32_bf16 v[30:33], v[130:133], v[208:211], v[30:33]
	v_mfma_f32_16x16x32_bf16 v[26:29], v[154:157], v[208:211], v[26:29]
	v_mfma_f32_16x16x32_bf16 v[10:13], v[154:157], v[216:219], v[10:13]
	v_mfma_f32_16x16x32_bf16 v[14:17], v[130:133], v[216:219], v[14:17]
	v_mfma_f32_16x16x32_bf16 v[62:65], v[134:137], v[196:199], v[62:65]
	v_mfma_f32_16x16x32_bf16 v[58:61], v[158:161], v[196:199], v[58:61]
	v_mfma_f32_16x16x32_bf16 v[42:45], v[158:161], v[204:207], v[42:45]
	v_mfma_f32_16x16x32_bf16 v[46:49], v[134:137], v[204:207], v[46:49]
	v_mfma_f32_16x16x32_bf16 v[30:33], v[134:137], v[212:215], v[30:33]
	v_mfma_f32_16x16x32_bf16 v[26:29], v[158:161], v[212:215], v[26:29]
	v_mfma_f32_16x16x32_bf16 v[10:13], v[158:161], v[220:223], v[10:13]
	v_mfma_f32_16x16x32_bf16 v[14:17], v[134:137], v[220:223], v[14:17]
	v_mfma_f32_16x16x32_bf16 v[54:57], v[162:165], v[192:195], v[54:57]
	v_mfma_f32_16x16x32_bf16 v[50:53], v[184:187], v[192:195], v[50:53]
	v_mfma_f32_16x16x32_bf16 v[34:37], v[184:187], v[200:203], v[34:37]
	v_mfma_f32_16x16x32_bf16 v[38:41], v[162:165], v[200:203], v[38:41]
	v_mfma_f32_16x16x32_bf16 v[22:25], v[162:165], v[208:211], v[22:25]
	v_mfma_f32_16x16x32_bf16 v[18:21], v[184:187], v[208:211], v[18:21]
	v_mfma_f32_16x16x32_bf16 v[2:5], v[184:187], v[216:219], v[2:5]
	v_mfma_f32_16x16x32_bf16 v[6:9], v[162:165], v[216:219], v[6:9]
	v_mfma_f32_16x16x32_bf16 v[54:57], v[166:169], v[196:199], v[54:57]
	v_mfma_f32_16x16x32_bf16 v[50:53], v[188:191], v[196:199], v[50:53]
	v_mfma_f32_16x16x32_bf16 v[34:37], v[188:191], v[204:207], v[34:37]
	v_mfma_f32_16x16x32_bf16 v[38:41], v[166:169], v[204:207], v[38:41]
	s_barrier
	s_setprio 2
	v_mfma_f32_16x16x32_bf16 v[22:25], v[166:169], v[212:215], v[22:25]
	v_mfma_f32_16x16x32_bf16 v[18:21], v[188:191], v[212:215], v[18:21]
	v_mfma_f32_16x16x32_bf16 v[2:5], v[188:191], v[220:223], v[2:5]
	v_mfma_f32_16x16x32_bf16 v[6:9], v[166:169], v[220:223], v[6:9]
	s_setprio 0
	s_add_i32 s80, 0, 0x18000
	v_add_u32_e32 v140, s80, v173
	s_add_i32 s81, 0, 0x1c000
	ds_read_b128 v[130:133], v140
	ds_read_b128 v[134:137], v140 offset:1024
	ds_read_b128 v[154:157], v140 offset:2048
	ds_read_b128 v[158:161], v140 offset:3072
	v_add_u32_e32 v140, s81, v173
	ds_read_b128 v[162:165], v140
	ds_read_b128 v[166:169], v140 offset:1024
	ds_read_b128 v[184:187], v140 offset:2048
	ds_read_b128 v[188:191], v140 offset:3072
	s_mov_b32 m0, s58
	v_lshl_add_u64 v[226:227], v[224:225], 0, s[20:21]
	ds_read_b128 v[192:195], v178 offset:32768
	ds_read_b128 v[196:199], v178 offset:33792
	ds_read_b128 v[200:203], v178 offset:34816
	ds_read_b128 v[204:207], v178 offset:35840
	ds_read_b128 v[208:211], v178 offset:36864
	ds_read_b128 v[212:215], v178 offset:37888
	ds_read_b128 v[216:219], v178 offset:38912
	ds_read_b128 v[220:223], v178 offset:39936
	global_load_lds_dwordx4 v[226:227], off
	v_lshl_add_u64 v[226:227], v[224:225], 0, s[22:23]
	s_mov_b32 m0, s59
	s_nop 0
	global_load_lds_dwordx4 v[226:227], off
	s_waitcnt vmcnt(8)
	s_waitcnt lgkmcnt(0)
	s_barrier
	s_setprio 1
	s_waitcnt lgkmcnt(0)
	v_mfma_f32_16x16x32_bf16 v[126:129], v[130:133], v[192:195], v[126:129]
	v_mfma_f32_16x16x32_bf16 v[122:125], v[154:157], v[192:195], v[122:125]
	v_mfma_f32_16x16x32_bf16 v[106:109], v[154:157], v[200:203], v[106:109]
	v_mfma_f32_16x16x32_bf16 v[110:113], v[130:133], v[200:203], v[110:113]
	v_mfma_f32_16x16x32_bf16 v[94:97], v[130:133], v[208:211], v[94:97]
	v_mfma_f32_16x16x32_bf16 v[90:93], v[154:157], v[208:211], v[90:93]
	v_mfma_f32_16x16x32_bf16 v[74:77], v[154:157], v[216:219], v[74:77]
	v_mfma_f32_16x16x32_bf16 v[78:81], v[130:133], v[216:219], v[78:81]
	v_mfma_f32_16x16x32_bf16 v[126:129], v[134:137], v[196:199], v[126:129]
	v_mfma_f32_16x16x32_bf16 v[122:125], v[158:161], v[196:199], v[122:125]
	v_mfma_f32_16x16x32_bf16 v[106:109], v[158:161], v[204:207], v[106:109]
	v_mfma_f32_16x16x32_bf16 v[110:113], v[134:137], v[204:207], v[110:113]
	v_mfma_f32_16x16x32_bf16 v[94:97], v[134:137], v[212:215], v[94:97]
	v_mfma_f32_16x16x32_bf16 v[90:93], v[158:161], v[212:215], v[90:93]
	v_mfma_f32_16x16x32_bf16 v[74:77], v[158:161], v[220:223], v[74:77]
	v_mfma_f32_16x16x32_bf16 v[78:81], v[134:137], v[220:223], v[78:81]
	v_mfma_f32_16x16x32_bf16 v[118:121], v[162:165], v[192:195], v[118:121]
	v_mfma_f32_16x16x32_bf16 v[114:117], v[184:187], v[192:195], v[114:117]
	v_mfma_f32_16x16x32_bf16 v[98:101], v[184:187], v[200:203], v[98:101]
	v_mfma_f32_16x16x32_bf16 v[102:105], v[162:165], v[200:203], v[102:105]
	v_mfma_f32_16x16x32_bf16 v[86:89], v[162:165], v[208:211], v[86:89]
	v_mfma_f32_16x16x32_bf16 v[82:85], v[184:187], v[208:211], v[82:85]
	v_mfma_f32_16x16x32_bf16 v[66:69], v[184:187], v[216:219], v[66:69]
	v_mfma_f32_16x16x32_bf16 v[70:73], v[162:165], v[216:219], v[70:73]
	v_mfma_f32_16x16x32_bf16 v[118:121], v[166:169], v[196:199], v[118:121]
	v_mfma_f32_16x16x32_bf16 v[114:117], v[188:191], v[196:199], v[114:117]
	v_mfma_f32_16x16x32_bf16 v[98:101], v[188:191], v[204:207], v[98:101]
	v_mfma_f32_16x16x32_bf16 v[102:105], v[166:169], v[204:207], v[102:105]
	s_barrier
; #define PG8_STAGE(bufoff, gbase, voff) do { if constexpr (!pg8_noload<Epi>::value) { _Pragma("unroll") for (int _i = 0; _i < 2; ++_i) \
;         __builtin_amdgcn_global_load_lds((const unsigned*)((const char*)(gbase) + (size_t)_i * pstep + (voff)[0]), (PG8_LAS unsigned*)(lds + (bufoff) + ldsw + _i * 8192), 16, 0, 0); } } while (0)
; #define PG8_LDA(dst, b, h) do { _Pragma("unroll") for (int m = 0; m < 4; ++m) _Pragma("unroll") for (int k = 0; k < 2; ++k) dst[m][k] = *(const PG8_LAS bf16x8*)(lds + PG8_SA(b, h) + aoff + m * 2048 + k * 1024); } while (0)
; #define PG8_MMA(ai, bj, At, Bt) do { __builtin_amdgcn_s_setprio(1); _Pragma("unroll") for (int m = 0; m < 4; ++m) _Pragma("unroll") for (int n = 0; n < 2; ++n) _Pragma("unroll") for (int k = 0; k < 2; ++k) \
;         acc[ai][bj][m][n] = __builtin_amdgcn_mfma_f32_16x16x32_bf16(Bt[n][k], At[m][k], acc[ai][bj][m][n], 0, 0, 0); __builtin_amdgcn_s_setprio(0); } while (0)
; #define PG8_WAIT_V(n) asm volatile("s_waitcnt vmcnt(" #n ")" ::: "memory")
; #define PG8_WAIT_L(n) asm volatile("s_waitcnt lgkmcnt(" #n ")" ::: "memory")
; #define PG8_BAR __builtin_amdgcn_s_barrier()
; #define PG8_SCHED __builtin_amdgcn_sched_barrier(0)
; template <class Epi, class Sched, bool ALIGN_EPI = false, bool SP2 = false, bool ABLK = false>
; __device__ __forceinline__ void gemm_phase(PG8_LAS unsigned char* lds, const Gemm g, const Sched& S, const Epi& E) {
;     ...
;         for (int t = 0; t < nt; t += 2) {
;     ...
;             PG8_WAIT_V(8); PG8_WAIT_L(0); PG8_BAR; PG8_MMA(0, 0, At, B0); PG8_MMA(0, 1, At, B1); PG8_BAR; PG8_SCHED;
;             PG8_LDA(At, 1, 1); PG8_STAGE(PG8_SB(1, 0), b3, voffB); PG8_STAGE(PG8_SB(1, 1), b3 + hstep, voffB); PG8_STAGE(PG8_SA(1, 0), a3, voffA);
;             PG8_WAIT_V(8); PG8_WAIT_L(0); PG8_BAR; PG8_MMA(1, 0, At, B0); PG8_MMA(1, 1, At, B1); PG8_BAR; PG8_SCHED;
	s_setprio 2
	v_mfma_f32_16x16x32_bf16 v[86:89], v[166:169], v[212:215], v[86:89]
	v_mfma_f32_16x16x32_bf16 v[82:85], v[188:191], v[212:215], v[82:85]
	v_mfma_f32_16x16x32_bf16 v[66:69], v[188:191], v[220:223], v[66:69]
	v_mfma_f32_16x16x32_bf16 v[70:73], v[166:169], v[220:223], v[70:73]
	s_setprio 0
	s_add_i32 s80, s80, s55
	v_lshl_add_u64 v[226:227], v[170:171], 0, s[30:31]
	s_mov_b32 m0, s80
	ds_read_b128 v[192:195], v178 offset:49152
	ds_read_b128 v[196:199], v178 offset:50176
	ds_read_b128 v[200:203], v178 offset:51200
	ds_read_b128 v[204:207], v178 offset:52224
	ds_read_b128 v[208:211], v178 offset:53248
	ds_read_b128 v[212:215], v178 offset:54272
	ds_read_b128 v[216:219], v178 offset:55296
	ds_read_b128 v[220:223], v178 offset:56320
	global_load_lds_dwordx4 v[226:227], off
	v_lshl_add_u64 v[226:227], v[170:171], 0, s[34:35]
	s_add_i32 m0, s80, 0x2000
	s_add_i32 s80, s81, s55
	global_load_lds_dwordx4 v[226:227], off
	v_lshl_add_u64 v[226:227], v[170:171], 0, s[36:37]
	s_mov_b32 m0, s80
	v_lshl_add_u64 v[170:171], v[170:171], 0, s[38:39]
	global_load_lds_dwordx4 v[226:227], off
	s_add_i32 m0, s80, 0x2000
	s_nop 0
	global_load_lds_dwordx4 v[170:171], off
	v_lshl_add_u64 v[170:171], v[224:225], 0, s[30:31]
	s_mov_b32 m0, s63
	s_nop 0
	global_load_lds_dwordx4 v[170:171], off
	v_lshl_add_u64 v[170:171], v[224:225], 0, s[34:35]
	s_mov_b32 m0, s73
	s_nop 0
	global_load_lds_dwordx4 v[170:171], off
	s_waitcnt vmcnt(8)
	s_waitcnt lgkmcnt(0)
	s_barrier
	s_setprio 1
	s_waitcnt lgkmcnt(0)
	v_mfma_f32_16x16x32_bf16 v[62:65], v[130:133], v[192:195], v[62:65]
	v_mfma_f32_16x16x32_bf16 v[58:61], v[154:157], v[192:195], v[58:61]
	v_mfma_f32_16x16x32_bf16 v[42:45], v[154:157], v[200:203], v[42:45]
	v_mfma_f32_16x16x32_bf16 v[46:49], v[130:133], v[200:203], v[46:49]
	v_mfma_f32_16x16x32_bf16 v[30:33], v[130:133], v[208:211], v[30:33]
	v_mfma_f32_16x16x32_bf16 v[26:29], v[154:157], v[208:211], v[26:29]
	v_mfma_f32_16x16x32_bf16 v[10:13], v[154:157], v[216:219], v[10:13]
	v_mfma_f32_16x16x32_bf16 v[14:17], v[130:133], v[216:219], v[14:17]
	v_mfma_f32_16x16x32_bf16 v[62:65], v[134:137], v[196:199], v[62:65]
	v_mfma_f32_16x16x32_bf16 v[58:61], v[158:161], v[196:199], v[58:61]
	v_mfma_f32_16x16x32_bf16 v[42:45], v[158:161], v[204:207], v[42:45]
	v_mfma_f32_16x16x32_bf16 v[46:49], v[134:137], v[204:207], v[46:49]
	v_mfma_f32_16x16x32_bf16 v[30:33], v[134:137], v[212:215], v[30:33]
	v_mfma_f32_16x16x32_bf16 v[26:29], v[158:161], v[212:215], v[26:29]
	v_mfma_f32_16x16x32_bf16 v[10:13], v[158:161], v[220:223], v[10:13]
	v_mfma_f32_16x16x32_bf16 v[14:17], v[134:137], v[220:223], v[14:17]
	v_mfma_f32_16x16x32_bf16 v[54:57], v[162:165], v[192:195], v[54:57]
	v_mfma_f32_16x16x32_bf16 v[50:53], v[184:187], v[192:195], v[50:53]
	v_mfma_f32_16x16x32_bf16 v[34:37], v[184:187], v[200:203], v[34:37]
	v_mfma_f32_16x16x32_bf16 v[38:41], v[162:165], v[200:203], v[38:41]
	v_mfma_f32_16x16x32_bf16 v[22:25], v[162:165], v[208:211], v[22:25]
	v_mfma_f32_16x16x32_bf16 v[18:21], v[184:187], v[208:211], v[18:21]
	v_mfma_f32_16x16x32_bf16 v[2:5], v[184:187], v[216:219], v[2:5]
	v_mfma_f32_16x16x32_bf16 v[6:9], v[162:165], v[216:219], v[6:9]
	v_mfma_f32_16x16x32_bf16 v[54:57], v[166:169], v[196:199], v[54:57]
	v_mfma_f32_16x16x32_bf16 v[50:53], v[188:191], v[196:199], v[50:53]
	v_mfma_f32_16x16x32_bf16 v[34:37], v[188:191], v[204:207], v[34:37]
	v_mfma_f32_16x16x32_bf16 v[38:41], v[166:169], v[204:207], v[38:41]
	s_barrier
	s_setprio 2
	v_mfma_f32_16x16x32_bf16 v[22:25], v[166:169], v[212:215], v[22:25]
	v_mfma_f32_16x16x32_bf16 v[18:21], v[188:191], v[212:215], v[18:21]
	v_mfma_f32_16x16x32_bf16 v[2:5], v[188:191], v[220:223], v[2:5]
	v_mfma_f32_16x16x32_bf16 v[6:9], v[166:169], v[220:223], v[6:9]
	s_setprio 0
	s_cmp_gt_u32 s94, 29
	s_mov_b32 s94, s26
	s_cbranch_scc1 .LBB0_1669

; #define PG8_STAGE(bufoff, gbase, voff) do { if constexpr (!pg8_noload<Epi>::value) { _Pragma("unroll") for (int _i = 0; _i < 2; ++_i) \
;         __builtin_amdgcn_global_load_lds((const unsigned*)((const char*)(gbase) + (size_t)_i * pstep + (voff)[0]), (PG8_LAS unsigned*)(lds + (bufoff) + ldsw + _i * 8192), 16, 0, 0); } } while (0)
; #define PG8_LDA(dst, b, h) do { _Pragma("unroll") for (int m = 0; m < 4; ++m) _Pragma("unroll") for (int k = 0; k < 2; ++k) dst[m][k] = *(const PG8_LAS bf16x8*)(lds + PG8_SA(b, h) + aoff + m * 2048 + k * 1024); } while (0)
; #define PG8_LDB(dst, b, h) do { _Pragma("unroll") for (int n = 0; n < 2; ++n) _Pragma("unroll") for (int k = 0; k < 2; ++k) dst[n][k] = *(const PG8_LAS bf16x8*)(lds + PG8_SB(b, h) + boff + n * 2048 + k * 1024); } while (0)
; #define PG8_MMA(ai, bj, At, Bt) do { __builtin_amdgcn_s_setprio(1); _Pragma("unroll") for (int m = 0; m < 4; ++m) _Pragma("unroll") for (int n = 0; n < 2; ++n) _Pragma("unroll") for (int k = 0; k < 2; ++k) \
;         acc[ai][bj][m][n] = __builtin_amdgcn_mfma_f32_16x16x32_bf16(Bt[n][k], At[m][k], acc[ai][bj][m][n], 0, 0, 0); __builtin_amdgcn_s_setprio(0); } while (0)
; #define PG8_WAIT_V(n) asm volatile("s_waitcnt vmcnt(" #n ")" ::: "memory")
; #define PG8_WAIT_L(n) asm volatile("s_waitcnt lgkmcnt(" #n ")" ::: "memory")
; #define PG8_BAR __builtin_amdgcn_s_barrier()
; template <class Epi, class Sched, bool ALIGN_EPI = false, bool SP2 = false, bool ABLK = false>
; __device__ __forceinline__ void gemm_phase(PG8_LAS unsigned char* lds, const Gemm g, const Sched& S, const Epi& E) {
;     ...
;             const bool last = (t == nt - 2);
;             const char* a1 = cA + (size_t)(t + 1) * kstep;
;             const char* a2 = last ? nA : cA + (size_t)(t + 2) * kstep; const char* b2 = last ? nB : cB + (size_t)(t + 2) * kstepB;
;             const char* a3 = a2 + kstep; const char* b3 = b2 + kstepB;
;             if (last && has_next) S.a_ready(nxt);
;             if constexpr (SP2) {
;             PG8_LDB(B0, 0, 0); PG8_LDB(B1, 0, 1); PG8_SCHED; PG8_LDA(At, 0, 0); PG8_STAGE(PG8_SA(1, 1), a1 + hstep, voffA);
;             PG8_WAIT_V(8); PG8_WAIT_L(0); PG8_BAR; PG8_MMA(0, 0, At, B0); PG8_MMA(0, 1, At, B1); PG8_BAR; PG8_SCHED;
;             PG8_LDA(At, 0, 1); PG8_STAGE(PG8_SB(0, 0), b2, voffB); PG8_STAGE(PG8_SB(0, 1), b2 + hstep, voffB); PG8_STAGE(PG8_SA(0, 0), a2, voffA);
.LBB0_1997:
	ds_read_b128 v[130:133], v175
	ds_read_b128 v[134:137], v175 offset:1024
	ds_read_b128 v[138:141], v175 offset:2048
	ds_read_b128 v[142:145], v175 offset:3072
	ds_read_b128 v[146:149], v176
	ds_read_b128 v[150:153], v176 offset:1024
	ds_read_b128 v[154:157], v176 offset:2048
	ds_read_b128 v[158:161], v176 offset:3072
	s_add_i32 s43, s41, 2
	s_add_u32 s62, s52, 0xfff80800
	s_addc_u32 s63, s53, -1
	s_cmp_eq_u32 s3, s41
	s_cselect_b32 s63, s45, s63
	s_cselect_b32 s62, s44, s62
	s_cselect_b32 s77, s47, s39
	s_cselect_b32 s76, s46, s11
	v_lshl_add_u64 v[170:171], s[52:53], 0, v[166:167]
	s_add_i32 m0, s49, 0xc000
	ds_read_b128 v[184:187], v177
	ds_read_b128 v[188:191], v177 offset:1024
	ds_read_b128 v[192:195], v177 offset:2048
	ds_read_b128 v[196:199], v177 offset:3072
	ds_read_b128 v[200:203], v177 offset:4096
	ds_read_b128 v[204:207], v177 offset:5120
	ds_read_b128 v[208:211], v177 offset:6144
	ds_read_b128 v[212:215], v177 offset:7168
	global_load_lds_dwordx4 v[170:171], off
	v_lshl_add_u64 v[170:171], v[170:171], 0, s[12:13]
	s_add_i32 m0, s49, 0xe000
	s_nop 0
	global_load_lds_dwordx4 v[170:171], off
	s_waitcnt vmcnt(8)
	s_waitcnt lgkmcnt(0)
	s_barrier
	s_setprio 1
	s_waitcnt lgkmcnt(0)
	v_mfma_f32_16x16x32_bf16 v[126:129], v[130:133], v[184:187], v[126:129]
	v_mfma_f32_16x16x32_bf16 v[122:125], v[138:141], v[184:187], v[122:125]
	v_mfma_f32_16x16x32_bf16 v[106:109], v[138:141], v[192:195], v[106:109]
	v_mfma_f32_16x16x32_bf16 v[110:113], v[130:133], v[192:195], v[110:113]
	v_mfma_f32_16x16x32_bf16 v[94:97], v[130:133], v[200:203], v[94:97]
	v_mfma_f32_16x16x32_bf16 v[90:93], v[138:141], v[200:203], v[90:93]
	v_mfma_f32_16x16x32_bf16 v[74:77], v[138:141], v[208:211], v[74:77]
	v_mfma_f32_16x16x32_bf16 v[78:81], v[130:133], v[208:211], v[78:81]
	v_mfma_f32_16x16x32_bf16 v[126:129], v[134:137], v[188:191], v[126:129]
	v_mfma_f32_16x16x32_bf16 v[122:125], v[142:145], v[188:191], v[122:125]
	v_mfma_f32_16x16x32_bf16 v[106:109], v[142:145], v[196:199], v[106:109]
	v_mfma_f32_16x16x32_bf16 v[110:113], v[134:137], v[196:199], v[110:113]
	v_mfma_f32_16x16x32_bf16 v[94:97], v[134:137], v[204:207], v[94:97]
	v_mfma_f32_16x16x32_bf16 v[90:93], v[142:145], v[204:207], v[90:93]
	v_mfma_f32_16x16x32_bf16 v[74:77], v[142:145], v[212:215], v[74:77]
	v_mfma_f32_16x16x32_bf16 v[78:81], v[134:137], v[212:215], v[78:81]
	v_mfma_f32_16x16x32_bf16 v[118:121], v[146:149], v[184:187], v[118:121]
	v_mfma_f32_16x16x32_bf16 v[114:117], v[154:157], v[184:187], v[114:117]
	v_mfma_f32_16x16x32_bf16 v[98:101], v[154:157], v[192:195], v[98:101]
	v_mfma_f32_16x16x32_bf16 v[102:105], v[146:149], v[192:195], v[102:105]
	v_mfma_f32_16x16x32_bf16 v[86:89], v[146:149], v[200:203], v[86:89]
	v_mfma_f32_16x16x32_bf16 v[82:85], v[154:157], v[200:203], v[82:85]
	v_mfma_f32_16x16x32_bf16 v[66:69], v[154:157], v[208:211], v[66:69]
	v_mfma_f32_16x16x32_bf16 v[70:73], v[146:149], v[208:211], v[70:73]
	v_mfma_f32_16x16x32_bf16 v[118:121], v[150:153], v[188:191], v[118:121]
	v_mfma_f32_16x16x32_bf16 v[114:117], v[158:161], v[188:191], v[114:117]
	v_mfma_f32_16x16x32_bf16 v[98:101], v[158:161], v[196:199], v[98:101]
	v_mfma_f32_16x16x32_bf16 v[102:105], v[150:153], v[196:199], v[102:105]
	s_barrier
	s_setprio 2
	v_mfma_f32_16x16x32_bf16 v[86:89], v[150:153], v[204:207], v[86:89]
	v_mfma_f32_16x16x32_bf16 v[82:85], v[158:161], v[204:207], v[82:85]
	v_mfma_f32_16x16x32_bf16 v[66:69], v[158:161], v[212:215], v[66:69]
	v_mfma_f32_16x16x32_bf16 v[70:73], v[150:153], v[212:215], v[70:73]
	s_setprio 0
	s_add_i32 s41, s70, s57
	v_lshl_add_u64 v[170:171], s[76:77], 0, v[162:163]
	s_mov_b32 m0, s41
	ds_read_b128 v[184:187], v177 offset:16384
	ds_read_b128 v[188:191], v177 offset:17408
	ds_read_b128 v[192:195], v177 offset:18432
	ds_read_b128 v[196:199], v177 offset:19456
	ds_read_b128 v[200:203], v177 offset:20480
	ds_read_b128 v[204:207], v177 offset:21504
	ds_read_b128 v[208:211], v177 offset:22528
	ds_read_b128 v[212:215], v177 offset:23552
	global_load_lds_dwordx4 v[170:171], off
	v_lshl_add_u64 v[216:217], v[170:171], 0, s[12:13]
	s_add_i32 m0, s41, 0x2000
	s_add_i32 s41, s71, s57
	global_load_lds_dwordx4 v[216:217], off
	v_lshl_add_u64 v[216:217], v[170:171], 0, s[14:15]
	s_mov_b32 m0, s41
	s_nop 0
	global_load_lds_dwordx4 v[216:217], off
	v_lshl_add_u64 v[216:217], v[170:171], 0, s[16:17]
	s_add_i32 m0, s41, 0x2000
	s_nop 0
	global_load_lds_dwordx4 v[216:217], off
	v_lshl_add_u64 v[216:217], s[62:63], 0, v[162:163]
	s_mov_b32 m0, s49
	v_lshl_add_u64 v[218:219], v[216:217], 0, s[12:13]
	global_load_lds_dwordx4 v[216:217], off
	s_mov_b32 m0, s58
	s_nop 0
	global_load_lds_dwordx4 v[218:219], off
	s_waitcnt vmcnt(8)
	s_waitcnt lgkmcnt(0)
	s_barrier
; #define PG8_STAGE(bufoff, gbase, voff) do { if constexpr (!pg8_noload<Epi>::value) { _Pragma("unroll") for (int _i = 0; _i < 2; ++_i) \
;         __builtin_amdgcn_global_load_lds((const unsigned*)((const char*)(gbase) + (size_t)_i * pstep + (voff)[0]), (PG8_LAS unsigned*)(lds + (bufoff) + ldsw + _i * 8192), 16, 0, 0); } } while (0)
; #define PG8_LDA(dst, b, h) do { _Pragma("unroll") for (int m = 0; m < 4; ++m) _Pragma("unroll") for (int k = 0; k < 2; ++k) dst[m][k] = *(const PG8_LAS bf16x8*)(lds + PG8_SA(b, h) + aoff + m * 2048 + k * 1024); } while (0)
; #define PG8_LDB(dst, b, h) do { _Pragma("unroll") for (int n = 0; n < 2; ++n) _Pragma("unroll") for (int k = 0; k < 2; ++k) dst[n][k] = *(const PG8_LAS bf16x8*)(lds + PG8_SB(b, h) + boff + n * 2048 + k * 1024); } while (0)
; #define PG8_MMA(ai, bj, At, Bt) do { __builtin_amdgcn_s_setprio(1); _Pragma("unroll") for (int m = 0; m < 4; ++m) _Pragma("unroll") for (int n = 0; n < 2; ++n) _Pragma("unroll") for (int k = 0; k < 2; ++k) \
;         acc[ai][bj][m][n] = __builtin_amdgcn_mfma_f32_16x16x32_bf16(Bt[n][k], At[m][k], acc[ai][bj][m][n], 0, 0, 0); __builtin_amdgcn_s_setprio(0); } while (0)
; #define PG8_WAIT_V(n) asm volatile("s_waitcnt vmcnt(" #n ")" ::: "memory")
; #define PG8_WAIT_L(n) asm volatile("s_waitcnt lgkmcnt(" #n ")" ::: "memory")
; #define PG8_BAR __builtin_amdgcn_s_barrier()
; #define PG8_SCHED __builtin_amdgcn_sched_barrier(0)
; template <class Epi, class Sched, bool ALIGN_EPI = false, bool SP2 = false, bool ABLK = false>
; __device__ __forceinline__ void gemm_phase(PG8_LAS unsigned char* lds, const Gemm g, const Sched& S, const Epi& E) {
;     ...
;             PG8_WAIT_V(8); PG8_WAIT_L(0); PG8_BAR; PG8_MMA(1, 0, At, B0); PG8_MMA(1, 1, At, B1); PG8_BAR; PG8_SCHED;
;             PG8_LDB(B0, 1, 0); PG8_LDB(B1, 1, 1); PG8_SCHED; PG8_LDA(At, 1, 0); PG8_STAGE(PG8_SA(0, 1), a2 + hstep, voffA);
;             PG8_WAIT_V(8); PG8_WAIT_L(0); PG8_BAR; PG8_MMA(0, 0, At, B0); PG8_MMA(0, 1, At, B1); PG8_BAR; PG8_SCHED;
	s_setprio 1
	s_waitcnt lgkmcnt(0)
	v_mfma_f32_16x16x32_bf16 v[62:65], v[130:133], v[184:187], v[62:65]
	v_mfma_f32_16x16x32_bf16 v[58:61], v[138:141], v[184:187], v[58:61]
	v_mfma_f32_16x16x32_bf16 v[42:45], v[138:141], v[192:195], v[42:45]
	v_mfma_f32_16x16x32_bf16 v[46:49], v[130:133], v[192:195], v[46:49]
	v_mfma_f32_16x16x32_bf16 v[30:33], v[130:133], v[200:203], v[30:33]
	v_mfma_f32_16x16x32_bf16 v[26:29], v[138:141], v[200:203], v[26:29]
	v_mfma_f32_16x16x32_bf16 v[10:13], v[138:141], v[208:211], v[10:13]
	v_mfma_f32_16x16x32_bf16 v[14:17], v[130:133], v[208:211], v[14:17]
	v_mfma_f32_16x16x32_bf16 v[62:65], v[134:137], v[188:191], v[62:65]
	v_mfma_f32_16x16x32_bf16 v[58:61], v[142:145], v[188:191], v[58:61]
	v_mfma_f32_16x16x32_bf16 v[42:45], v[142:145], v[196:199], v[42:45]
	v_mfma_f32_16x16x32_bf16 v[46:49], v[134:137], v[196:199], v[46:49]
	v_mfma_f32_16x16x32_bf16 v[30:33], v[134:137], v[204:207], v[30:33]
	v_mfma_f32_16x16x32_bf16 v[26:29], v[142:145], v[204:207], v[26:29]
	v_mfma_f32_16x16x32_bf16 v[10:13], v[142:145], v[212:215], v[10:13]
	v_mfma_f32_16x16x32_bf16 v[14:17], v[134:137], v[212:215], v[14:17]
	v_mfma_f32_16x16x32_bf16 v[54:57], v[146:149], v[184:187], v[54:57]
	v_mfma_f32_16x16x32_bf16 v[50:53], v[154:157], v[184:187], v[50:53]
	v_mfma_f32_16x16x32_bf16 v[34:37], v[154:157], v[192:195], v[34:37]
	v_mfma_f32_16x16x32_bf16 v[38:41], v[146:149], v[192:195], v[38:41]
	v_mfma_f32_16x16x32_bf16 v[22:25], v[146:149], v[200:203], v[22:25]
	v_mfma_f32_16x16x32_bf16 v[18:21], v[154:157], v[200:203], v[18:21]
	v_mfma_f32_16x16x32_bf16 v[2:5], v[154:157], v[208:211], v[2:5]
	v_mfma_f32_16x16x32_bf16 v[6:9], v[146:149], v[208:211], v[6:9]
	v_mfma_f32_16x16x32_bf16 v[54:57], v[150:153], v[188:191], v[54:57]
	v_mfma_f32_16x16x32_bf16 v[50:53], v[158:161], v[188:191], v[50:53]
	v_mfma_f32_16x16x32_bf16 v[34:37], v[158:161], v[196:199], v[34:37]
	v_mfma_f32_16x16x32_bf16 v[38:41], v[150:153], v[196:199], v[38:41]
	s_barrier
	s_setprio 2
	v_mfma_f32_16x16x32_bf16 v[22:25], v[150:153], v[204:207], v[22:25]
	v_mfma_f32_16x16x32_bf16 v[18:21], v[158:161], v[204:207], v[18:21]
	v_mfma_f32_16x16x32_bf16 v[2:5], v[158:161], v[212:215], v[2:5]
	v_mfma_f32_16x16x32_bf16 v[6:9], v[150:153], v[212:215], v[6:9]
	s_setprio 0
	s_add_i32 s41, 0, 0x18000
	s_add_i32 s62, 0, 0x1c000
	v_add_u32_e32 v142, s41, v1
	v_add_u32_e32 v158, s62, v1
	ds_read_b128 v[130:133], v142
	ds_read_b128 v[134:137], v142 offset:1024
	ds_read_b128 v[138:141], v142 offset:2048
	ds_read_b128 v[142:145], v142 offset:3072
	ds_read_b128 v[146:149], v158
	ds_read_b128 v[150:153], v158 offset:1024
	ds_read_b128 v[154:157], v158 offset:2048
	ds_read_b128 v[158:161], v158 offset:3072
	s_mov_b32 m0, s59
	v_lshl_add_u64 v[218:219], v[216:217], 0, s[14:15]
	ds_read_b128 v[184:187], v177 offset:32768
	ds_read_b128 v[188:191], v177 offset:33792
	ds_read_b128 v[192:195], v177 offset:34816
	ds_read_b128 v[196:199], v177 offset:35840
	ds_read_b128 v[200:203], v177 offset:36864
	ds_read_b128 v[204:207], v177 offset:37888
	ds_read_b128 v[208:211], v177 offset:38912
	ds_read_b128 v[212:215], v177 offset:39936
	global_load_lds_dwordx4 v[218:219], off
	v_lshl_add_u64 v[218:219], v[216:217], 0, s[16:17]
	s_mov_b32 m0, s60
	s_nop 0
	global_load_lds_dwordx4 v[218:219], off
	s_waitcnt vmcnt(8)
	s_waitcnt lgkmcnt(0)
	s_barrier
	s_setprio 1
	s_waitcnt lgkmcnt(0)
	v_mfma_f32_16x16x32_bf16 v[126:129], v[130:133], v[184:187], v[126:129]
	v_mfma_f32_16x16x32_bf16 v[122:125], v[138:141], v[184:187], v[122:125]
	v_mfma_f32_16x16x32_bf16 v[106:109], v[138:141], v[192:195], v[106:109]
	v_mfma_f32_16x16x32_bf16 v[110:113], v[130:133], v[192:195], v[110:113]
	v_mfma_f32_16x16x32_bf16 v[94:97], v[130:133], v[200:203], v[94:97]
	v_mfma_f32_16x16x32_bf16 v[90:93], v[138:141], v[200:203], v[90:93]
	v_mfma_f32_16x16x32_bf16 v[74:77], v[138:141], v[208:211], v[74:77]
	v_mfma_f32_16x16x32_bf16 v[78:81], v[130:133], v[208:211], v[78:81]
	v_mfma_f32_16x16x32_bf16 v[126:129], v[134:137], v[188:191], v[126:129]
	v_mfma_f32_16x16x32_bf16 v[122:125], v[142:145], v[188:191], v[122:125]
	v_mfma_f32_16x16x32_bf16 v[106:109], v[142:145], v[196:199], v[106:109]
	v_mfma_f32_16x16x32_bf16 v[110:113], v[134:137], v[196:199], v[110:113]
	v_mfma_f32_16x16x32_bf16 v[94:97], v[134:137], v[204:207], v[94:97]
	v_mfma_f32_16x16x32_bf16 v[90:93], v[142:145], v[204:207], v[90:93]
	v_mfma_f32_16x16x32_bf16 v[74:77], v[142:145], v[212:215], v[74:77]
	v_mfma_f32_16x16x32_bf16 v[78:81], v[134:137], v[212:215], v[78:81]
	v_mfma_f32_16x16x32_bf16 v[118:121], v[146:149], v[184:187], v[118:121]
	v_mfma_f32_16x16x32_bf16 v[114:117], v[154:157], v[184:187], v[114:117]
	v_mfma_f32_16x16x32_bf16 v[98:101], v[154:157], v[192:195], v[98:101]
	v_mfma_f32_16x16x32_bf16 v[102:105], v[146:149], v[192:195], v[102:105]
	v_mfma_f32_16x16x32_bf16 v[86:89], v[146:149], v[200:203], v[86:89]
	v_mfma_f32_16x16x32_bf16 v[82:85], v[154:157], v[200:203], v[82:85]
	v_mfma_f32_16x16x32_bf16 v[66:69], v[154:157], v[208:211], v[66:69]
	v_mfma_f32_16x16x32_bf16 v[70:73], v[146:149], v[208:211], v[70:73]
	v_mfma_f32_16x16x32_bf16 v[118:121], v[150:153], v[188:191], v[118:121]
	v_mfma_f32_16x16x32_bf16 v[114:117], v[158:161], v[188:191], v[114:117]
	v_mfma_f32_16x16x32_bf16 v[98:101], v[158:161], v[196:199], v[98:101]
	v_mfma_f32_16x16x32_bf16 v[102:105], v[150:153], v[196:199], v[102:105]
	s_barrier
; #define PG8_STAGE(bufoff, gbase, voff) do { if constexpr (!pg8_noload<Epi>::value) { _Pragma("unroll") for (int _i = 0; _i < 2; ++_i) \
;         __builtin_amdgcn_global_load_lds((const unsigned*)((const char*)(gbase) + (size_t)_i * pstep + (voff)[0]), (PG8_LAS unsigned*)(lds + (bufoff) + ldsw + _i * 8192), 16, 0, 0); } } while (0)
; #define PG8_LDA(dst, b, h) do { _Pragma("unroll") for (int m = 0; m < 4; ++m) _Pragma("unroll") for (int k = 0; k < 2; ++k) dst[m][k] = *(const PG8_LAS bf16x8*)(lds + PG8_SA(b, h) + aoff + m * 2048 + k * 1024); } while (0)
; #define PG8_MMA(ai, bj, At, Bt) do { __builtin_amdgcn_s_setprio(1); _Pragma("unroll") for (int m = 0; m < 4; ++m) _Pragma("unroll") for (int n = 0; n < 2; ++n) _Pragma("unroll") for (int k = 0; k < 2; ++k) \
;         acc[ai][bj][m][n] = __builtin_amdgcn_mfma_f32_16x16x32_bf16(Bt[n][k], At[m][k], acc[ai][bj][m][n], 0, 0, 0); __builtin_amdgcn_s_setprio(0); } while (0)
; #define PG8_WAIT_V(n) asm volatile("s_waitcnt vmcnt(" #n ")" ::: "memory")
; #define PG8_WAIT_L(n) asm volatile("s_waitcnt lgkmcnt(" #n ")" ::: "memory")
; #define PG8_BAR __builtin_amdgcn_s_barrier()
; #define PG8_SCHED __builtin_amdgcn_sched_barrier(0)
;     __device__ __forceinline__ void operator()(const f32x4 (&acc)[2][2][4][2], const Unit& u, int wr, int wc, int fr, int fq) const {
;         const int c0 = u.pn * BM + wc * 32 + 8 * fq;
;         if (u.pm * BM < seq) {
;             bf16_t* xbb = XB + ((size_t)(u.pm * 16 + wr * 4) * 64 + u.pn * 8 + 2 * wc) * 512 + fr * 32 + (((fq * 16) ^ ((fr >> 3) << 5)) >> 1);
; template <class Epi, class Sched, bool ALIGN_EPI = false, bool SP2 = false, bool ABLK = false>
; __device__ __forceinline__ void gemm_phase(PG8_LAS unsigned char* lds, const Gemm g, const Sched& S, const Epi& E) {
;     ...
;         for (int t = 0; t < nt; t += 2) {
;     ...
;             PG8_WAIT_V(8); PG8_WAIT_L(0); PG8_BAR; PG8_MMA(0, 0, At, B0); PG8_MMA(0, 1, At, B1); PG8_BAR; PG8_SCHED;
;             PG8_LDA(At, 1, 1); PG8_STAGE(PG8_SB(1, 0), b3, voffB); PG8_STAGE(PG8_SB(1, 1), b3 + hstep, voffB); PG8_STAGE(PG8_SA(1, 0), a3, voffA);
;             PG8_WAIT_V(8); PG8_WAIT_L(0); PG8_BAR; PG8_MMA(1, 0, At, B0); PG8_MMA(1, 1, At, B1); PG8_BAR; PG8_SCHED;
	s_setprio 2
	v_mfma_f32_16x16x32_bf16 v[86:89], v[150:153], v[204:207], v[86:89]
	v_mfma_f32_16x16x32_bf16 v[82:85], v[158:161], v[204:207], v[82:85]
	v_mfma_f32_16x16x32_bf16 v[66:69], v[158:161], v[212:215], v[66:69]
	v_mfma_f32_16x16x32_bf16 v[70:73], v[150:153], v[212:215], v[70:73]
	s_setprio 0
	s_add_i32 s41, s41, s57
	v_lshl_add_u64 v[218:219], v[170:171], 0, s[24:25]
	s_mov_b32 m0, s41
	ds_read_b128 v[184:187], v177 offset:49152
	ds_read_b128 v[188:191], v177 offset:50176
	ds_read_b128 v[192:195], v177 offset:51200
	ds_read_b128 v[196:199], v177 offset:52224
	ds_read_b128 v[200:203], v177 offset:53248
	ds_read_b128 v[204:207], v177 offset:54272
	ds_read_b128 v[208:211], v177 offset:55296
	ds_read_b128 v[212:215], v177 offset:56320
	global_load_lds_dwordx4 v[218:219], off
	v_lshl_add_u64 v[218:219], v[170:171], 0, s[26:27]
	s_add_i32 m0, s41, 0x2000
	s_add_i32 s41, s62, s57
	global_load_lds_dwordx4 v[218:219], off
	v_lshl_add_u64 v[218:219], v[170:171], 0, s[28:29]
	s_mov_b32 m0, s41
	v_lshl_add_u64 v[170:171], v[170:171], 0, s[30:31]
	global_load_lds_dwordx4 v[218:219], off
	s_add_i32 m0, s41, 0x2000
	s_nop 0
	global_load_lds_dwordx4 v[170:171], off
	v_lshl_add_u64 v[170:171], v[216:217], 0, s[24:25]
	s_mov_b32 m0, s65
	s_nop 0
	global_load_lds_dwordx4 v[170:171], off
	v_lshl_add_u64 v[170:171], v[216:217], 0, s[26:27]
	s_mov_b32 m0, s66
	s_nop 0
	global_load_lds_dwordx4 v[170:171], off
	s_waitcnt vmcnt(8)
	s_waitcnt lgkmcnt(0)
	s_barrier
	s_setprio 1
	s_waitcnt lgkmcnt(0)
	v_mfma_f32_16x16x32_bf16 v[62:65], v[130:133], v[184:187], v[62:65]
	v_mfma_f32_16x16x32_bf16 v[58:61], v[138:141], v[184:187], v[58:61]
	v_mfma_f32_16x16x32_bf16 v[42:45], v[138:141], v[192:195], v[42:45]
	v_mfma_f32_16x16x32_bf16 v[46:49], v[130:133], v[192:195], v[46:49]
	v_mfma_f32_16x16x32_bf16 v[30:33], v[130:133], v[200:203], v[30:33]
	v_mfma_f32_16x16x32_bf16 v[26:29], v[138:141], v[200:203], v[26:29]
	v_mfma_f32_16x16x32_bf16 v[10:13], v[138:141], v[208:211], v[10:13]
	v_mfma_f32_16x16x32_bf16 v[14:17], v[130:133], v[208:211], v[14:17]
	v_mfma_f32_16x16x32_bf16 v[62:65], v[134:137], v[188:191], v[62:65]
	v_mfma_f32_16x16x32_bf16 v[58:61], v[142:145], v[188:191], v[58:61]
	v_mfma_f32_16x16x32_bf16 v[42:45], v[142:145], v[196:199], v[42:45]
	v_mfma_f32_16x16x32_bf16 v[46:49], v[134:137], v[196:199], v[46:49]
	v_mfma_f32_16x16x32_bf16 v[30:33], v[134:137], v[204:207], v[30:33]
	v_mfma_f32_16x16x32_bf16 v[26:29], v[142:145], v[204:207], v[26:29]
	v_mfma_f32_16x16x32_bf16 v[10:13], v[142:145], v[212:215], v[10:13]
	v_mfma_f32_16x16x32_bf16 v[14:17], v[134:137], v[212:215], v[14:17]
	v_mfma_f32_16x16x32_bf16 v[54:57], v[146:149], v[184:187], v[54:57]
	v_mfma_f32_16x16x32_bf16 v[50:53], v[154:157], v[184:187], v[50:53]
	v_mfma_f32_16x16x32_bf16 v[34:37], v[154:157], v[192:195], v[34:37]
	v_mfma_f32_16x16x32_bf16 v[38:41], v[146:149], v[192:195], v[38:41]
	v_mfma_f32_16x16x32_bf16 v[22:25], v[146:149], v[200:203], v[22:25]
	v_mfma_f32_16x16x32_bf16 v[18:21], v[154:157], v[200:203], v[18:21]
	v_mfma_f32_16x16x32_bf16 v[2:5], v[154:157], v[208:211], v[2:5]
	v_mfma_f32_16x16x32_bf16 v[6:9], v[146:149], v[208:211], v[6:9]
	v_mfma_f32_16x16x32_bf16 v[54:57], v[150:153], v[188:191], v[54:57]
	v_mfma_f32_16x16x32_bf16 v[50:53], v[158:161], v[188:191], v[50:53]
	v_mfma_f32_16x16x32_bf16 v[34:37], v[158:161], v[196:199], v[34:37]
	v_mfma_f32_16x16x32_bf16 v[38:41], v[150:153], v[196:199], v[38:41]
	s_barrier
	s_setprio 2
	v_mfma_f32_16x16x32_bf16 v[22:25], v[150:153], v[204:207], v[22:25]
	v_mfma_f32_16x16x32_bf16 v[18:21], v[158:161], v[204:207], v[18:21]
	v_mfma_f32_16x16x32_bf16 v[2:5], v[158:161], v[212:215], v[2:5]
	v_mfma_f32_16x16x32_bf16 v[6:9], v[150:153], v[212:215], v[6:9]
	s_setprio 0
	s_add_u32 s52, s52, 0x1000
	s_addc_u32 s53, s53, 0
	s_add_u32 s11, s11, 0x1000
	s_addc_u32 s39, s39, 0
	s_cmp_ge_i32 s43, s75
	s_mov_b32 s41, s43
	s_cbranch_scc0 .LBB0_1997
	s_and_b64 vcc, exec, s[34:35]
	s_cbranch_vccnz .LBB0_2002
	s_lshl_b32 s11, s2, 8
	s_cmp_gt_i32 s2, 63
	s_mov_b64 s[52:53], -1
	s_cbranch_scc1 .LBB0_2003

; #define PG8_STAGE(bufoff, gbase, voff) do { if constexpr (!pg8_noload<Epi>::value) { _Pragma("unroll") for (int _i = 0; _i < 2; ++_i) \
;         __builtin_amdgcn_global_load_lds((const unsigned*)((const char*)(gbase) + (size_t)_i * pstep + (voff)[0]), (PG8_LAS unsigned*)(lds + (bufoff) + ldsw + _i * 8192), 16, 0, 0); } } while (0)
; #define PG8_LDA(dst, b, h) do { _Pragma("unroll") for (int m = 0; m < 4; ++m) _Pragma("unroll") for (int k = 0; k < 2; ++k) dst[m][k] = *(const PG8_LAS bf16x8*)(lds + PG8_SA(b, h) + aoff + m * 2048 + k * 1024); } while (0)
; #define PG8_LDB(dst, b, h) do { _Pragma("unroll") for (int n = 0; n < 2; ++n) _Pragma("unroll") for (int k = 0; k < 2; ++k) dst[n][k] = *(const PG8_LAS bf16x8*)(lds + PG8_SB(b, h) + boff + n * 2048 + k * 1024); } while (0)
; #define PG8_MMA(ai, bj, At, Bt) do { __builtin_amdgcn_s_setprio(1); _Pragma("unroll") for (int m = 0; m < 4; ++m) _Pragma("unroll") for (int n = 0; n < 2; ++n) _Pragma("unroll") for (int k = 0; k < 2; ++k) \
;         acc[ai][bj][m][n] = __builtin_amdgcn_mfma_f32_16x16x32_bf16(Bt[n][k], At[m][k], acc[ai][bj][m][n], 0, 0, 0); __builtin_amdgcn_s_setprio(0); } while (0)
; #define PG8_WAIT_V(n) asm volatile("s_waitcnt vmcnt(" #n ")" ::: "memory")
; #define PG8_WAIT_L(n) asm volatile("s_waitcnt lgkmcnt(" #n ")" ::: "memory")
; #define PG8_BAR __builtin_amdgcn_s_barrier()
; template <class Epi, class Sched, bool ALIGN_EPI = false, bool SP2 = false, bool ABLK = false>
; __device__ __forceinline__ void gemm_phase(PG8_LAS unsigned char* lds, const Gemm g, const Sched& S, const Epi& E) {
;     ...
;             const bool last = (t == nt - 2);
;             const char* a1 = cA + (size_t)(t + 1) * kstep;
;             const char* a2 = last ? nA : cA + (size_t)(t + 2) * kstep; const char* b2 = last ? nB : cB + (size_t)(t + 2) * kstepB;
;             const char* a3 = a2 + kstep; const char* b3 = b2 + kstepB;
;             if (last && has_next) S.a_ready(nxt);
;             if constexpr (SP2) {
;             PG8_LDB(B0, 0, 0); PG8_LDB(B1, 0, 1); PG8_SCHED; PG8_LDA(At, 0, 0); PG8_STAGE(PG8_SA(1, 1), a1 + hstep, voffA);
;             PG8_WAIT_V(8); PG8_WAIT_L(0); PG8_BAR; PG8_MMA(0, 0, At, B0); PG8_MMA(0, 1, At, B1); PG8_BAR; PG8_SCHED;
;             PG8_LDA(At, 0, 1); PG8_STAGE(PG8_SB(0, 0), b2, voffB); PG8_STAGE(PG8_SB(0, 1), b2 + hstep, voffB); PG8_STAGE(PG8_SA(0, 0), a2, voffA);
.LBB0_2119:
	s_or_b32 s30, s59, 1
	s_lshl_b64 s[14:15], s[30:31], 11
	s_add_u32 s14, s82, s14
	v_add_u32_e32 v133, s71, v148
	s_addc_u32 s15, s83, s15
	s_add_i32 s30, s59, 2
	ds_read_b128 v[144:147], v133
	ds_read_b128 v[184:187], v133 offset:1024
	ds_read_b128 v[188:191], v133 offset:2048
	ds_read_b128 v[192:195], v133 offset:3072
	v_add_u32_e32 v133, s73, v148
	s_lshl_b64 s[34:35], s[30:31], 11
	ds_read_b128 v[196:199], v133
	ds_read_b128 v[200:203], v133 offset:1024
	ds_read_b128 v[204:207], v133 offset:2048
	ds_read_b128 v[208:211], v133 offset:3072
	s_add_u32 s96, s82, s34
	s_addc_u32 s97, s83, s35
	s_and_b64 s[94:95], s[92:93], exec
	s_cselect_b32 s95, s97, s77
	s_cselect_b32 s94, s96, s28
	s_add_u32 s96, s88, s34
	s_addc_u32 s97, s89, s35
	s_and_b64 s[34:35], s[92:93], exec
	s_cselect_b32 s35, s97, s29
	s_cselect_b32 s34, s96, s75
	v_lshl_add_u64 v[180:181], s[14:15], 0, v[130:131]
	v_lshl_add_u64 v[244:245], v[180:181], 0, s[24:25]
	s_add_i32 m0, s17, 0xc000
	ds_read_b128 v[212:215], v168
	ds_read_b128 v[216:219], v168 offset:1024
	ds_read_b128 v[220:223], v168 offset:2048
	ds_read_b128 v[224:227], v168 offset:3072
	ds_read_b128 v[228:231], v168 offset:4096
	ds_read_b128 v[232:235], v168 offset:5120
	ds_read_b128 v[236:239], v168 offset:6144
	ds_read_b128 v[240:243], v168 offset:7168
	global_load_lds_dwordx4 v[244:245], off
	v_lshl_add_u64 v[180:181], v[180:181], 0, s[26:27]
	s_add_i32 m0, s17, 0xe000
	s_nop 0
	global_load_lds_dwordx4 v[180:181], off
	s_waitcnt vmcnt(8)
	s_waitcnt lgkmcnt(0)
	s_barrier
	s_setprio 1
	s_waitcnt lgkmcnt(0)
	v_mfma_f32_16x16x32_bf16 v[126:129], v[144:147], v[212:215], v[126:129]
	v_mfma_f32_16x16x32_bf16 v[122:125], v[188:191], v[212:215], v[122:125]
	v_mfma_f32_16x16x32_bf16 v[106:109], v[188:191], v[220:223], v[106:109]
	v_mfma_f32_16x16x32_bf16 v[110:113], v[144:147], v[220:223], v[110:113]
	v_mfma_f32_16x16x32_bf16 v[94:97], v[144:147], v[228:231], v[94:97]
	v_mfma_f32_16x16x32_bf16 v[90:93], v[188:191], v[228:231], v[90:93]
	v_mfma_f32_16x16x32_bf16 v[74:77], v[188:191], v[236:239], v[74:77]
	v_mfma_f32_16x16x32_bf16 v[78:81], v[144:147], v[236:239], v[78:81]
	v_mfma_f32_16x16x32_bf16 v[126:129], v[184:187], v[216:219], v[126:129]
	v_mfma_f32_16x16x32_bf16 v[122:125], v[192:195], v[216:219], v[122:125]
	v_mfma_f32_16x16x32_bf16 v[106:109], v[192:195], v[224:227], v[106:109]
	v_mfma_f32_16x16x32_bf16 v[110:113], v[184:187], v[224:227], v[110:113]
	v_mfma_f32_16x16x32_bf16 v[94:97], v[184:187], v[232:235], v[94:97]
	v_mfma_f32_16x16x32_bf16 v[90:93], v[192:195], v[232:235], v[90:93]
	v_mfma_f32_16x16x32_bf16 v[74:77], v[192:195], v[240:243], v[74:77]
	v_mfma_f32_16x16x32_bf16 v[78:81], v[184:187], v[240:243], v[78:81]
	v_mfma_f32_16x16x32_bf16 v[118:121], v[196:199], v[212:215], v[118:121]
	v_mfma_f32_16x16x32_bf16 v[114:117], v[204:207], v[212:215], v[114:117]
	v_mfma_f32_16x16x32_bf16 v[98:101], v[204:207], v[220:223], v[98:101]
	v_mfma_f32_16x16x32_bf16 v[102:105], v[196:199], v[220:223], v[102:105]
	v_mfma_f32_16x16x32_bf16 v[86:89], v[196:199], v[228:231], v[86:89]
	v_mfma_f32_16x16x32_bf16 v[82:85], v[204:207], v[228:231], v[82:85]
	v_mfma_f32_16x16x32_bf16 v[66:69], v[204:207], v[236:239], v[66:69]
	v_mfma_f32_16x16x32_bf16 v[70:73], v[196:199], v[236:239], v[70:73]
	v_mfma_f32_16x16x32_bf16 v[118:121], v[200:203], v[216:219], v[118:121]
	v_mfma_f32_16x16x32_bf16 v[114:117], v[208:211], v[216:219], v[114:117]
	v_mfma_f32_16x16x32_bf16 v[98:101], v[208:211], v[224:227], v[98:101]
	v_mfma_f32_16x16x32_bf16 v[102:105], v[200:203], v[224:227], v[102:105]
	s_barrier
	s_setprio 2
	v_mfma_f32_16x16x32_bf16 v[86:89], v[200:203], v[232:235], v[86:89]
	v_mfma_f32_16x16x32_bf16 v[82:85], v[208:211], v[232:235], v[82:85]
	v_mfma_f32_16x16x32_bf16 v[66:69], v[208:211], v[240:243], v[66:69]
	v_mfma_f32_16x16x32_bf16 v[70:73], v[200:203], v[240:243], v[70:73]
	s_setprio 0
	s_add_i32 s14, s71, s3
	v_lshl_add_u64 v[180:181], s[34:35], 0, v[130:131]
	s_mov_b32 m0, s14
	ds_read_b128 v[212:215], v168 offset:16384
	ds_read_b128 v[216:219], v168 offset:17408
	ds_read_b128 v[220:223], v168 offset:18432
	ds_read_b128 v[224:227], v168 offset:19456
	ds_read_b128 v[228:231], v168 offset:20480
	ds_read_b128 v[232:235], v168 offset:21504
	ds_read_b128 v[236:239], v168 offset:22528
	ds_read_b128 v[240:243], v168 offset:23552
	global_load_lds_dwordx4 v[180:181], off
	v_lshl_add_u64 v[244:245], v[180:181], 0, s[22:23]
	s_add_i32 m0, s14, 0x2000
	s_add_i32 s14, s73, s3
	global_load_lds_dwordx4 v[244:245], off
	v_lshl_add_u64 v[244:245], v[180:181], 0, s[24:25]
	s_mov_b32 m0, s14
	s_nop 0
	global_load_lds_dwordx4 v[244:245], off
	v_lshl_add_u64 v[244:245], v[180:181], 0, s[26:27]
	s_add_i32 m0, s14, 0x2000
	s_nop 0
	global_load_lds_dwordx4 v[244:245], off
	v_lshl_add_u64 v[244:245], s[94:95], 0, v[130:131]
	s_mov_b32 m0, s17
	v_lshl_add_u64 v[246:247], v[244:245], 0, s[22:23]
	global_load_lds_dwordx4 v[244:245], off
	s_mov_b32 m0, s56
	s_nop 0
	global_load_lds_dwordx4 v[246:247], off
	s_waitcnt vmcnt(8)
	s_waitcnt lgkmcnt(0)
	s_barrier
; #define PG8_STAGE(bufoff, gbase, voff) do { if constexpr (!pg8_noload<Epi>::value) { _Pragma("unroll") for (int _i = 0; _i < 2; ++_i) \
;         __builtin_amdgcn_global_load_lds((const unsigned*)((const char*)(gbase) + (size_t)_i * pstep + (voff)[0]), (PG8_LAS unsigned*)(lds + (bufoff) + ldsw + _i * 8192), 16, 0, 0); } } while (0)
; #define PG8_LDA(dst, b, h) do { _Pragma("unroll") for (int m = 0; m < 4; ++m) _Pragma("unroll") for (int k = 0; k < 2; ++k) dst[m][k] = *(const PG8_LAS bf16x8*)(lds + PG8_SA(b, h) + aoff + m * 2048 + k * 1024); } while (0)
; #define PG8_LDB(dst, b, h) do { _Pragma("unroll") for (int n = 0; n < 2; ++n) _Pragma("unroll") for (int k = 0; k < 2; ++k) dst[n][k] = *(const PG8_LAS bf16x8*)(lds + PG8_SB(b, h) + boff + n * 2048 + k * 1024); } while (0)
; #define PG8_MMA(ai, bj, At, Bt) do { __builtin_amdgcn_s_setprio(1); _Pragma("unroll") for (int m = 0; m < 4; ++m) _Pragma("unroll") for (int n = 0; n < 2; ++n) _Pragma("unroll") for (int k = 0; k < 2; ++k) \
;         acc[ai][bj][m][n] = __builtin_amdgcn_mfma_f32_16x16x32_bf16(Bt[n][k], At[m][k], acc[ai][bj][m][n], 0, 0, 0); __builtin_amdgcn_s_setprio(0); } while (0)
; #define PG8_WAIT_V(n) asm volatile("s_waitcnt vmcnt(" #n ")" ::: "memory")
; #define PG8_WAIT_L(n) asm volatile("s_waitcnt lgkmcnt(" #n ")" ::: "memory")
; #define PG8_BAR __builtin_amdgcn_s_barrier()
; #define PG8_SCHED __builtin_amdgcn_sched_barrier(0)
; template <class Epi, class Sched, bool ALIGN_EPI = false, bool SP2 = false, bool ABLK = false>
; __device__ __forceinline__ void gemm_phase(PG8_LAS unsigned char* lds, const Gemm g, const Sched& S, const Epi& E) {
;     ...
;             PG8_WAIT_V(8); PG8_WAIT_L(0); PG8_BAR; PG8_MMA(1, 0, At, B0); PG8_MMA(1, 1, At, B1); PG8_BAR; PG8_SCHED;
;             PG8_LDB(B0, 1, 0); PG8_LDB(B1, 1, 1); PG8_SCHED; PG8_LDA(At, 1, 0); PG8_STAGE(PG8_SA(0, 1), a2 + hstep, voffA);
;             PG8_WAIT_V(8); PG8_WAIT_L(0); PG8_BAR; PG8_MMA(0, 0, At, B0); PG8_MMA(0, 1, At, B1); PG8_BAR; PG8_SCHED;
	s_setprio 1
	s_waitcnt lgkmcnt(0)
	v_mfma_f32_16x16x32_bf16 v[62:65], v[144:147], v[212:215], v[62:65]
	v_mfma_f32_16x16x32_bf16 v[58:61], v[188:191], v[212:215], v[58:61]
	v_mfma_f32_16x16x32_bf16 v[42:45], v[188:191], v[220:223], v[42:45]
	v_mfma_f32_16x16x32_bf16 v[46:49], v[144:147], v[220:223], v[46:49]
	v_mfma_f32_16x16x32_bf16 v[30:33], v[144:147], v[228:231], v[30:33]
	v_mfma_f32_16x16x32_bf16 v[26:29], v[188:191], v[228:231], v[26:29]
	v_mfma_f32_16x16x32_bf16 v[10:13], v[188:191], v[236:239], v[10:13]
	v_mfma_f32_16x16x32_bf16 v[14:17], v[144:147], v[236:239], v[14:17]
	v_mfma_f32_16x16x32_bf16 v[62:65], v[184:187], v[216:219], v[62:65]
	v_mfma_f32_16x16x32_bf16 v[58:61], v[192:195], v[216:219], v[58:61]
	v_mfma_f32_16x16x32_bf16 v[42:45], v[192:195], v[224:227], v[42:45]
	v_mfma_f32_16x16x32_bf16 v[46:49], v[184:187], v[224:227], v[46:49]
	v_mfma_f32_16x16x32_bf16 v[30:33], v[184:187], v[232:235], v[30:33]
	v_mfma_f32_16x16x32_bf16 v[26:29], v[192:195], v[232:235], v[26:29]
	v_mfma_f32_16x16x32_bf16 v[10:13], v[192:195], v[240:243], v[10:13]
	v_mfma_f32_16x16x32_bf16 v[14:17], v[184:187], v[240:243], v[14:17]
	v_mfma_f32_16x16x32_bf16 v[54:57], v[196:199], v[212:215], v[54:57]
	v_mfma_f32_16x16x32_bf16 v[50:53], v[204:207], v[212:215], v[50:53]
	v_mfma_f32_16x16x32_bf16 v[34:37], v[204:207], v[220:223], v[34:37]
	v_mfma_f32_16x16x32_bf16 v[38:41], v[196:199], v[220:223], v[38:41]
	v_mfma_f32_16x16x32_bf16 v[22:25], v[196:199], v[228:231], v[22:25]
	v_mfma_f32_16x16x32_bf16 v[18:21], v[204:207], v[228:231], v[18:21]
	v_mfma_f32_16x16x32_bf16 v[2:5], v[204:207], v[236:239], v[2:5]
	v_mfma_f32_16x16x32_bf16 v[6:9], v[196:199], v[236:239], v[6:9]
	v_mfma_f32_16x16x32_bf16 v[54:57], v[200:203], v[216:219], v[54:57]
	v_mfma_f32_16x16x32_bf16 v[50:53], v[208:211], v[216:219], v[50:53]
	v_mfma_f32_16x16x32_bf16 v[34:37], v[208:211], v[224:227], v[34:37]
	v_mfma_f32_16x16x32_bf16 v[38:41], v[200:203], v[224:227], v[38:41]
	s_barrier
	s_setprio 2
	v_mfma_f32_16x16x32_bf16 v[22:25], v[200:203], v[232:235], v[22:25]
	v_mfma_f32_16x16x32_bf16 v[18:21], v[208:211], v[232:235], v[18:21]
	v_mfma_f32_16x16x32_bf16 v[2:5], v[208:211], v[240:243], v[2:5]
	v_mfma_f32_16x16x32_bf16 v[6:9], v[200:203], v[240:243], v[6:9]
	s_setprio 0
	s_add_i32 s14, 0, 0x18000
	v_add_u32_e32 v133, s14, v148
	s_add_i32 s15, 0, 0x1c000
	ds_read_b128 v[144:147], v133
	ds_read_b128 v[184:187], v133 offset:1024
	ds_read_b128 v[188:191], v133 offset:2048
	ds_read_b128 v[192:195], v133 offset:3072
	v_add_u32_e32 v133, s15, v148
	ds_read_b128 v[196:199], v133
	ds_read_b128 v[200:203], v133 offset:1024
	ds_read_b128 v[204:207], v133 offset:2048
	ds_read_b128 v[208:211], v133 offset:3072
	s_mov_b32 m0, s57
	v_lshl_add_u64 v[246:247], v[244:245], 0, s[24:25]
	ds_read_b128 v[212:215], v168 offset:32768
	ds_read_b128 v[216:219], v168 offset:33792
	ds_read_b128 v[220:223], v168 offset:34816
	ds_read_b128 v[224:227], v168 offset:35840
	ds_read_b128 v[228:231], v168 offset:36864
	ds_read_b128 v[232:235], v168 offset:37888
	ds_read_b128 v[236:239], v168 offset:38912
	ds_read_b128 v[240:243], v168 offset:39936
	global_load_lds_dwordx4 v[246:247], off
	v_lshl_add_u64 v[246:247], v[244:245], 0, s[26:27]
	s_mov_b32 m0, s58
	s_nop 0
	global_load_lds_dwordx4 v[246:247], off
	s_waitcnt vmcnt(8)
	s_waitcnt lgkmcnt(0)
	s_barrier
	s_setprio 1
	s_waitcnt lgkmcnt(0)
	v_mfma_f32_16x16x32_bf16 v[126:129], v[144:147], v[212:215], v[126:129]
	v_mfma_f32_16x16x32_bf16 v[122:125], v[188:191], v[212:215], v[122:125]
	v_mfma_f32_16x16x32_bf16 v[106:109], v[188:191], v[220:223], v[106:109]
	v_mfma_f32_16x16x32_bf16 v[110:113], v[144:147], v[220:223], v[110:113]
	v_mfma_f32_16x16x32_bf16 v[94:97], v[144:147], v[228:231], v[94:97]
	v_mfma_f32_16x16x32_bf16 v[90:93], v[188:191], v[228:231], v[90:93]
	v_mfma_f32_16x16x32_bf16 v[74:77], v[188:191], v[236:239], v[74:77]
	v_mfma_f32_16x16x32_bf16 v[78:81], v[144:147], v[236:239], v[78:81]
	v_mfma_f32_16x16x32_bf16 v[126:129], v[184:187], v[216:219], v[126:129]
	v_mfma_f32_16x16x32_bf16 v[122:125], v[192:195], v[216:219], v[122:125]
	v_mfma_f32_16x16x32_bf16 v[106:109], v[192:195], v[224:227], v[106:109]
	v_mfma_f32_16x16x32_bf16 v[110:113], v[184:187], v[224:227], v[110:113]
	v_mfma_f32_16x16x32_bf16 v[94:97], v[184:187], v[232:235], v[94:97]
	v_mfma_f32_16x16x32_bf16 v[90:93], v[192:195], v[232:235], v[90:93]
	v_mfma_f32_16x16x32_bf16 v[74:77], v[192:195], v[240:243], v[74:77]
	v_mfma_f32_16x16x32_bf16 v[78:81], v[184:187], v[240:243], v[78:81]
	v_mfma_f32_16x16x32_bf16 v[118:121], v[196:199], v[212:215], v[118:121]
	v_mfma_f32_16x16x32_bf16 v[114:117], v[204:207], v[212:215], v[114:117]
	v_mfma_f32_16x16x32_bf16 v[98:101], v[204:207], v[220:223], v[98:101]
	v_mfma_f32_16x16x32_bf16 v[102:105], v[196:199], v[220:223], v[102:105]
	v_mfma_f32_16x16x32_bf16 v[86:89], v[196:199], v[228:231], v[86:89]
	v_mfma_f32_16x16x32_bf16 v[82:85], v[204:207], v[228:231], v[82:85]
	v_mfma_f32_16x16x32_bf16 v[66:69], v[204:207], v[236:239], v[66:69]
	v_mfma_f32_16x16x32_bf16 v[70:73], v[196:199], v[236:239], v[70:73]
	v_mfma_f32_16x16x32_bf16 v[118:121], v[200:203], v[216:219], v[118:121]
	v_mfma_f32_16x16x32_bf16 v[114:117], v[208:211], v[216:219], v[114:117]
	v_mfma_f32_16x16x32_bf16 v[98:101], v[208:211], v[224:227], v[98:101]
	v_mfma_f32_16x16x32_bf16 v[102:105], v[200:203], v[224:227], v[102:105]
	s_barrier
; #define PG8_STAGE(bufoff, gbase, voff) do { if constexpr (!pg8_noload<Epi>::value) { _Pragma("unroll") for (int _i = 0; _i < 2; ++_i) \
;         __builtin_amdgcn_global_load_lds((const unsigned*)((const char*)(gbase) + (size_t)_i * pstep + (voff)[0]), (PG8_LAS unsigned*)(lds + (bufoff) + ldsw + _i * 8192), 16, 0, 0); } } while (0)
; #define PG8_LDA(dst, b, h) do { _Pragma("unroll") for (int m = 0; m < 4; ++m) _Pragma("unroll") for (int k = 0; k < 2; ++k) dst[m][k] = *(const PG8_LAS bf16x8*)(lds + PG8_SA(b, h) + aoff + m * 2048 + k * 1024); } while (0)
; #define PG8_MMA(ai, bj, At, Bt) do { __builtin_amdgcn_s_setprio(1); _Pragma("unroll") for (int m = 0; m < 4; ++m) _Pragma("unroll") for (int n = 0; n < 2; ++n) _Pragma("unroll") for (int k = 0; k < 2; ++k) \
;         acc[ai][bj][m][n] = __builtin_amdgcn_mfma_f32_16x16x32_bf16(Bt[n][k], At[m][k], acc[ai][bj][m][n], 0, 0, 0); __builtin_amdgcn_s_setprio(0); } while (0)
; #define PG8_WAIT_V(n) asm volatile("s_waitcnt vmcnt(" #n ")" ::: "memory")
; #define PG8_WAIT_L(n) asm volatile("s_waitcnt lgkmcnt(" #n ")" ::: "memory")
; #define PG8_BAR __builtin_amdgcn_s_barrier()
; #define PG8_SCHED __builtin_amdgcn_sched_barrier(0)
; template <class Epi, class Sched, bool ALIGN_EPI = false, bool SP2 = false, bool ABLK = false>
; __device__ __forceinline__ void gemm_phase(PG8_LAS unsigned char* lds, const Gemm g, const Sched& S, const Epi& E) {
;     ...
;         for (int t = 0; t < nt; t += 2) {
;     ...
;             PG8_WAIT_V(8); PG8_WAIT_L(0); PG8_BAR; PG8_MMA(0, 0, At, B0); PG8_MMA(0, 1, At, B1); PG8_BAR; PG8_SCHED;
;             PG8_LDA(At, 1, 1); PG8_STAGE(PG8_SB(1, 0), b3, voffB); PG8_STAGE(PG8_SB(1, 1), b3 + hstep, voffB); PG8_STAGE(PG8_SA(1, 0), a3, voffA);
;             PG8_WAIT_V(8); PG8_WAIT_L(0); PG8_BAR; PG8_MMA(1, 0, At, B0); PG8_MMA(1, 1, At, B1); PG8_BAR; PG8_SCHED;
	s_setprio 2
	v_mfma_f32_16x16x32_bf16 v[86:89], v[200:203], v[232:235], v[86:89]
	v_mfma_f32_16x16x32_bf16 v[82:85], v[208:211], v[232:235], v[82:85]
	v_mfma_f32_16x16x32_bf16 v[66:69], v[208:211], v[240:243], v[66:69]
	v_mfma_f32_16x16x32_bf16 v[70:73], v[200:203], v[240:243], v[70:73]
	s_setprio 0
	s_add_i32 s14, s14, s3
	v_lshl_add_u64 v[246:247], v[180:181], 0, s[38:39]
	s_mov_b32 m0, s14
	ds_read_b128 v[212:215], v168 offset:49152
	ds_read_b128 v[216:219], v168 offset:50176
	ds_read_b128 v[220:223], v168 offset:51200
	ds_read_b128 v[224:227], v168 offset:52224
	ds_read_b128 v[228:231], v168 offset:53248
	ds_read_b128 v[232:235], v168 offset:54272
	ds_read_b128 v[236:239], v168 offset:55296
	ds_read_b128 v[240:243], v168 offset:56320
	global_load_lds_dwordx4 v[246:247], off
	v_lshl_add_u64 v[246:247], v[180:181], 0, s[40:41]
	s_add_i32 m0, s14, 0x2000
	s_add_i32 s14, s15, s3
	global_load_lds_dwordx4 v[246:247], off
	v_lshl_add_u64 v[246:247], v[180:181], 0, s[42:43]
	s_mov_b32 m0, s14
	v_lshl_add_u64 v[180:181], v[180:181], 0, s[44:45]
	global_load_lds_dwordx4 v[246:247], off
	s_add_i32 m0, s14, 0x2000
	s_nop 0
	global_load_lds_dwordx4 v[180:181], off
	v_lshl_add_u64 v[180:181], v[244:245], 0, s[38:39]
	s_mov_b32 m0, s61
	s_nop 0
	global_load_lds_dwordx4 v[180:181], off
	v_lshl_add_u64 v[180:181], v[244:245], 0, s[40:41]
	s_mov_b32 m0, s63
	s_nop 0
	global_load_lds_dwordx4 v[180:181], off
	s_waitcnt vmcnt(8)
	s_waitcnt lgkmcnt(0)
	s_barrier
	s_setprio 1
	s_waitcnt lgkmcnt(0)
	v_mfma_f32_16x16x32_bf16 v[62:65], v[144:147], v[212:215], v[62:65]
	v_mfma_f32_16x16x32_bf16 v[58:61], v[188:191], v[212:215], v[58:61]
	v_mfma_f32_16x16x32_bf16 v[42:45], v[188:191], v[220:223], v[42:45]
	v_mfma_f32_16x16x32_bf16 v[46:49], v[144:147], v[220:223], v[46:49]
	v_mfma_f32_16x16x32_bf16 v[30:33], v[144:147], v[228:231], v[30:33]
	v_mfma_f32_16x16x32_bf16 v[26:29], v[188:191], v[228:231], v[26:29]
	v_mfma_f32_16x16x32_bf16 v[10:13], v[188:191], v[236:239], v[10:13]
	v_mfma_f32_16x16x32_bf16 v[14:17], v[144:147], v[236:239], v[14:17]
	v_mfma_f32_16x16x32_bf16 v[62:65], v[184:187], v[216:219], v[62:65]
	v_mfma_f32_16x16x32_bf16 v[58:61], v[192:195], v[216:219], v[58:61]
	v_mfma_f32_16x16x32_bf16 v[42:45], v[192:195], v[224:227], v[42:45]
	v_mfma_f32_16x16x32_bf16 v[46:49], v[184:187], v[224:227], v[46:49]
	v_mfma_f32_16x16x32_bf16 v[30:33], v[184:187], v[232:235], v[30:33]
	v_mfma_f32_16x16x32_bf16 v[26:29], v[192:195], v[232:235], v[26:29]
	v_mfma_f32_16x16x32_bf16 v[10:13], v[192:195], v[240:243], v[10:13]
	v_mfma_f32_16x16x32_bf16 v[14:17], v[184:187], v[240:243], v[14:17]
	v_mfma_f32_16x16x32_bf16 v[54:57], v[196:199], v[212:215], v[54:57]
	v_mfma_f32_16x16x32_bf16 v[50:53], v[204:207], v[212:215], v[50:53]
	v_mfma_f32_16x16x32_bf16 v[34:37], v[204:207], v[220:223], v[34:37]
	v_mfma_f32_16x16x32_bf16 v[38:41], v[196:199], v[220:223], v[38:41]
	v_mfma_f32_16x16x32_bf16 v[22:25], v[196:199], v[228:231], v[22:25]
	v_mfma_f32_16x16x32_bf16 v[18:21], v[204:207], v[228:231], v[18:21]
	v_mfma_f32_16x16x32_bf16 v[2:5], v[204:207], v[236:239], v[2:5]
	v_mfma_f32_16x16x32_bf16 v[6:9], v[196:199], v[236:239], v[6:9]
	v_mfma_f32_16x16x32_bf16 v[54:57], v[200:203], v[216:219], v[54:57]
	v_mfma_f32_16x16x32_bf16 v[50:53], v[208:211], v[216:219], v[50:53]
	v_mfma_f32_16x16x32_bf16 v[34:37], v[208:211], v[224:227], v[34:37]
	v_mfma_f32_16x16x32_bf16 v[38:41], v[200:203], v[224:227], v[38:41]
	s_barrier
	s_setprio 2
	v_mfma_f32_16x16x32_bf16 v[22:25], v[200:203], v[232:235], v[22:25]
	v_mfma_f32_16x16x32_bf16 v[18:21], v[208:211], v[232:235], v[18:21]
	v_mfma_f32_16x16x32_bf16 v[2:5], v[208:211], v[240:243], v[2:5]
	v_mfma_f32_16x16x32_bf16 v[6:9], v[200:203], v[240:243], v[6:9]
	s_setprio 0
	s_cmp_gt_u32 s59, 29
	s_mov_b32 s59, s30
	s_cbranch_scc1 .LBB0_2131

; #define PG8_STAGE(bufoff, gbase, voff) do { if constexpr (!pg8_noload<Epi>::value) { _Pragma("unroll") for (int _i = 0; _i < 2; ++_i) \
;         __builtin_amdgcn_global_load_lds((const unsigned*)((const char*)(gbase) + (size_t)_i * pstep + (voff)[0]), (PG8_LAS unsigned*)(lds + (bufoff) + ldsw + _i * 8192), 16, 0, 0); } } while (0)
; #define PG8_LDA(dst, b, h) do { _Pragma("unroll") for (int m = 0; m < 4; ++m) _Pragma("unroll") for (int k = 0; k < 2; ++k) dst[m][k] = *(const PG8_LAS bf16x8*)(lds + PG8_SA(b, h) + aoff + m * 2048 + k * 1024); } while (0)
; #define PG8_LDB(dst, b, h) do { _Pragma("unroll") for (int n = 0; n < 2; ++n) _Pragma("unroll") for (int k = 0; k < 2; ++k) dst[n][k] = *(const PG8_LAS bf16x8*)(lds + PG8_SB(b, h) + boff + n * 2048 + k * 1024); } while (0)
; #define PG8_MMA(ai, bj, At, Bt) do { __builtin_amdgcn_s_setprio(1); _Pragma("unroll") for (int m = 0; m < 4; ++m) _Pragma("unroll") for (int n = 0; n < 2; ++n) _Pragma("unroll") for (int k = 0; k < 2; ++k) \
;         acc[ai][bj][m][n] = __builtin_amdgcn_mfma_f32_16x16x32_bf16(Bt[n][k], At[m][k], acc[ai][bj][m][n], 0, 0, 0); __builtin_amdgcn_s_setprio(0); } while (0)
; #define PG8_WAIT_V(n) asm volatile("s_waitcnt vmcnt(" #n ")" ::: "memory")
; #define PG8_WAIT_L(n) asm volatile("s_waitcnt lgkmcnt(" #n ")" ::: "memory")
; #define PG8_BAR __builtin_amdgcn_s_barrier()
; template <class Epi, class Sched, bool ALIGN_EPI = false, bool SP2 = false, bool ABLK = false>
; __device__ __forceinline__ void gemm_phase(PG8_LAS unsigned char* lds, const Gemm g, const Sched& S, const Epi& E) {
;     ...
;             const bool last = (t == nt - 2);
;             const char* a1 = cA + (size_t)(t + 1) * kstep;
;             const char* a2 = last ? nA : cA + (size_t)(t + 2) * kstep; const char* b2 = last ? nB : cB + (size_t)(t + 2) * kstepB;
;             const char* a3 = a2 + kstep; const char* b3 = b2 + kstepB;
;             if (last && has_next) S.a_ready(nxt);
;             if constexpr (SP2) {
;             PG8_LDB(B0, 0, 0); PG8_LDB(B1, 0, 1); PG8_SCHED; PG8_LDA(At, 0, 0); PG8_STAGE(PG8_SA(1, 1), a1 + hstep, voffA);
;             PG8_WAIT_V(8); PG8_WAIT_L(0); PG8_BAR; PG8_MMA(0, 0, At, B0); PG8_MMA(0, 1, At, B1); PG8_BAR; PG8_SCHED;
;             PG8_LDA(At, 0, 1); PG8_STAGE(PG8_SB(0, 0), b2, voffB); PG8_STAGE(PG8_SB(0, 1), b2 + hstep, voffB); PG8_STAGE(PG8_SA(0, 0), a2, voffA);
.LBB0_2399:
	ds_read_b128 v[130:133], v175
	ds_read_b128 v[134:137], v175 offset:1024
	ds_read_b128 v[138:141], v175 offset:2048
	ds_read_b128 v[142:145], v175 offset:3072
	ds_read_b128 v[146:149], v176
	ds_read_b128 v[150:153], v176 offset:1024
	ds_read_b128 v[154:157], v176 offset:2048
	ds_read_b128 v[158:161], v176 offset:3072
	s_add_i32 s55, s53, 2
	s_add_u32 s64, s62, 0xfff00800
	s_addc_u32 s65, s63, -1
	s_cmp_eq_u32 s3, s53
	s_cselect_b32 s65, s57, s65
	s_cselect_b32 s64, s56, s64
	s_cselect_b32 s91, s59, s49
	s_cselect_b32 s90, s58, s11
	v_lshl_add_u64 v[170:171], s[62:63], 0, v[166:167]
	s_add_i32 m0, s61, 0xc000
	ds_read_b128 v[184:187], v177
	ds_read_b128 v[188:191], v177 offset:1024
	ds_read_b128 v[192:195], v177 offset:2048
	ds_read_b128 v[196:199], v177 offset:3072
	ds_read_b128 v[200:203], v177 offset:4096
	ds_read_b128 v[204:207], v177 offset:5120
	ds_read_b128 v[208:211], v177 offset:6144
	ds_read_b128 v[212:215], v177 offset:7168
	global_load_lds_dwordx4 v[170:171], off
	v_lshl_add_u64 v[170:171], v[170:171], 0, s[12:13]
	s_add_i32 m0, s61, 0xe000
	s_nop 0
	global_load_lds_dwordx4 v[170:171], off
	s_waitcnt vmcnt(8)
	s_waitcnt lgkmcnt(0)
	s_barrier
	s_setprio 1
	s_waitcnt lgkmcnt(0)
	v_mfma_f32_16x16x32_bf16 v[126:129], v[130:133], v[184:187], v[126:129]
	v_mfma_f32_16x16x32_bf16 v[122:125], v[138:141], v[184:187], v[122:125]
	v_mfma_f32_16x16x32_bf16 v[106:109], v[138:141], v[192:195], v[106:109]
	v_mfma_f32_16x16x32_bf16 v[110:113], v[130:133], v[192:195], v[110:113]
	v_mfma_f32_16x16x32_bf16 v[94:97], v[130:133], v[200:203], v[94:97]
	v_mfma_f32_16x16x32_bf16 v[90:93], v[138:141], v[200:203], v[90:93]
	v_mfma_f32_16x16x32_bf16 v[74:77], v[138:141], v[208:211], v[74:77]
	v_mfma_f32_16x16x32_bf16 v[78:81], v[130:133], v[208:211], v[78:81]
	v_mfma_f32_16x16x32_bf16 v[126:129], v[134:137], v[188:191], v[126:129]
	v_mfma_f32_16x16x32_bf16 v[122:125], v[142:145], v[188:191], v[122:125]
	v_mfma_f32_16x16x32_bf16 v[106:109], v[142:145], v[196:199], v[106:109]
	v_mfma_f32_16x16x32_bf16 v[110:113], v[134:137], v[196:199], v[110:113]
	v_mfma_f32_16x16x32_bf16 v[94:97], v[134:137], v[204:207], v[94:97]
	v_mfma_f32_16x16x32_bf16 v[90:93], v[142:145], v[204:207], v[90:93]
	v_mfma_f32_16x16x32_bf16 v[74:77], v[142:145], v[212:215], v[74:77]
	v_mfma_f32_16x16x32_bf16 v[78:81], v[134:137], v[212:215], v[78:81]
	v_mfma_f32_16x16x32_bf16 v[118:121], v[146:149], v[184:187], v[118:121]
	v_mfma_f32_16x16x32_bf16 v[114:117], v[154:157], v[184:187], v[114:117]
	v_mfma_f32_16x16x32_bf16 v[98:101], v[154:157], v[192:195], v[98:101]
	v_mfma_f32_16x16x32_bf16 v[102:105], v[146:149], v[192:195], v[102:105]
	v_mfma_f32_16x16x32_bf16 v[86:89], v[146:149], v[200:203], v[86:89]
	v_mfma_f32_16x16x32_bf16 v[82:85], v[154:157], v[200:203], v[82:85]
	v_mfma_f32_16x16x32_bf16 v[66:69], v[154:157], v[208:211], v[66:69]
	v_mfma_f32_16x16x32_bf16 v[70:73], v[146:149], v[208:211], v[70:73]
	v_mfma_f32_16x16x32_bf16 v[118:121], v[150:153], v[188:191], v[118:121]
	v_mfma_f32_16x16x32_bf16 v[114:117], v[158:161], v[188:191], v[114:117]
	v_mfma_f32_16x16x32_bf16 v[98:101], v[158:161], v[196:199], v[98:101]
	v_mfma_f32_16x16x32_bf16 v[102:105], v[150:153], v[196:199], v[102:105]
	s_barrier
	s_setprio 2
	v_mfma_f32_16x16x32_bf16 v[86:89], v[150:153], v[204:207], v[86:89]
	v_mfma_f32_16x16x32_bf16 v[82:85], v[158:161], v[204:207], v[82:85]
	v_mfma_f32_16x16x32_bf16 v[66:69], v[158:161], v[212:215], v[66:69]
	v_mfma_f32_16x16x32_bf16 v[70:73], v[150:153], v[212:215], v[70:73]
	s_setprio 0
	s_add_i32 s53, s80, s69
	v_lshl_add_u64 v[170:171], s[90:91], 0, v[162:163]
	s_mov_b32 m0, s53
	ds_read_b128 v[184:187], v177 offset:16384
	ds_read_b128 v[188:191], v177 offset:17408
	ds_read_b128 v[192:195], v177 offset:18432
	ds_read_b128 v[196:199], v177 offset:19456
	ds_read_b128 v[200:203], v177 offset:20480
	ds_read_b128 v[204:207], v177 offset:21504
	ds_read_b128 v[208:211], v177 offset:22528
	ds_read_b128 v[212:215], v177 offset:23552
	global_load_lds_dwordx4 v[170:171], off
	v_lshl_add_u64 v[216:217], v[170:171], 0, s[12:13]
	s_add_i32 m0, s53, 0x2000
	s_add_i32 s53, s81, s69
	global_load_lds_dwordx4 v[216:217], off
	v_lshl_add_u64 v[216:217], v[170:171], 0, s[14:15]
	s_mov_b32 m0, s53
	s_nop 0
	global_load_lds_dwordx4 v[216:217], off
	v_lshl_add_u64 v[216:217], v[170:171], 0, s[16:17]
	s_add_i32 m0, s53, 0x2000
	s_nop 0
	global_load_lds_dwordx4 v[216:217], off
	v_lshl_add_u64 v[216:217], s[64:65], 0, v[162:163]
	s_mov_b32 m0, s61
	v_lshl_add_u64 v[218:219], v[216:217], 0, s[12:13]
	global_load_lds_dwordx4 v[216:217], off
	s_mov_b32 m0, s70
	s_nop 0
	global_load_lds_dwordx4 v[218:219], off
	s_waitcnt vmcnt(8)
	s_waitcnt lgkmcnt(0)
	s_barrier
; #define PG8_STAGE(bufoff, gbase, voff) do { if constexpr (!pg8_noload<Epi>::value) { _Pragma("unroll") for (int _i = 0; _i < 2; ++_i) \
;         __builtin_amdgcn_global_load_lds((const unsigned*)((const char*)(gbase) + (size_t)_i * pstep + (voff)[0]), (PG8_LAS unsigned*)(lds + (bufoff) + ldsw + _i * 8192), 16, 0, 0); } } while (0)
; #define PG8_LDA(dst, b, h) do { _Pragma("unroll") for (int m = 0; m < 4; ++m) _Pragma("unroll") for (int k = 0; k < 2; ++k) dst[m][k] = *(const PG8_LAS bf16x8*)(lds + PG8_SA(b, h) + aoff + m * 2048 + k * 1024); } while (0)
; #define PG8_LDB(dst, b, h) do { _Pragma("unroll") for (int n = 0; n < 2; ++n) _Pragma("unroll") for (int k = 0; k < 2; ++k) dst[n][k] = *(const PG8_LAS bf16x8*)(lds + PG8_SB(b, h) + boff + n * 2048 + k * 1024); } while (0)
; #define PG8_MMA(ai, bj, At, Bt) do { __builtin_amdgcn_s_setprio(1); _Pragma("unroll") for (int m = 0; m < 4; ++m) _Pragma("unroll") for (int n = 0; n < 2; ++n) _Pragma("unroll") for (int k = 0; k < 2; ++k) \
;         acc[ai][bj][m][n] = __builtin_amdgcn_mfma_f32_16x16x32_bf16(Bt[n][k], At[m][k], acc[ai][bj][m][n], 0, 0, 0); __builtin_amdgcn_s_setprio(0); } while (0)
; #define PG8_WAIT_V(n) asm volatile("s_waitcnt vmcnt(" #n ")" ::: "memory")
; #define PG8_WAIT_L(n) asm volatile("s_waitcnt lgkmcnt(" #n ")" ::: "memory")
; #define PG8_BAR __builtin_amdgcn_s_barrier()
; #define PG8_SCHED __builtin_amdgcn_sched_barrier(0)
; template <class Epi, class Sched, bool ALIGN_EPI = false, bool SP2 = false, bool ABLK = false>
; __device__ __forceinline__ void gemm_phase(PG8_LAS unsigned char* lds, const Gemm g, const Sched& S, const Epi& E) {
;     ...
;             PG8_WAIT_V(8); PG8_WAIT_L(0); PG8_BAR; PG8_MMA(1, 0, At, B0); PG8_MMA(1, 1, At, B1); PG8_BAR; PG8_SCHED;
;             PG8_LDB(B0, 1, 0); PG8_LDB(B1, 1, 1); PG8_SCHED; PG8_LDA(At, 1, 0); PG8_STAGE(PG8_SA(0, 1), a2 + hstep, voffA);
;             PG8_WAIT_V(8); PG8_WAIT_L(0); PG8_BAR; PG8_MMA(0, 0, At, B0); PG8_MMA(0, 1, At, B1); PG8_BAR; PG8_SCHED;
	s_setprio 1
	s_waitcnt lgkmcnt(0)
	v_mfma_f32_16x16x32_bf16 v[62:65], v[130:133], v[184:187], v[62:65]
	v_mfma_f32_16x16x32_bf16 v[58:61], v[138:141], v[184:187], v[58:61]
	v_mfma_f32_16x16x32_bf16 v[42:45], v[138:141], v[192:195], v[42:45]
	v_mfma_f32_16x16x32_bf16 v[46:49], v[130:133], v[192:195], v[46:49]
	v_mfma_f32_16x16x32_bf16 v[30:33], v[130:133], v[200:203], v[30:33]
	v_mfma_f32_16x16x32_bf16 v[26:29], v[138:141], v[200:203], v[26:29]
	v_mfma_f32_16x16x32_bf16 v[10:13], v[138:141], v[208:211], v[10:13]
	v_mfma_f32_16x16x32_bf16 v[14:17], v[130:133], v[208:211], v[14:17]
	v_mfma_f32_16x16x32_bf16 v[62:65], v[134:137], v[188:191], v[62:65]
	v_mfma_f32_16x16x32_bf16 v[58:61], v[142:145], v[188:191], v[58:61]
	v_mfma_f32_16x16x32_bf16 v[42:45], v[142:145], v[196:199], v[42:45]
	v_mfma_f32_16x16x32_bf16 v[46:49], v[134:137], v[196:199], v[46:49]
	v_mfma_f32_16x16x32_bf16 v[30:33], v[134:137], v[204:207], v[30:33]
	v_mfma_f32_16x16x32_bf16 v[26:29], v[142:145], v[204:207], v[26:29]
	v_mfma_f32_16x16x32_bf16 v[10:13], v[142:145], v[212:215], v[10:13]
	v_mfma_f32_16x16x32_bf16 v[14:17], v[134:137], v[212:215], v[14:17]
	v_mfma_f32_16x16x32_bf16 v[54:57], v[146:149], v[184:187], v[54:57]
	v_mfma_f32_16x16x32_bf16 v[50:53], v[154:157], v[184:187], v[50:53]
	v_mfma_f32_16x16x32_bf16 v[34:37], v[154:157], v[192:195], v[34:37]
	v_mfma_f32_16x16x32_bf16 v[38:41], v[146:149], v[192:195], v[38:41]
	v_mfma_f32_16x16x32_bf16 v[22:25], v[146:149], v[200:203], v[22:25]
	v_mfma_f32_16x16x32_bf16 v[18:21], v[154:157], v[200:203], v[18:21]
	v_mfma_f32_16x16x32_bf16 v[2:5], v[154:157], v[208:211], v[2:5]
	v_mfma_f32_16x16x32_bf16 v[6:9], v[146:149], v[208:211], v[6:9]
	v_mfma_f32_16x16x32_bf16 v[54:57], v[150:153], v[188:191], v[54:57]
	v_mfma_f32_16x16x32_bf16 v[50:53], v[158:161], v[188:191], v[50:53]
	v_mfma_f32_16x16x32_bf16 v[34:37], v[158:161], v[196:199], v[34:37]
	v_mfma_f32_16x16x32_bf16 v[38:41], v[150:153], v[196:199], v[38:41]
	s_barrier
	s_setprio 2
	v_mfma_f32_16x16x32_bf16 v[22:25], v[150:153], v[204:207], v[22:25]
	v_mfma_f32_16x16x32_bf16 v[18:21], v[158:161], v[204:207], v[18:21]
	v_mfma_f32_16x16x32_bf16 v[2:5], v[158:161], v[212:215], v[2:5]
	v_mfma_f32_16x16x32_bf16 v[6:9], v[150:153], v[212:215], v[6:9]
	s_setprio 0
	s_add_i32 s53, 0, 0x18000
	s_add_i32 s64, 0, 0x1c000
	v_add_u32_e32 v142, s53, v1
	v_add_u32_e32 v158, s64, v1
	ds_read_b128 v[130:133], v142
	ds_read_b128 v[134:137], v142 offset:1024
	ds_read_b128 v[138:141], v142 offset:2048
	ds_read_b128 v[142:145], v142 offset:3072
	ds_read_b128 v[146:149], v158
	ds_read_b128 v[150:153], v158 offset:1024
	ds_read_b128 v[154:157], v158 offset:2048
	ds_read_b128 v[158:161], v158 offset:3072
	s_mov_b32 m0, s71
	v_lshl_add_u64 v[218:219], v[216:217], 0, s[14:15]
	ds_read_b128 v[184:187], v177 offset:32768
	ds_read_b128 v[188:191], v177 offset:33792
	ds_read_b128 v[192:195], v177 offset:34816
	ds_read_b128 v[196:199], v177 offset:35840
	ds_read_b128 v[200:203], v177 offset:36864
	ds_read_b128 v[204:207], v177 offset:37888
	ds_read_b128 v[208:211], v177 offset:38912
	ds_read_b128 v[212:215], v177 offset:39936
	global_load_lds_dwordx4 v[218:219], off
	v_lshl_add_u64 v[218:219], v[216:217], 0, s[16:17]
	s_mov_b32 m0, s72
	s_nop 0
	global_load_lds_dwordx4 v[218:219], off
	s_waitcnt vmcnt(8)
	s_waitcnt lgkmcnt(0)
	s_barrier
	s_setprio 1
	s_waitcnt lgkmcnt(0)
	v_mfma_f32_16x16x32_bf16 v[126:129], v[130:133], v[184:187], v[126:129]
	v_mfma_f32_16x16x32_bf16 v[122:125], v[138:141], v[184:187], v[122:125]
	v_mfma_f32_16x16x32_bf16 v[106:109], v[138:141], v[192:195], v[106:109]
	v_mfma_f32_16x16x32_bf16 v[110:113], v[130:133], v[192:195], v[110:113]
	v_mfma_f32_16x16x32_bf16 v[94:97], v[130:133], v[200:203], v[94:97]
	v_mfma_f32_16x16x32_bf16 v[90:93], v[138:141], v[200:203], v[90:93]
	v_mfma_f32_16x16x32_bf16 v[74:77], v[138:141], v[208:211], v[74:77]
	v_mfma_f32_16x16x32_bf16 v[78:81], v[130:133], v[208:211], v[78:81]
	v_mfma_f32_16x16x32_bf16 v[126:129], v[134:137], v[188:191], v[126:129]
	v_mfma_f32_16x16x32_bf16 v[122:125], v[142:145], v[188:191], v[122:125]
	v_mfma_f32_16x16x32_bf16 v[106:109], v[142:145], v[196:199], v[106:109]
	v_mfma_f32_16x16x32_bf16 v[110:113], v[134:137], v[196:199], v[110:113]
	v_mfma_f32_16x16x32_bf16 v[94:97], v[134:137], v[204:207], v[94:97]
	v_mfma_f32_16x16x32_bf16 v[90:93], v[142:145], v[204:207], v[90:93]
	v_mfma_f32_16x16x32_bf16 v[74:77], v[142:145], v[212:215], v[74:77]
	v_mfma_f32_16x16x32_bf16 v[78:81], v[134:137], v[212:215], v[78:81]
	v_mfma_f32_16x16x32_bf16 v[118:121], v[146:149], v[184:187], v[118:121]
	v_mfma_f32_16x16x32_bf16 v[114:117], v[154:157], v[184:187], v[114:117]
	v_mfma_f32_16x16x32_bf16 v[98:101], v[154:157], v[192:195], v[98:101]
	v_mfma_f32_16x16x32_bf16 v[102:105], v[146:149], v[192:195], v[102:105]
	v_mfma_f32_16x16x32_bf16 v[86:89], v[146:149], v[200:203], v[86:89]
	v_mfma_f32_16x16x32_bf16 v[82:85], v[154:157], v[200:203], v[82:85]
	v_mfma_f32_16x16x32_bf16 v[66:69], v[154:157], v[208:211], v[66:69]
	v_mfma_f32_16x16x32_bf16 v[70:73], v[146:149], v[208:211], v[70:73]
	v_mfma_f32_16x16x32_bf16 v[118:121], v[150:153], v[188:191], v[118:121]
	v_mfma_f32_16x16x32_bf16 v[114:117], v[158:161], v[188:191], v[114:117]
	v_mfma_f32_16x16x32_bf16 v[98:101], v[158:161], v[196:199], v[98:101]
	v_mfma_f32_16x16x32_bf16 v[102:105], v[150:153], v[196:199], v[102:105]
	s_barrier
; #define PG8_STAGE(bufoff, gbase, voff) do { if constexpr (!pg8_noload<Epi>::value) { _Pragma("unroll") for (int _i = 0; _i < 2; ++_i) \
;         __builtin_amdgcn_global_load_lds((const unsigned*)((const char*)(gbase) + (size_t)_i * pstep + (voff)[0]), (PG8_LAS unsigned*)(lds + (bufoff) + ldsw + _i * 8192), 16, 0, 0); } } while (0)
; #define PG8_LDA(dst, b, h) do { _Pragma("unroll") for (int m = 0; m < 4; ++m) _Pragma("unroll") for (int k = 0; k < 2; ++k) dst[m][k] = *(const PG8_LAS bf16x8*)(lds + PG8_SA(b, h) + aoff + m * 2048 + k * 1024); } while (0)
; #define PG8_MMA(ai, bj, At, Bt) do { __builtin_amdgcn_s_setprio(1); _Pragma("unroll") for (int m = 0; m < 4; ++m) _Pragma("unroll") for (int n = 0; n < 2; ++n) _Pragma("unroll") for (int k = 0; k < 2; ++k) \
;         acc[ai][bj][m][n] = __builtin_amdgcn_mfma_f32_16x16x32_bf16(Bt[n][k], At[m][k], acc[ai][bj][m][n], 0, 0, 0); __builtin_amdgcn_s_setprio(0); } while (0)
; #define PG8_WAIT_V(n) asm volatile("s_waitcnt vmcnt(" #n ")" ::: "memory")
; #define PG8_WAIT_L(n) asm volatile("s_waitcnt lgkmcnt(" #n ")" ::: "memory")
; #define PG8_BAR __builtin_amdgcn_s_barrier()
; #define PG8_SCHED __builtin_amdgcn_sched_barrier(0)
; template <class Epi, class Sched, bool ALIGN_EPI = false, bool SP2 = false, bool ABLK = false>
; __device__ __forceinline__ void gemm_phase(PG8_LAS unsigned char* lds, const Gemm g, const Sched& S, const Epi& E) {
;     ...
;             PG8_WAIT_V(8); PG8_WAIT_L(0); PG8_BAR; PG8_MMA(0, 0, At, B0); PG8_MMA(0, 1, At, B1); PG8_BAR; PG8_SCHED;
;             PG8_LDA(At, 1, 1); PG8_STAGE(PG8_SB(1, 0), b3, voffB); PG8_STAGE(PG8_SB(1, 1), b3 + hstep, voffB); PG8_STAGE(PG8_SA(1, 0), a3, voffA);
;             PG8_WAIT_V(8); PG8_WAIT_L(0); PG8_BAR; PG8_MMA(1, 0, At, B0); PG8_MMA(1, 1, At, B1); PG8_BAR; PG8_SCHED;
	s_setprio 2
	v_mfma_f32_16x16x32_bf16 v[86:89], v[150:153], v[204:207], v[86:89]
	v_mfma_f32_16x16x32_bf16 v[82:85], v[158:161], v[204:207], v[82:85]
	v_mfma_f32_16x16x32_bf16 v[66:69], v[158:161], v[212:215], v[66:69]
	v_mfma_f32_16x16x32_bf16 v[70:73], v[150:153], v[212:215], v[70:73]
	s_setprio 0
	s_add_i32 s53, s53, s69
	v_lshl_add_u64 v[218:219], v[170:171], 0, s[24:25]
	s_mov_b32 m0, s53
	ds_read_b128 v[184:187], v177 offset:49152
	ds_read_b128 v[188:191], v177 offset:50176
	ds_read_b128 v[192:195], v177 offset:51200
	ds_read_b128 v[196:199], v177 offset:52224
	ds_read_b128 v[200:203], v177 offset:53248
	ds_read_b128 v[204:207], v177 offset:54272
	ds_read_b128 v[208:211], v177 offset:55296
	ds_read_b128 v[212:215], v177 offset:56320
	global_load_lds_dwordx4 v[218:219], off
	v_lshl_add_u64 v[218:219], v[170:171], 0, s[26:27]
	s_add_i32 m0, s53, 0x2000
	s_add_i32 s53, s64, s69
	global_load_lds_dwordx4 v[218:219], off
	v_lshl_add_u64 v[218:219], v[170:171], 0, s[28:29]
	s_mov_b32 m0, s53
	v_lshl_add_u64 v[170:171], v[170:171], 0, s[30:31]
	global_load_lds_dwordx4 v[218:219], off
	s_add_i32 m0, s53, 0x2000
	s_nop 0
	global_load_lds_dwordx4 v[170:171], off
	v_lshl_add_u64 v[170:171], v[216:217], 0, s[24:25]
	s_mov_b32 m0, s75
	s_nop 0
	global_load_lds_dwordx4 v[170:171], off
	v_lshl_add_u64 v[170:171], v[216:217], 0, s[26:27]
	s_mov_b32 m0, s76
	s_nop 0
	global_load_lds_dwordx4 v[170:171], off
	s_waitcnt vmcnt(8)
	s_waitcnt lgkmcnt(0)
	s_barrier
	s_setprio 1
	s_waitcnt lgkmcnt(0)
	v_mfma_f32_16x16x32_bf16 v[62:65], v[130:133], v[184:187], v[62:65]
	v_mfma_f32_16x16x32_bf16 v[58:61], v[138:141], v[184:187], v[58:61]
	v_mfma_f32_16x16x32_bf16 v[42:45], v[138:141], v[192:195], v[42:45]
	v_mfma_f32_16x16x32_bf16 v[46:49], v[130:133], v[192:195], v[46:49]
	v_mfma_f32_16x16x32_bf16 v[30:33], v[130:133], v[200:203], v[30:33]
	v_mfma_f32_16x16x32_bf16 v[26:29], v[138:141], v[200:203], v[26:29]
	v_mfma_f32_16x16x32_bf16 v[10:13], v[138:141], v[208:211], v[10:13]
	v_mfma_f32_16x16x32_bf16 v[14:17], v[130:133], v[208:211], v[14:17]
	v_mfma_f32_16x16x32_bf16 v[62:65], v[134:137], v[188:191], v[62:65]
	v_mfma_f32_16x16x32_bf16 v[58:61], v[142:145], v[188:191], v[58:61]
	v_mfma_f32_16x16x32_bf16 v[42:45], v[142:145], v[196:199], v[42:45]
	v_mfma_f32_16x16x32_bf16 v[46:49], v[134:137], v[196:199], v[46:49]
	v_mfma_f32_16x16x32_bf16 v[30:33], v[134:137], v[204:207], v[30:33]
	v_mfma_f32_16x16x32_bf16 v[26:29], v[142:145], v[204:207], v[26:29]
	v_mfma_f32_16x16x32_bf16 v[10:13], v[142:145], v[212:215], v[10:13]
	v_mfma_f32_16x16x32_bf16 v[14:17], v[134:137], v[212:215], v[14:17]
	v_mfma_f32_16x16x32_bf16 v[54:57], v[146:149], v[184:187], v[54:57]
	v_mfma_f32_16x16x32_bf16 v[50:53], v[154:157], v[184:187], v[50:53]
	v_mfma_f32_16x16x32_bf16 v[34:37], v[154:157], v[192:195], v[34:37]
	v_mfma_f32_16x16x32_bf16 v[38:41], v[146:149], v[192:195], v[38:41]
	v_mfma_f32_16x16x32_bf16 v[22:25], v[146:149], v[200:203], v[22:25]
	v_mfma_f32_16x16x32_bf16 v[18:21], v[154:157], v[200:203], v[18:21]
	v_mfma_f32_16x16x32_bf16 v[2:5], v[154:157], v[208:211], v[2:5]
	v_mfma_f32_16x16x32_bf16 v[6:9], v[146:149], v[208:211], v[6:9]
	v_mfma_f32_16x16x32_bf16 v[54:57], v[150:153], v[188:191], v[54:57]
	v_mfma_f32_16x16x32_bf16 v[50:53], v[158:161], v[188:191], v[50:53]
	v_mfma_f32_16x16x32_bf16 v[34:37], v[158:161], v[196:199], v[34:37]
	v_mfma_f32_16x16x32_bf16 v[38:41], v[150:153], v[196:199], v[38:41]
	s_barrier
	s_setprio 2
	v_mfma_f32_16x16x32_bf16 v[22:25], v[150:153], v[204:207], v[22:25]
	v_mfma_f32_16x16x32_bf16 v[18:21], v[158:161], v[204:207], v[18:21]
	v_mfma_f32_16x16x32_bf16 v[2:5], v[158:161], v[212:215], v[2:5]
	v_mfma_f32_16x16x32_bf16 v[6:9], v[150:153], v[212:215], v[6:9]
	s_setprio 0
	s_add_u32 s62, s62, 0x1000
	s_addc_u32 s63, s63, 0
	s_add_u32 s11, s11, 0x1000
	s_addc_u32 s49, s49, 0
	s_cmp_ge_i32 s55, s89
	s_mov_b32 s53, s55
	s_cbranch_scc0 .LBB0_2399
	s_and_b64 vcc, exec, s[34:35]
	s_cbranch_vccnz .LBB0_2404
	s_lshl_b32 s11, s2, 8
	s_cmp_gt_i32 s2, 63
	s_mov_b64 s[62:63], -1
	s_cbranch_scc1 .LBB0_2405
